# stack of small edits on v24: all 16 DMA in SGPR-base form, L1 scalar setup moved into M1, cvt loop waits relaxed, GLA-norm 12-load prefetch, scan packed-mul split
# speedup vs baseline: 1.0122x; 1.0050x over previous
; #define LAS __attribute__((address_space(3)))
; DI int fresh_tid() { int t = threadIdx.x; asm volatile("" : "+v"(t)); return t; }
; DI int fresh_bid() { int t = blockIdx.x; asm volatile("" : "+s"(t)); return t; }
; DI void cvt_job(LAS float* tile, const CvtJob& j, int& cursor) {
;   const int ntiles = (j.K / 64) * (j.ncols / 64); const int G = gridDim.x;
;   const int tid = fresh_tid();
;   int t = (fresh_bid() - cursor % G + G) % G;
;   cursor += ntiles;
;   __syncthreads();
;   CvtRegs cur, nxt; int buf = 0;
;   if (t < ntiles) cvt_load(j, t, tid, cur);
.LBB0_27:
	v_lshlrev_b32_e32 v10, 3, v12
	v_ashrrev_i32_e32 v33, 3, v12
	v_and_b32_e32 v12, 56, v10
	v_mov_b32_e32 v10, 0
	s_movk_i32 s18, 0x104
	v_mov_b32_e32 v25, v10
	s_lshl_b32 s23, s33, 6
	v_cndmask_b32_e64 v11, 0, 1, s[6:7]
	v_mul_lo_u32 v27, v22, s18
	v_mul_u32_u24_e32 v36, 0x104, v12
	v_lshl_add_u64 v[28:29], s[8:9], 0, v[24:25]
	s_lshl_b32 s29, s22, 6
	v_add_u32_e32 v25, s23, v22
	s_mov_b32 s24, 0
	s_movk_i32 s25, 0x1600
	s_movk_i32 s26, 0x5800
	v_cmp_ne_u32_e64 s[6:7], 1, v11
	s_movk_i32 s27, 0xff00
	v_lshlrev_b32_e32 v30, 1, v12
	s_waitcnt vmcnt(0)
	s_branch .LBB0_31

; #define LAS __attribute__((address_space(3)))
; DI void cvt_load(const CvtJob& j, int t, int tid, CvtRegs& R) {
;   const int nkt = j.K / 64; const int kt = t % nkt, ct = t / nkt; const int k0 = kt * 64, n0 = ct * 64;
;   const float* sp = j.mode == 2 ? j.src + (size_t)(n0 >> 9) * 512 * 512 + (n0 & 511) : j.src + n0;
; #pragma unroll
;   for (int i = 0; i < 2; ++i) {
;     const int r = (tid >> 4) + i * 32, c4 = (tid & 15) * 4;
;     R.v[i] = (f32x4){0.f, 0.f, 0.f, 0.f};
;     if (n0 + c4 < j.nvalid) R.v[i] = __builtin_nontemporal_load((const f32x4*)(sp + (size_t)(k0 + r) * j.ldsrc + c4));
; DI void cvt_job(LAS float* tile, const CvtJob& j, int& cursor) {
;     ...
;   for (; t < ntiles; t += G) {
;     const bool more = t + G < ntiles;
;     if (more) cvt_load(j, t + G, tid, nxt);
;     LAS float* tb = tile + buf * 4224;
;     cvt_write(tb, tid, cur);
;     asm volatile("s_waitcnt lgkmcnt(0)" ::: "memory"); __builtin_amdgcn_s_barrier(); asm volatile("" ::: "memory");
;     cvt_store(tb, j, t, tid);
;     if (more) cur = nxt;
;     buf ^= 1;
.LBB0_33:
	s_waitcnt vmcnt(1)
	v_mov_b64_e32 v[20:21], v[8:9]
	v_mov_b64_e32 v[16:17], v[4:5]
	s_andn2_b64 vcc, exec, s[8:9]
	v_mov_b64_e32 v[18:19], v[6:7]
	v_mov_b64_e32 v[14:15], v[2:3]
	s_cbranch_vccnz .LBB0_30
	s_ashr_i32 s8, s30, 31
	s_lshr_b32 s8, s8, 27
	s_add_i32 s8, s30, s8
	s_ashr_i32 s8, s8, 5
	s_lshl_b32 s9, s8, 11
	s_lshl_b32 s8, s8, 6
	s_sub_i32 s31, 0, s9
	s_ashr_i32 s9, s8, 31
	v_or_b32_e32 v11, s8, v1
	v_mov_b32_e32 v12, v10
	v_mov_b32_e32 v13, v10
	v_lshl_add_u64 v[34:35], s[8:9], 2, v[28:29]
	v_cmp_gt_i32_e64 s[8:9], s25, v11
	v_mov_b32_e32 v11, v10
	v_mov_b64_e32 v[16:17], v[12:13]
	v_mov_b64_e32 v[14:15], v[10:11]
	s_and_saveexec_b64 s[20:21], s[8:9]
	s_cbranch_execz .LBB0_36
	s_add_i32 s34, s31, s29
	v_add_u32_e32 v11, s34, v25
	v_mad_i64_i32 v[12:13], s[34:35], v11, s26, v[34:35]
	global_load_dwordx4 v[14:17], v[12:13], off nt

; #define LAS __attribute__((address_space(3)))
; DI int fresh_tid() { int t = threadIdx.x; asm volatile("" : "+v"(t)); return t; }
; DI int fresh_bid() { int t = blockIdx.x; asm volatile("" : "+s"(t)); return t; }
; DI void cvt_job(LAS float* tile, const CvtJob& j, int& cursor) {
;   const int ntiles = (j.K / 64) * (j.ncols / 64); const int G = gridDim.x;
;   const int tid = fresh_tid();
;   int t = (fresh_bid() - cursor % G + G) % G;
;   cursor += ntiles;
;   __syncthreads();
;   CvtRegs cur, nxt; int buf = 0;
;   if (t < ntiles) cvt_load(j, t, tid, cur);
.LBB0_54:
	v_lshlrev_b32_e32 v10, 3, v12
	v_ashrrev_i32_e32 v33, 3, v12
	v_and_b32_e32 v12, 56, v10
	v_mov_b32_e32 v10, 0
	s_movk_i32 s8, 0x104
	v_mov_b32_e32 v25, v10
	s_lshl_b32 s21, s33, 6
	v_cndmask_b32_e64 v11, 0, 1, s[6:7]
	v_mul_lo_u32 v27, v22, s8
	v_mul_u32_u24_e32 v36, 0x104, v12
	v_lshl_add_u64 v[28:29], s[10:11], 0, v[24:25]
	s_lshl_b32 s26, s20, 6
	v_add_u32_e32 v25, s21, v22
	s_mov_b32 s22, 0
	s_movk_i32 s23, 0x1600
	s_movk_i32 s24, 0x5800
	v_cmp_ne_u32_e64 s[6:7], 1, v11
	s_movk_i32 s25, 0x80
	v_lshlrev_b32_e32 v30, 1, v12
	s_waitcnt vmcnt(0)
	s_branch .LBB0_58

; #define LAS __attribute__((address_space(3)))
; DI void cvt_load(const CvtJob& j, int t, int tid, CvtRegs& R) {
;   const int nkt = j.K / 64; const int kt = t % nkt, ct = t / nkt; const int k0 = kt * 64, n0 = ct * 64;
;   const float* sp = j.mode == 2 ? j.src + (size_t)(n0 >> 9) * 512 * 512 + (n0 & 511) : j.src + n0;
; #pragma unroll
;   for (int i = 0; i < 2; ++i) {
;     const int r = (tid >> 4) + i * 32, c4 = (tid & 15) * 4;
;     R.v[i] = (f32x4){0.f, 0.f, 0.f, 0.f};
;     if (n0 + c4 < j.nvalid) R.v[i] = __builtin_nontemporal_load((const f32x4*)(sp + (size_t)(k0 + r) * j.ldsrc + c4));
; DI void cvt_job(LAS float* tile, const CvtJob& j, int& cursor) {
;     ...
;   for (; t < ntiles; t += G) {
;     const bool more = t + G < ntiles;
;     if (more) cvt_load(j, t + G, tid, nxt);
;     LAS float* tb = tile + buf * 4224;
;     cvt_write(tb, tid, cur);
;     asm volatile("s_waitcnt lgkmcnt(0)" ::: "memory"); __builtin_amdgcn_s_barrier(); asm volatile("" ::: "memory");
;     cvt_store(tb, j, t, tid);
;     if (more) cur = nxt;
;     buf ^= 1;
.LBB0_60:
	s_waitcnt vmcnt(1)
	v_mov_b64_e32 v[20:21], v[8:9]
	v_mov_b64_e32 v[16:17], v[4:5]
	s_andn2_b64 vcc, exec, s[8:9]
	v_mov_b64_e32 v[18:19], v[6:7]
	v_mov_b64_e32 v[14:15], v[2:3]
	s_cbranch_vccnz .LBB0_57
	s_ashr_i32 s8, s27, 31
	s_lshr_b32 s8, s8, 27
	s_add_i32 s8, s27, s8
	s_ashr_i32 s8, s8, 5
	s_lshl_b32 s9, s8, 11
	s_lshl_b32 s8, s8, 6
	s_sub_i32 s30, 0, s9
	s_ashr_i32 s9, s8, 31
	v_or_b32_e32 v11, s8, v1
	v_mov_b32_e32 v12, v10
	v_mov_b32_e32 v13, v10
	v_lshl_add_u64 v[34:35], s[8:9], 2, v[28:29]
	v_cmp_gt_i32_e64 s[8:9], s23, v11
	v_mov_b32_e32 v11, v10
	v_mov_b64_e32 v[16:17], v[12:13]
	v_mov_b64_e32 v[14:15], v[10:11]
	s_and_saveexec_b64 s[18:19], s[8:9]
	s_cbranch_execz .LBB0_63
	s_add_i32 s31, s30, s26
	v_add_u32_e32 v11, s31, v25
	v_mad_i64_i32 v[12:13], s[34:35], v11, s24, v[34:35]
	global_load_dwordx4 v[14:17], v[12:13], off nt

; #define PG8_STAGE(bufoff, gbase, voff) do { _Pragma("unroll") for (int _i = 0; _i < 2; ++_i) \
;     __builtin_amdgcn_global_load_lds((const unsigned*)((const char*)(gbase) + (voff)[_i]), (LAS unsigned*)(lds + (bufoff) + ldsw + _i * 8192), 16, 0, 0); } while (0)
; #define PG8_LDA(dst, b, h) do { _Pragma("unroll") for (int m = 0; m < 4; ++m) _Pragma("unroll") for (int k = 0; k < 2; ++k) dst[m][k] = *(const LAS bf16x8*)(lds + PG8_SA(b, h) + aoff + m * 2048 + k * 1024); } while (0)
; #define PG8_LDB(dst, b, h) do { _Pragma("unroll") for (int n = 0; n < 2; ++n) _Pragma("unroll") for (int k = 0; k < 2; ++k) dst[n][k] = *(const LAS bf16x8*)(lds + PG8_SB(b, h) + boff + n * 2048 + k * 1024); } while (0)
; #define PG8_MMA(ai, bj, At, Bt) do { __builtin_amdgcn_s_setprio(1); _Pragma("unroll") for (int m = 0; m < 4; ++m) _Pragma("unroll") for (int n = 0; n < 2; ++n) _Pragma("unroll") for (int k = 0; k < 2; ++k) \
;     acc[ai][bj][m][n] = __builtin_amdgcn_mfma_f32_16x16x32_bf16(Bt[n][k], At[m][k], acc[ai][bj][m][n], 0, 0, 0); __builtin_amdgcn_s_setprio(0); } while (0)
; #define PG8_WAIT_V(n) asm volatile("s_waitcnt vmcnt(" #n ")" ::: "memory")
; #define PG8_BAR __builtin_amdgcn_s_barrier()
; template <class Epi>
; DI void gemm_phase(LAS unsigned char* lds, const Gemm g, const Epi& E) {
;     ...
;     const bool has_next = S.next(ui + 1, nxt);
;     const char* nA = has_next ? PG8_APTR(nxt) : cA; const char* nB = has_next ? (const char*)g.Bt + (size_t)nxt.pn * tstepB : cB;
;     for (int t = 0; t < nt; t += 2) {
;       const bool last = (t == nt - 2);
;       const char* a1 = cA + (size_t)(t + 1) * kstep;
;       const char* a2 = last ? nA : cA + (size_t)(t + 2) * kstep; const char* b2 = last ? nB : cB + (size_t)(t + 2) * kstep;
;       const char* a3 = a2 + kstep; const char* b3 = b2 + kstep;
;       PG8_LDB(B0, 0, 0); PG8_SCHED; PG8_LDA(At, 0, 0); PG8_STAGE(PG8_SA(1, 1), a1 + hstepA, voffA);
;       PG8_WAIT_L(8); PG8_BAR; PG8_WAIT_L(0); PG8_MMA(0, 0, At, B0); PG8_BAR; PG8_SCHED;
;       PG8_LDB(B1, 0, 1); PG8_STAGE(PG8_SB(0, 0), b2, voffB);
;       PG8_BAR; PG8_WAIT_L(0); PG8_MMA(0, 1, At, B1); PG8_BAR;
;       PG8_LDA(At, 0, 1); PG8_STAGE(PG8_SA(0, 0), a2, voffA);
;       PG8_BAR; PG8_WAIT_L(0); PG8_MMA(1, 0, At, B0); PG8_BAR; PG8_SCHED;
;       PG8_STAGE(PG8_SB(0, 1), b2 + hstepB, voffB);
;       PG8_WAIT_V(6); PG8_BAR; PG8_MMA(1, 1, At, B1); PG8_BAR;
.LBB0_189:
	s_ashr_i32 s13, s12, 31
	v_cmp_lt_i64_e32 vcc, s[18:19], v[170:171]
	s_lshl_b64 s[18:19], s[12:13], 20
	s_add_u32 s18, s42, s18
	s_addc_u32 s19, s43, s19
	s_and_b64 s[22:23], vcc, exec
	s_cselect_b32 s13, s19, s31
	s_cselect_b32 s55, s18, s30
	s_ashr_i32 s3, s2, 31
	s_lshl_b64 s[22:23], s[2:3], 20
	s_add_u32 s22, s44, s22
	s_addc_u32 s23, s45, s23
	s_and_b64 s[40:41], vcc, exec
	s_cselect_b32 s3, s23, s37
	s_cselect_b32 s56, s22, s36
	s_add_u32 s30, s30, 0x80080
	s_addc_u32 s31, s31, 0
	s_add_u32 s57, s36, 0x100
	s_addc_u32 s58, s37, 0
	s_mov_b32 s59, -2
	v_add_u32_e32 v248, 0x10000, v143
	ds_read_b128 v[146:149], v248
	ds_read_b128 v[150:153], v248 offset:1024
	ds_read_b128 v[154:157], v248 offset:2048
	ds_read_b128 v[158:161], v248 offset:3072
	s_add_i32 m0, s27, 0xc000
	ds_read_b128 v[180:183], v145
	ds_read_b128 v[184:187], v145 offset:1024
	ds_read_b128 v[188:191], v145 offset:2048
	ds_read_b128 v[192:195], v145 offset:3072
	ds_read_b128 v[196:199], v145 offset:4096
	ds_read_b128 v[200:203], v145 offset:5120
	ds_read_b128 v[208:211], v145 offset:6144
	ds_read_b128 v[212:215], v145 offset:7168
	global_load_lds_dwordx4 v138, s[30:31]
	s_add_i32 m0, s27, 0xe000
	s_nop 0
	global_load_lds_dwordx4 v140, s[30:31]
	s_waitcnt lgkmcnt(8)
	s_barrier
	s_waitcnt lgkmcnt(0)
	s_setprio 1
	s_waitcnt lgkmcnt(0)
	v_mfma_f32_16x16x32_bf16 v[128:131], v[146:149], v[180:183], 0
	s_add_u32 s36, s30, 0xfff80080
	s_addc_u32 s37, s31, -1
	v_mfma_f32_16x16x32_bf16 v[120:123], v[154:157], v[180:183], 0
	s_add_i32 s60, 0, 0x10000
	v_mfma_f32_16x16x32_bf16 v[112:115], v[146:149], v[188:191], 0
	s_cmp_eq_u32 s59, 28
	s_cselect_b32 s41, s13, s37
	s_cselect_b32 s40, s55, s36
	s_cselect_b32 s37, s3, s58
	s_cselect_b32 s36, s56, s57
	v_mfma_f32_16x16x32_bf16 v[104:107], v[154:157], v[188:191], 0
	v_mfma_f32_16x16x32_bf16 v[96:99], v[146:149], v[196:199], 0
	v_mfma_f32_16x16x32_bf16 v[88:91], v[154:157], v[196:199], 0
	v_mfma_f32_16x16x32_bf16 v[80:83], v[146:149], v[208:211], 0
	v_mfma_f32_16x16x32_bf16 v[72:75], v[154:157], v[208:211], 0
	v_mfma_f32_16x16x32_bf16 v[128:131], v[150:153], v[184:187], v[128:131]
	v_mfma_f32_16x16x32_bf16 v[120:123], v[158:161], v[184:187], v[120:123]
	v_mfma_f32_16x16x32_bf16 v[112:115], v[150:153], v[192:195], v[112:115]
	v_mfma_f32_16x16x32_bf16 v[104:107], v[158:161], v[192:195], v[104:107]
	v_mfma_f32_16x16x32_bf16 v[96:99], v[150:153], v[200:203], v[96:99]
	v_mfma_f32_16x16x32_bf16 v[88:91], v[158:161], v[200:203], v[88:91]
	s_setprio 2
	s_barrier
	v_mfma_f32_16x16x32_bf16 v[80:83], v[150:153], v[212:215], v[80:83]
	v_mfma_f32_16x16x32_bf16 v[72:75], v[158:161], v[212:215], v[72:75]
	s_setprio 0
	s_add_i32 s62, 0, 0x14000
	s_add_i32 s60, s60, s47
	ds_read_b128 v[216:219], v248 offset:16384
	ds_read_b128 v[220:223], v248 offset:17408
	ds_read_b128 v[224:227], v248 offset:18432
	ds_read_b128 v[228:231], v248 offset:19456
	s_add_u32 s98, s36, 0x80
	s_addc_u32 s99, s37, 0
	s_mov_b32 m0, s60
	global_load_lds_dwordx4 v2, s[36:37]
	s_add_i32 m0, s60, 0x2000
	s_nop 0
	global_load_lds_dwordx4 v132, s[36:37]
	s_barrier
	s_waitcnt lgkmcnt(0)
	s_setprio 1
	s_waitcnt lgkmcnt(0)
	v_mfma_f32_16x16x32_bf16 v[124:127], v[216:219], v[180:183], 0
	v_mfma_f32_16x16x32_bf16 v[116:119], v[224:227], v[180:183], 0
	v_mfma_f32_16x16x32_bf16 v[108:111], v[216:219], v[188:191], 0
	v_mfma_f32_16x16x32_bf16 v[100:103], v[224:227], v[188:191], 0
	v_mfma_f32_16x16x32_bf16 v[92:95], v[216:219], v[196:199], 0
	v_mfma_f32_16x16x32_bf16 v[84:87], v[224:227], v[196:199], 0
	v_mfma_f32_16x16x32_bf16 v[76:79], v[216:219], v[208:211], 0
	v_mfma_f32_16x16x32_bf16 v[68:71], v[224:227], v[208:211], 0
	v_mfma_f32_16x16x32_bf16 v[124:127], v[220:223], v[184:187], v[124:127]
	v_mfma_f32_16x16x32_bf16 v[116:119], v[228:231], v[184:187], v[116:119]
	v_mfma_f32_16x16x32_bf16 v[108:111], v[220:223], v[192:195], v[108:111]
	v_mfma_f32_16x16x32_bf16 v[100:103], v[228:231], v[192:195], v[100:103]
	v_mfma_f32_16x16x32_bf16 v[92:95], v[220:223], v[200:203], v[92:95]
	v_mfma_f32_16x16x32_bf16 v[84:87], v[228:231], v[200:203], v[84:87]
	s_setprio 2
	s_barrier
	v_mfma_f32_16x16x32_bf16 v[76:79], v[220:223], v[212:215], v[76:79]
	v_mfma_f32_16x16x32_bf16 v[68:71], v[228:231], v[212:215], v[68:71]
	s_setprio 0
	s_mov_b32 m0, s27
	s_add_u32 s100, s40, 0x80
	s_addc_u32 s101, s41, 0
	ds_read_b128 v[180:183], v145 offset:16384
	ds_read_b128 v[184:187], v145 offset:17408
	ds_read_b128 v[188:191], v145 offset:18432
	ds_read_b128 v[192:195], v145 offset:19456
	ds_read_b128 v[196:199], v145 offset:20480
	ds_read_b128 v[200:203], v145 offset:21504
	ds_read_b128 v[208:211], v145 offset:22528
	ds_read_b128 v[212:215], v145 offset:23552
	global_load_lds_dwordx4 v136, s[40:41]
	s_mov_b32 m0, s48
	s_nop 0
	global_load_lds_dwordx4 v134, s[40:41]
	s_waitcnt vmcnt(10)
	s_barrier
	s_waitcnt lgkmcnt(0)
	s_setprio 1
	s_waitcnt lgkmcnt(0)
	v_mfma_f32_16x16x32_bf16 v[64:67], v[146:149], v[180:183], 0
	v_mfma_f32_16x16x32_bf16 v[56:59], v[154:157], v[180:183], 0
	v_mfma_f32_16x16x32_bf16 v[48:51], v[146:149], v[188:191], 0
	v_mfma_f32_16x16x32_bf16 v[40:43], v[154:157], v[188:191], 0
	v_mfma_f32_16x16x32_bf16 v[32:35], v[146:149], v[196:199], 0
	v_mfma_f32_16x16x32_bf16 v[24:27], v[154:157], v[196:199], 0
	v_mfma_f32_16x16x32_bf16 v[16:19], v[146:149], v[208:211], 0
	v_mfma_f32_16x16x32_bf16 v[8:11], v[154:157], v[208:211], 0
	v_mfma_f32_16x16x32_bf16 v[64:67], v[150:153], v[184:187], v[64:67]
	v_mfma_f32_16x16x32_bf16 v[56:59], v[158:161], v[184:187], v[56:59]
	v_mfma_f32_16x16x32_bf16 v[48:51], v[150:153], v[192:195], v[48:51]
	v_mfma_f32_16x16x32_bf16 v[40:43], v[158:161], v[192:195], v[40:43]
	v_mfma_f32_16x16x32_bf16 v[32:35], v[150:153], v[200:203], v[32:35]
	v_mfma_f32_16x16x32_bf16 v[24:27], v[158:161], v[200:203], v[24:27]
	s_setprio 2
	s_barrier
; #define PG8_STAGE(bufoff, gbase, voff) do { _Pragma("unroll") for (int _i = 0; _i < 2; ++_i) \
;     __builtin_amdgcn_global_load_lds((const unsigned*)((const char*)(gbase) + (voff)[_i]), (LAS unsigned*)(lds + (bufoff) + ldsw + _i * 8192), 16, 0, 0); } while (0)
; #define PG8_LDA(dst, b, h) do { _Pragma("unroll") for (int m = 0; m < 4; ++m) _Pragma("unroll") for (int k = 0; k < 2; ++k) dst[m][k] = *(const LAS bf16x8*)(lds + PG8_SA(b, h) + aoff + m * 2048 + k * 1024); } while (0)
; #define PG8_LDB(dst, b, h) do { _Pragma("unroll") for (int n = 0; n < 2; ++n) _Pragma("unroll") for (int k = 0; k < 2; ++k) dst[n][k] = *(const LAS bf16x8*)(lds + PG8_SB(b, h) + boff + n * 2048 + k * 1024); } while (0)
; #define PG8_MMA(ai, bj, At, Bt) do { __builtin_amdgcn_s_setprio(1); _Pragma("unroll") for (int m = 0; m < 4; ++m) _Pragma("unroll") for (int n = 0; n < 2; ++n) _Pragma("unroll") for (int k = 0; k < 2; ++k) \
;     acc[ai][bj][m][n] = __builtin_amdgcn_mfma_f32_16x16x32_bf16(Bt[n][k], At[m][k], acc[ai][bj][m][n], 0, 0, 0); __builtin_amdgcn_s_setprio(0); } while (0)
; #define PG8_WAIT_V(n) asm volatile("s_waitcnt vmcnt(" #n ")" ::: "memory")
; #define PG8_WAIT_L(n) asm volatile("s_waitcnt lgkmcnt(" #n ")" ::: "memory")
; #define PG8_BAR __builtin_amdgcn_s_barrier()
; #define PG8_SCHED __builtin_amdgcn_sched_barrier(0)
; template <class Epi>
; DI void gemm_phase(LAS unsigned char* lds, const Gemm g, const Epi& E) {
;     ...
;       PG8_WAIT_V(6); PG8_BAR; PG8_MMA(1, 1, At, B1); PG8_BAR;
;       PG8_LDB(B0, 1, 0); PG8_SCHED; PG8_LDA(At, 1, 0); PG8_STAGE(PG8_SA(0, 1), a2 + hstepA, voffA);
;       PG8_WAIT_L(8); PG8_BAR; PG8_WAIT_L(0); PG8_MMA(0, 0, At, B0); PG8_BAR; PG8_SCHED;
;       PG8_LDB(B1, 1, 1); PG8_STAGE(PG8_SB(1, 0), b3, voffB);
;       PG8_BAR; PG8_WAIT_L(0); PG8_MMA(0, 1, At, B1); PG8_BAR;
;       PG8_LDA(At, 1, 1); PG8_STAGE(PG8_SA(1, 0), a3, voffA);
;       PG8_BAR; PG8_WAIT_L(0); PG8_MMA(1, 0, At, B0); PG8_BAR; PG8_SCHED;
	v_mfma_f32_16x16x32_bf16 v[16:19], v[150:153], v[212:215], v[16:19]
	v_mfma_f32_16x16x32_bf16 v[8:11], v[158:161], v[212:215], v[8:11]
	s_setprio 0
	ds_read_b128 v[146:149], v248 offset:32768
	ds_read_b128 v[150:153], v248 offset:33792
	ds_read_b128 v[154:157], v248 offset:34816
	ds_read_b128 v[158:161], v248 offset:35840
	s_add_u32 s60, s36, 0x80000
	s_addc_u32 s61, s37, 0
	s_add_i32 s62, s62, s47
	s_mov_b32 m0, s62
	s_nop 0
	global_load_lds_dwordx4 v2, s[60:61]
	s_add_i32 m0, s62, 0x2000
	s_nop 0
	global_load_lds_dwordx4 v132, s[60:61]
	s_waitcnt vmcnt(6)
	s_barrier
	s_setprio 1
	v_mfma_f32_16x16x32_bf16 v[60:63], v[216:219], v[180:183], 0
	v_mfma_f32_16x16x32_bf16 v[52:55], v[224:227], v[180:183], 0
	v_mfma_f32_16x16x32_bf16 v[44:47], v[216:219], v[188:191], 0
	v_mfma_f32_16x16x32_bf16 v[36:39], v[224:227], v[188:191], 0
	v_mfma_f32_16x16x32_bf16 v[28:31], v[216:219], v[196:199], 0
	v_mfma_f32_16x16x32_bf16 v[20:23], v[224:227], v[196:199], 0
	v_mfma_f32_16x16x32_bf16 v[12:15], v[216:219], v[208:211], 0
	v_mfma_f32_16x16x32_bf16 v[4:7], v[224:227], v[208:211], 0
	v_mfma_f32_16x16x32_bf16 v[60:63], v[220:223], v[184:187], v[60:63]
	v_mfma_f32_16x16x32_bf16 v[52:55], v[228:231], v[184:187], v[52:55]
	v_mfma_f32_16x16x32_bf16 v[44:47], v[220:223], v[192:195], v[44:47]
	v_mfma_f32_16x16x32_bf16 v[36:39], v[228:231], v[192:195], v[36:39]
	v_mfma_f32_16x16x32_bf16 v[28:31], v[220:223], v[200:203], v[28:31]
	v_mfma_f32_16x16x32_bf16 v[20:23], v[228:231], v[200:203], v[20:23]
	s_setprio 2
	s_barrier
	v_mfma_f32_16x16x32_bf16 v[12:15], v[220:223], v[212:215], v[12:15]
	v_mfma_f32_16x16x32_bf16 v[4:7], v[228:231], v[212:215], v[4:7]
	s_setprio 0
	s_add_i32 s60, 0, 0x18000
	s_add_u32 s40, s40, 0x80000
	s_addc_u32 s41, s41, 0
	s_mov_b32 m0, s49
	ds_read_b128 v[180:183], v145 offset:32768
	ds_read_b128 v[184:187], v145 offset:33792
	ds_read_b128 v[188:191], v145 offset:34816
	ds_read_b128 v[192:195], v145 offset:35840
	ds_read_b128 v[196:199], v145 offset:36864
	ds_read_b128 v[200:203], v145 offset:37888
	ds_read_b128 v[208:211], v145 offset:38912
	ds_read_b128 v[212:215], v145 offset:39936
	global_load_lds_dwordx4 v136, s[40:41]
	s_mov_b32 m0, s50
	s_nop 0
	global_load_lds_dwordx4 v134, s[40:41]
	s_waitcnt lgkmcnt(8)
	s_barrier
	s_waitcnt lgkmcnt(0)
	s_setprio 1
	s_waitcnt lgkmcnt(0)
	v_mfma_f32_16x16x32_bf16 v[128:131], v[146:149], v[180:183], v[128:131]
	v_mfma_f32_16x16x32_bf16 v[120:123], v[154:157], v[180:183], v[120:123]
	v_mfma_f32_16x16x32_bf16 v[112:115], v[146:149], v[188:191], v[112:115]
	v_mfma_f32_16x16x32_bf16 v[104:107], v[154:157], v[188:191], v[104:107]
	v_mfma_f32_16x16x32_bf16 v[96:99], v[146:149], v[196:199], v[96:99]
	v_mfma_f32_16x16x32_bf16 v[88:91], v[154:157], v[196:199], v[88:91]
	v_mfma_f32_16x16x32_bf16 v[80:83], v[146:149], v[208:211], v[80:83]
	v_mfma_f32_16x16x32_bf16 v[72:75], v[154:157], v[208:211], v[72:75]
	v_mfma_f32_16x16x32_bf16 v[128:131], v[150:153], v[184:187], v[128:131]
	v_mfma_f32_16x16x32_bf16 v[120:123], v[158:161], v[184:187], v[120:123]
	v_mfma_f32_16x16x32_bf16 v[112:115], v[150:153], v[192:195], v[112:115]
	v_mfma_f32_16x16x32_bf16 v[104:107], v[158:161], v[192:195], v[104:107]
	v_mfma_f32_16x16x32_bf16 v[96:99], v[150:153], v[200:203], v[96:99]
	v_mfma_f32_16x16x32_bf16 v[88:91], v[158:161], v[200:203], v[88:91]
	s_setprio 2
	s_barrier
	v_mfma_f32_16x16x32_bf16 v[80:83], v[150:153], v[212:215], v[80:83]
	v_mfma_f32_16x16x32_bf16 v[72:75], v[158:161], v[212:215], v[72:75]
	s_setprio 0
	s_add_i32 s40, 0, 0x1c000
	s_add_i32 s41, s60, s47
	s_mov_b32 m0, s41
	ds_read_b128 v[216:219], v248 offset:49152
	ds_read_b128 v[220:223], v248 offset:50176
	ds_read_b128 v[224:227], v248 offset:51200
	ds_read_b128 v[228:231], v248 offset:52224
	global_load_lds_dwordx4 v2, s[98:99]
	s_add_i32 m0, s41, 0x2000
	s_nop 0
	global_load_lds_dwordx4 v132, s[98:99]
	s_barrier
	s_waitcnt lgkmcnt(0)
	s_setprio 1
	s_waitcnt lgkmcnt(0)
	v_mfma_f32_16x16x32_bf16 v[124:127], v[216:219], v[180:183], v[124:127]
	v_mfma_f32_16x16x32_bf16 v[116:119], v[224:227], v[180:183], v[116:119]
	v_mfma_f32_16x16x32_bf16 v[108:111], v[216:219], v[188:191], v[108:111]
	v_mfma_f32_16x16x32_bf16 v[100:103], v[224:227], v[188:191], v[100:103]
	v_mfma_f32_16x16x32_bf16 v[92:95], v[216:219], v[196:199], v[92:95]
	v_mfma_f32_16x16x32_bf16 v[84:87], v[224:227], v[196:199], v[84:87]
	v_mfma_f32_16x16x32_bf16 v[76:79], v[216:219], v[208:211], v[76:79]
	v_mfma_f32_16x16x32_bf16 v[68:71], v[224:227], v[208:211], v[68:71]
	v_mfma_f32_16x16x32_bf16 v[124:127], v[220:223], v[184:187], v[124:127]
	v_mfma_f32_16x16x32_bf16 v[116:119], v[228:231], v[184:187], v[116:119]
	v_mfma_f32_16x16x32_bf16 v[108:111], v[220:223], v[192:195], v[108:111]
	v_mfma_f32_16x16x32_bf16 v[100:103], v[228:231], v[192:195], v[100:103]
	v_mfma_f32_16x16x32_bf16 v[92:95], v[220:223], v[200:203], v[92:95]
	v_mfma_f32_16x16x32_bf16 v[84:87], v[228:231], v[200:203], v[84:87]
	s_setprio 2
	s_barrier
	v_mfma_f32_16x16x32_bf16 v[76:79], v[220:223], v[212:215], v[76:79]
	v_mfma_f32_16x16x32_bf16 v[68:71], v[228:231], v[212:215], v[68:71]
	s_setprio 0
	s_mov_b32 m0, s51
	ds_read_b128 v[180:183], v145 offset:49152
	ds_read_b128 v[184:187], v145 offset:50176
	ds_read_b128 v[188:191], v145 offset:51200
	ds_read_b128 v[192:195], v145 offset:52224
	ds_read_b128 v[196:199], v145 offset:53248
	ds_read_b128 v[200:203], v145 offset:54272
	ds_read_b128 v[208:211], v145 offset:55296
	ds_read_b128 v[212:215], v145 offset:56320
	global_load_lds_dwordx4 v136, s[100:101]
	s_mov_b32 m0, s52
	s_nop 0
	global_load_lds_dwordx4 v134, s[100:101]
	s_waitcnt vmcnt(10)
	s_barrier
; #define PG8_STAGE(bufoff, gbase, voff) do { _Pragma("unroll") for (int _i = 0; _i < 2; ++_i) \
;     __builtin_amdgcn_global_load_lds((const unsigned*)((const char*)(gbase) + (voff)[_i]), (LAS unsigned*)(lds + (bufoff) + ldsw + _i * 8192), 16, 0, 0); } while (0)
; #define PG8_LDA(dst, b, h) do { _Pragma("unroll") for (int m = 0; m < 4; ++m) _Pragma("unroll") for (int k = 0; k < 2; ++k) dst[m][k] = *(const LAS bf16x8*)(lds + PG8_SA(b, h) + aoff + m * 2048 + k * 1024); } while (0)
; #define PG8_LDB(dst, b, h) do { _Pragma("unroll") for (int n = 0; n < 2; ++n) _Pragma("unroll") for (int k = 0; k < 2; ++k) dst[n][k] = *(const LAS bf16x8*)(lds + PG8_SB(b, h) + boff + n * 2048 + k * 1024); } while (0)
; #define PG8_MMA(ai, bj, At, Bt) do { __builtin_amdgcn_s_setprio(1); _Pragma("unroll") for (int m = 0; m < 4; ++m) _Pragma("unroll") for (int n = 0; n < 2; ++n) _Pragma("unroll") for (int k = 0; k < 2; ++k) \
;     acc[ai][bj][m][n] = __builtin_amdgcn_mfma_f32_16x16x32_bf16(Bt[n][k], At[m][k], acc[ai][bj][m][n], 0, 0, 0); __builtin_amdgcn_s_setprio(0); } while (0)
; #define PG8_WAIT_V(n) asm volatile("s_waitcnt vmcnt(" #n ")" ::: "memory")
; #define PG8_WAIT_L(n) asm volatile("s_waitcnt lgkmcnt(" #n ")" ::: "memory")
; #define PG8_BAR __builtin_amdgcn_s_barrier()
; #define PG8_SCHED __builtin_amdgcn_sched_barrier(0)
; template <class Epi>
; DI void gemm_phase(LAS unsigned char* lds, const Gemm g, const Epi& E) {
;     ...
;       PG8_LDB(B0, 0, 0); PG8_SCHED; PG8_LDA(At, 0, 0); PG8_STAGE(PG8_SA(1, 1), a1 + hstepA, voffA);
;       PG8_WAIT_L(8); PG8_BAR; PG8_WAIT_L(0); PG8_MMA(0, 0, At, B0); PG8_BAR; PG8_SCHED;
;       PG8_LDB(B1, 0, 1); PG8_STAGE(PG8_SB(0, 0), b2, voffB);
;       PG8_BAR; PG8_WAIT_L(0); PG8_MMA(0, 1, At, B1); PG8_BAR;
;     ...
;       PG8_BAR; PG8_WAIT_L(0); PG8_MMA(1, 0, At, B0); PG8_BAR; PG8_SCHED;
;       PG8_STAGE(PG8_SB(1, 1), b3 + hstepB, voffB);
;       PG8_WAIT_V(6); PG8_BAR; PG8_MMA(1, 1, At, B1); PG8_BAR;
	s_waitcnt lgkmcnt(0)
	s_setprio 1
	s_waitcnt lgkmcnt(0)
	v_mfma_f32_16x16x32_bf16 v[64:67], v[146:149], v[180:183], v[64:67]
	v_mfma_f32_16x16x32_bf16 v[56:59], v[154:157], v[180:183], v[56:59]
	v_mfma_f32_16x16x32_bf16 v[48:51], v[146:149], v[188:191], v[48:51]
	v_mfma_f32_16x16x32_bf16 v[40:43], v[154:157], v[188:191], v[40:43]
	v_mfma_f32_16x16x32_bf16 v[32:35], v[146:149], v[196:199], v[32:35]
	v_mfma_f32_16x16x32_bf16 v[24:27], v[154:157], v[196:199], v[24:27]
	v_mfma_f32_16x16x32_bf16 v[16:19], v[146:149], v[208:211], v[16:19]
	v_mfma_f32_16x16x32_bf16 v[8:11], v[154:157], v[208:211], v[8:11]
	v_mfma_f32_16x16x32_bf16 v[64:67], v[150:153], v[184:187], v[64:67]
	v_mfma_f32_16x16x32_bf16 v[56:59], v[158:161], v[184:187], v[56:59]
	v_mfma_f32_16x16x32_bf16 v[48:51], v[150:153], v[192:195], v[48:51]
	v_mfma_f32_16x16x32_bf16 v[40:43], v[158:161], v[192:195], v[40:43]
	v_mfma_f32_16x16x32_bf16 v[32:35], v[150:153], v[200:203], v[32:35]
	v_mfma_f32_16x16x32_bf16 v[24:27], v[158:161], v[200:203], v[24:27]
	s_setprio 2
	s_barrier
	v_mfma_f32_16x16x32_bf16 v[16:19], v[150:153], v[212:215], v[16:19]
	v_mfma_f32_16x16x32_bf16 v[8:11], v[158:161], v[212:215], v[8:11]
	s_setprio 0
	ds_read_b128 v[146:149], v248
	ds_read_b128 v[150:153], v248 offset:1024
	ds_read_b128 v[154:157], v248 offset:2048
	ds_read_b128 v[158:161], v248 offset:3072
	s_add_u32 s36, s36, 0x80080
	s_addc_u32 s37, s37, 0
	s_add_i32 s40, s40, s47
	s_mov_b32 m0, s40
	s_nop 0
	global_load_lds_dwordx4 v2, s[36:37]
	s_add_i32 m0, s40, 0x2000
	s_nop 0
	global_load_lds_dwordx4 v132, s[36:37]
	s_waitcnt vmcnt(6)
	s_barrier
	s_setprio 1
	v_mfma_f32_16x16x32_bf16 v[60:63], v[216:219], v[180:183], v[60:63]
	v_mfma_f32_16x16x32_bf16 v[52:55], v[224:227], v[180:183], v[52:55]
	v_mfma_f32_16x16x32_bf16 v[44:47], v[216:219], v[188:191], v[44:47]
	v_mfma_f32_16x16x32_bf16 v[36:39], v[224:227], v[188:191], v[36:39]
	v_mfma_f32_16x16x32_bf16 v[28:31], v[216:219], v[196:199], v[28:31]
	v_mfma_f32_16x16x32_bf16 v[20:23], v[224:227], v[196:199], v[20:23]
	v_mfma_f32_16x16x32_bf16 v[12:15], v[216:219], v[208:211], v[12:15]
	v_mfma_f32_16x16x32_bf16 v[4:7], v[224:227], v[208:211], v[4:7]
	v_mfma_f32_16x16x32_bf16 v[60:63], v[220:223], v[184:187], v[60:63]
	v_mfma_f32_16x16x32_bf16 v[52:55], v[228:231], v[184:187], v[52:55]
	v_mfma_f32_16x16x32_bf16 v[44:47], v[220:223], v[192:195], v[44:47]
	v_mfma_f32_16x16x32_bf16 v[36:39], v[228:231], v[192:195], v[36:39]
	v_mfma_f32_16x16x32_bf16 v[28:31], v[220:223], v[200:203], v[28:31]
	v_mfma_f32_16x16x32_bf16 v[20:23], v[228:231], v[200:203], v[20:23]
	s_setprio 2
	s_barrier
	v_mfma_f32_16x16x32_bf16 v[12:15], v[220:223], v[212:215], v[12:15]
	v_mfma_f32_16x16x32_bf16 v[4:7], v[228:231], v[212:215], v[4:7]
	s_setprio 0
	s_add_i32 s59, s59, 2
	s_add_u32 s30, s30, 0x100
	s_addc_u32 s31, s31, 0
	s_add_u32 s57, s57, 0x100
	s_addc_u32 s58, s58, 0
	s_cmp_gt_u32 s59, 29
	s_cbranch_scc1 .Lpeel_exit_190
.LBB0_190:
	s_add_i32 m0, s27, 0xc000
	ds_read_b128 v[180:183], v145
	ds_read_b128 v[184:187], v145 offset:1024
	ds_read_b128 v[188:191], v145 offset:2048
	ds_read_b128 v[192:195], v145 offset:3072
	ds_read_b128 v[196:199], v145 offset:4096
	ds_read_b128 v[200:203], v145 offset:5120
	ds_read_b128 v[208:211], v145 offset:6144
	ds_read_b128 v[212:215], v145 offset:7168
	global_load_lds_dwordx4 v138, s[30:31]
	s_add_i32 m0, s27, 0xe000
	s_nop 0
	global_load_lds_dwordx4 v140, s[30:31]
	s_waitcnt lgkmcnt(8)
	s_barrier
	s_waitcnt lgkmcnt(0)
	s_setprio 1
	s_waitcnt lgkmcnt(0)
	v_mfma_f32_16x16x32_bf16 v[128:131], v[146:149], v[180:183], v[128:131]
	s_add_u32 s36, s30, 0xfff80080
	s_addc_u32 s37, s31, -1
	v_mfma_f32_16x16x32_bf16 v[120:123], v[154:157], v[180:183], v[120:123]
	s_add_i32 s60, 0, 0x10000
	v_mfma_f32_16x16x32_bf16 v[112:115], v[146:149], v[188:191], v[112:115]
	s_cmp_eq_u32 s59, 28
	s_cselect_b32 s41, s13, s37
	s_cselect_b32 s40, s55, s36
	s_cselect_b32 s37, s3, s58
	s_cselect_b32 s36, s56, s57
	v_mfma_f32_16x16x32_bf16 v[104:107], v[154:157], v[188:191], v[104:107]
	v_mfma_f32_16x16x32_bf16 v[96:99], v[146:149], v[196:199], v[96:99]
	v_mfma_f32_16x16x32_bf16 v[88:91], v[154:157], v[196:199], v[88:91]
	v_mfma_f32_16x16x32_bf16 v[80:83], v[146:149], v[208:211], v[80:83]
	v_mfma_f32_16x16x32_bf16 v[72:75], v[154:157], v[208:211], v[72:75]
	v_mfma_f32_16x16x32_bf16 v[128:131], v[150:153], v[184:187], v[128:131]
	v_mfma_f32_16x16x32_bf16 v[120:123], v[158:161], v[184:187], v[120:123]
	v_mfma_f32_16x16x32_bf16 v[112:115], v[150:153], v[192:195], v[112:115]
	v_mfma_f32_16x16x32_bf16 v[104:107], v[158:161], v[192:195], v[104:107]
	v_mfma_f32_16x16x32_bf16 v[96:99], v[150:153], v[200:203], v[96:99]
	v_mfma_f32_16x16x32_bf16 v[88:91], v[158:161], v[200:203], v[88:91]
	s_setprio 2
	s_barrier
	v_mfma_f32_16x16x32_bf16 v[80:83], v[150:153], v[212:215], v[80:83]
	v_mfma_f32_16x16x32_bf16 v[72:75], v[158:161], v[212:215], v[72:75]
	s_setprio 0
	s_add_i32 s62, 0, 0x14000
	s_add_i32 s60, s60, s47
	ds_read_b128 v[216:219], v248 offset:16384
	ds_read_b128 v[220:223], v248 offset:17408
	ds_read_b128 v[224:227], v248 offset:18432
	ds_read_b128 v[228:231], v248 offset:19456
	s_add_u32 s98, s36, 0x80
	s_addc_u32 s99, s37, 0
	s_mov_b32 m0, s60
	global_load_lds_dwordx4 v2, s[36:37]
	s_add_i32 m0, s60, 0x2000
	s_nop 0
	global_load_lds_dwordx4 v132, s[36:37]
	s_barrier
; #define PG8_STAGE(bufoff, gbase, voff) do { _Pragma("unroll") for (int _i = 0; _i < 2; ++_i) \
;     __builtin_amdgcn_global_load_lds((const unsigned*)((const char*)(gbase) + (voff)[_i]), (LAS unsigned*)(lds + (bufoff) + ldsw + _i * 8192), 16, 0, 0); } while (0)
; #define PG8_LDA(dst, b, h) do { _Pragma("unroll") for (int m = 0; m < 4; ++m) _Pragma("unroll") for (int k = 0; k < 2; ++k) dst[m][k] = *(const LAS bf16x8*)(lds + PG8_SA(b, h) + aoff + m * 2048 + k * 1024); } while (0)
; #define PG8_LDB(dst, b, h) do { _Pragma("unroll") for (int n = 0; n < 2; ++n) _Pragma("unroll") for (int k = 0; k < 2; ++k) dst[n][k] = *(const LAS bf16x8*)(lds + PG8_SB(b, h) + boff + n * 2048 + k * 1024); } while (0)
; #define PG8_MMA(ai, bj, At, Bt) do { __builtin_amdgcn_s_setprio(1); _Pragma("unroll") for (int m = 0; m < 4; ++m) _Pragma("unroll") for (int n = 0; n < 2; ++n) _Pragma("unroll") for (int k = 0; k < 2; ++k) \
;     acc[ai][bj][m][n] = __builtin_amdgcn_mfma_f32_16x16x32_bf16(Bt[n][k], At[m][k], acc[ai][bj][m][n], 0, 0, 0); __builtin_amdgcn_s_setprio(0); } while (0)
; #define PG8_WAIT_V(n) asm volatile("s_waitcnt vmcnt(" #n ")" ::: "memory")
; #define PG8_WAIT_L(n) asm volatile("s_waitcnt lgkmcnt(" #n ")" ::: "memory")
; #define PG8_BAR __builtin_amdgcn_s_barrier()
; #define PG8_SCHED __builtin_amdgcn_sched_barrier(0)
; template <class Epi>
; DI void gemm_phase(LAS unsigned char* lds, const Gemm g, const Epi& E) {
;     ...
;       PG8_BAR; PG8_WAIT_L(0); PG8_MMA(0, 1, At, B1); PG8_BAR;
;       PG8_LDA(At, 0, 1); PG8_STAGE(PG8_SA(0, 0), a2, voffA);
;       PG8_BAR; PG8_WAIT_L(0); PG8_MMA(1, 0, At, B0); PG8_BAR; PG8_SCHED;
;       PG8_STAGE(PG8_SB(0, 1), b2 + hstepB, voffB);
;       PG8_WAIT_V(6); PG8_BAR; PG8_MMA(1, 1, At, B1); PG8_BAR;
;       PG8_LDB(B0, 1, 0); PG8_SCHED; PG8_LDA(At, 1, 0); PG8_STAGE(PG8_SA(0, 1), a2 + hstepA, voffA);
;       PG8_WAIT_L(8); PG8_BAR; PG8_WAIT_L(0); PG8_MMA(0, 0, At, B0); PG8_BAR; PG8_SCHED;
;       PG8_LDB(B1, 1, 1); PG8_STAGE(PG8_SB(1, 0), b3, voffB);
;       PG8_BAR; PG8_WAIT_L(0); PG8_MMA(0, 1, At, B1); PG8_BAR;
;       PG8_LDA(At, 1, 1); PG8_STAGE(PG8_SA(1, 0), a3, voffA);
	s_waitcnt lgkmcnt(0)
	s_setprio 1
	s_waitcnt lgkmcnt(0)
	v_mfma_f32_16x16x32_bf16 v[124:127], v[216:219], v[180:183], v[124:127]
	v_mfma_f32_16x16x32_bf16 v[116:119], v[224:227], v[180:183], v[116:119]
	v_mfma_f32_16x16x32_bf16 v[108:111], v[216:219], v[188:191], v[108:111]
	v_mfma_f32_16x16x32_bf16 v[100:103], v[224:227], v[188:191], v[100:103]
	v_mfma_f32_16x16x32_bf16 v[92:95], v[216:219], v[196:199], v[92:95]
	v_mfma_f32_16x16x32_bf16 v[84:87], v[224:227], v[196:199], v[84:87]
	v_mfma_f32_16x16x32_bf16 v[76:79], v[216:219], v[208:211], v[76:79]
	v_mfma_f32_16x16x32_bf16 v[68:71], v[224:227], v[208:211], v[68:71]
	v_mfma_f32_16x16x32_bf16 v[124:127], v[220:223], v[184:187], v[124:127]
	v_mfma_f32_16x16x32_bf16 v[116:119], v[228:231], v[184:187], v[116:119]
	v_mfma_f32_16x16x32_bf16 v[108:111], v[220:223], v[192:195], v[108:111]
	v_mfma_f32_16x16x32_bf16 v[100:103], v[228:231], v[192:195], v[100:103]
	v_mfma_f32_16x16x32_bf16 v[92:95], v[220:223], v[200:203], v[92:95]
	v_mfma_f32_16x16x32_bf16 v[84:87], v[228:231], v[200:203], v[84:87]
	s_setprio 2
	s_barrier
	v_mfma_f32_16x16x32_bf16 v[76:79], v[220:223], v[212:215], v[76:79]
	v_mfma_f32_16x16x32_bf16 v[68:71], v[228:231], v[212:215], v[68:71]
	s_setprio 0
	s_mov_b32 m0, s27
	s_add_u32 s100, s40, 0x80
	s_addc_u32 s101, s41, 0
	ds_read_b128 v[180:183], v145 offset:16384
	ds_read_b128 v[184:187], v145 offset:17408
	ds_read_b128 v[188:191], v145 offset:18432
	ds_read_b128 v[192:195], v145 offset:19456
	ds_read_b128 v[196:199], v145 offset:20480
	ds_read_b128 v[200:203], v145 offset:21504
	ds_read_b128 v[208:211], v145 offset:22528
	ds_read_b128 v[212:215], v145 offset:23552
	global_load_lds_dwordx4 v136, s[40:41]
	s_mov_b32 m0, s48
	s_nop 0
	global_load_lds_dwordx4 v134, s[40:41]
	s_waitcnt vmcnt(10)
	s_barrier
	s_waitcnt lgkmcnt(0)
	s_setprio 1
	s_waitcnt lgkmcnt(0)
	v_mfma_f32_16x16x32_bf16 v[64:67], v[146:149], v[180:183], v[64:67]
	v_mfma_f32_16x16x32_bf16 v[56:59], v[154:157], v[180:183], v[56:59]
	v_mfma_f32_16x16x32_bf16 v[48:51], v[146:149], v[188:191], v[48:51]
	v_mfma_f32_16x16x32_bf16 v[40:43], v[154:157], v[188:191], v[40:43]
	v_mfma_f32_16x16x32_bf16 v[32:35], v[146:149], v[196:199], v[32:35]
	v_mfma_f32_16x16x32_bf16 v[24:27], v[154:157], v[196:199], v[24:27]
	v_mfma_f32_16x16x32_bf16 v[16:19], v[146:149], v[208:211], v[16:19]
	v_mfma_f32_16x16x32_bf16 v[8:11], v[154:157], v[208:211], v[8:11]
	v_mfma_f32_16x16x32_bf16 v[64:67], v[150:153], v[184:187], v[64:67]
	v_mfma_f32_16x16x32_bf16 v[56:59], v[158:161], v[184:187], v[56:59]
	v_mfma_f32_16x16x32_bf16 v[48:51], v[150:153], v[192:195], v[48:51]
	v_mfma_f32_16x16x32_bf16 v[40:43], v[158:161], v[192:195], v[40:43]
	v_mfma_f32_16x16x32_bf16 v[32:35], v[150:153], v[200:203], v[32:35]
	v_mfma_f32_16x16x32_bf16 v[24:27], v[158:161], v[200:203], v[24:27]
	s_setprio 2
	s_barrier
	v_mfma_f32_16x16x32_bf16 v[16:19], v[150:153], v[212:215], v[16:19]
	v_mfma_f32_16x16x32_bf16 v[8:11], v[158:161], v[212:215], v[8:11]
	s_setprio 0
	ds_read_b128 v[146:149], v248 offset:32768
	ds_read_b128 v[150:153], v248 offset:33792
	ds_read_b128 v[154:157], v248 offset:34816
	ds_read_b128 v[158:161], v248 offset:35840
	s_add_u32 s60, s36, 0x80000
	s_addc_u32 s61, s37, 0
	s_add_i32 s62, s62, s47
	s_mov_b32 m0, s62
	s_nop 0
	global_load_lds_dwordx4 v2, s[60:61]
	s_add_i32 m0, s62, 0x2000
	s_nop 0
	global_load_lds_dwordx4 v132, s[60:61]
	s_waitcnt vmcnt(6)
	s_barrier
	s_setprio 1
	v_mfma_f32_16x16x32_bf16 v[60:63], v[216:219], v[180:183], v[60:63]
	v_mfma_f32_16x16x32_bf16 v[52:55], v[224:227], v[180:183], v[52:55]
	v_mfma_f32_16x16x32_bf16 v[44:47], v[216:219], v[188:191], v[44:47]
	v_mfma_f32_16x16x32_bf16 v[36:39], v[224:227], v[188:191], v[36:39]
	v_mfma_f32_16x16x32_bf16 v[28:31], v[216:219], v[196:199], v[28:31]
	v_mfma_f32_16x16x32_bf16 v[20:23], v[224:227], v[196:199], v[20:23]
	v_mfma_f32_16x16x32_bf16 v[12:15], v[216:219], v[208:211], v[12:15]
	v_mfma_f32_16x16x32_bf16 v[4:7], v[224:227], v[208:211], v[4:7]
	v_mfma_f32_16x16x32_bf16 v[60:63], v[220:223], v[184:187], v[60:63]
	v_mfma_f32_16x16x32_bf16 v[52:55], v[228:231], v[184:187], v[52:55]
	v_mfma_f32_16x16x32_bf16 v[44:47], v[220:223], v[192:195], v[44:47]
	v_mfma_f32_16x16x32_bf16 v[36:39], v[228:231], v[192:195], v[36:39]
	v_mfma_f32_16x16x32_bf16 v[28:31], v[220:223], v[200:203], v[28:31]
	v_mfma_f32_16x16x32_bf16 v[20:23], v[228:231], v[200:203], v[20:23]
	s_setprio 2
	s_barrier
	v_mfma_f32_16x16x32_bf16 v[12:15], v[220:223], v[212:215], v[12:15]
	v_mfma_f32_16x16x32_bf16 v[4:7], v[228:231], v[212:215], v[4:7]
	s_setprio 0
	s_add_i32 s60, 0, 0x18000
	s_add_u32 s40, s40, 0x80000
	s_addc_u32 s41, s41, 0
	s_mov_b32 m0, s49
	ds_read_b128 v[180:183], v145 offset:32768
	ds_read_b128 v[184:187], v145 offset:33792
	ds_read_b128 v[188:191], v145 offset:34816
	ds_read_b128 v[192:195], v145 offset:35840
	ds_read_b128 v[196:199], v145 offset:36864
	ds_read_b128 v[200:203], v145 offset:37888
	ds_read_b128 v[208:211], v145 offset:38912
	ds_read_b128 v[212:215], v145 offset:39936
	global_load_lds_dwordx4 v136, s[40:41]
	s_mov_b32 m0, s50
	s_nop 0
	global_load_lds_dwordx4 v134, s[40:41]
	s_waitcnt lgkmcnt(8)
	s_barrier
; #define PG8_STAGE(bufoff, gbase, voff) do { _Pragma("unroll") for (int _i = 0; _i < 2; ++_i) \
;     __builtin_amdgcn_global_load_lds((const unsigned*)((const char*)(gbase) + (voff)[_i]), (LAS unsigned*)(lds + (bufoff) + ldsw + _i * 8192), 16, 0, 0); } while (0)
; #define PG8_LDA(dst, b, h) do { _Pragma("unroll") for (int m = 0; m < 4; ++m) _Pragma("unroll") for (int k = 0; k < 2; ++k) dst[m][k] = *(const LAS bf16x8*)(lds + PG8_SA(b, h) + aoff + m * 2048 + k * 1024); } while (0)
; #define PG8_MMA(ai, bj, At, Bt) do { __builtin_amdgcn_s_setprio(1); _Pragma("unroll") for (int m = 0; m < 4; ++m) _Pragma("unroll") for (int n = 0; n < 2; ++n) _Pragma("unroll") for (int k = 0; k < 2; ++k) \
;     acc[ai][bj][m][n] = __builtin_amdgcn_mfma_f32_16x16x32_bf16(Bt[n][k], At[m][k], acc[ai][bj][m][n], 0, 0, 0); __builtin_amdgcn_s_setprio(0); } while (0)
; #define PG8_WAIT_V(n) asm volatile("s_waitcnt vmcnt(" #n ")" ::: "memory")
; #define PG8_WAIT_L(n) asm volatile("s_waitcnt lgkmcnt(" #n ")" ::: "memory")
; #define PG8_BAR __builtin_amdgcn_s_barrier()
; #define PG8_SCHED __builtin_amdgcn_sched_barrier(0)
; template <class Epi>
; DI void gemm_phase(LAS unsigned char* lds, const Gemm g, const Epi& E) {
;     ...
;       PG8_LDA(At, 1, 1); PG8_STAGE(PG8_SA(1, 0), a3, voffA);
;       PG8_BAR; PG8_WAIT_L(0); PG8_MMA(1, 0, At, B0); PG8_BAR; PG8_SCHED;
;       PG8_STAGE(PG8_SB(1, 1), b3 + hstepB, voffB);
;       PG8_WAIT_V(6); PG8_BAR; PG8_MMA(1, 1, At, B1); PG8_BAR;
	s_waitcnt lgkmcnt(0)
	s_setprio 1
	s_waitcnt lgkmcnt(0)
	v_mfma_f32_16x16x32_bf16 v[128:131], v[146:149], v[180:183], v[128:131]
	v_mfma_f32_16x16x32_bf16 v[120:123], v[154:157], v[180:183], v[120:123]
	v_mfma_f32_16x16x32_bf16 v[112:115], v[146:149], v[188:191], v[112:115]
	v_mfma_f32_16x16x32_bf16 v[104:107], v[154:157], v[188:191], v[104:107]
	v_mfma_f32_16x16x32_bf16 v[96:99], v[146:149], v[196:199], v[96:99]
	v_mfma_f32_16x16x32_bf16 v[88:91], v[154:157], v[196:199], v[88:91]
	v_mfma_f32_16x16x32_bf16 v[80:83], v[146:149], v[208:211], v[80:83]
	v_mfma_f32_16x16x32_bf16 v[72:75], v[154:157], v[208:211], v[72:75]
	v_mfma_f32_16x16x32_bf16 v[128:131], v[150:153], v[184:187], v[128:131]
	v_mfma_f32_16x16x32_bf16 v[120:123], v[158:161], v[184:187], v[120:123]
	v_mfma_f32_16x16x32_bf16 v[112:115], v[150:153], v[192:195], v[112:115]
	v_mfma_f32_16x16x32_bf16 v[104:107], v[158:161], v[192:195], v[104:107]
	v_mfma_f32_16x16x32_bf16 v[96:99], v[150:153], v[200:203], v[96:99]
	v_mfma_f32_16x16x32_bf16 v[88:91], v[158:161], v[200:203], v[88:91]
	s_setprio 2
	s_barrier
	v_mfma_f32_16x16x32_bf16 v[80:83], v[150:153], v[212:215], v[80:83]
	v_mfma_f32_16x16x32_bf16 v[72:75], v[158:161], v[212:215], v[72:75]
	s_setprio 0
	s_add_i32 s40, 0, 0x1c000
	s_add_i32 s41, s60, s47
	s_mov_b32 m0, s41
	ds_read_b128 v[216:219], v248 offset:49152
	ds_read_b128 v[220:223], v248 offset:50176
	ds_read_b128 v[224:227], v248 offset:51200
	ds_read_b128 v[228:231], v248 offset:52224
	global_load_lds_dwordx4 v2, s[98:99]
	s_add_i32 m0, s41, 0x2000
	s_nop 0
	global_load_lds_dwordx4 v132, s[98:99]
	s_barrier
	s_waitcnt lgkmcnt(0)
	s_setprio 1
	s_waitcnt lgkmcnt(0)
	v_mfma_f32_16x16x32_bf16 v[124:127], v[216:219], v[180:183], v[124:127]
	v_mfma_f32_16x16x32_bf16 v[116:119], v[224:227], v[180:183], v[116:119]
	v_mfma_f32_16x16x32_bf16 v[108:111], v[216:219], v[188:191], v[108:111]
	v_mfma_f32_16x16x32_bf16 v[100:103], v[224:227], v[188:191], v[100:103]
	v_mfma_f32_16x16x32_bf16 v[92:95], v[216:219], v[196:199], v[92:95]
	v_mfma_f32_16x16x32_bf16 v[84:87], v[224:227], v[196:199], v[84:87]
	v_mfma_f32_16x16x32_bf16 v[76:79], v[216:219], v[208:211], v[76:79]
	v_mfma_f32_16x16x32_bf16 v[68:71], v[224:227], v[208:211], v[68:71]
	v_mfma_f32_16x16x32_bf16 v[124:127], v[220:223], v[184:187], v[124:127]
	v_mfma_f32_16x16x32_bf16 v[116:119], v[228:231], v[184:187], v[116:119]
	v_mfma_f32_16x16x32_bf16 v[108:111], v[220:223], v[192:195], v[108:111]
	v_mfma_f32_16x16x32_bf16 v[100:103], v[228:231], v[192:195], v[100:103]
	v_mfma_f32_16x16x32_bf16 v[92:95], v[220:223], v[200:203], v[92:95]
	v_mfma_f32_16x16x32_bf16 v[84:87], v[228:231], v[200:203], v[84:87]
	s_setprio 2
	s_barrier
	v_mfma_f32_16x16x32_bf16 v[76:79], v[220:223], v[212:215], v[76:79]
	v_mfma_f32_16x16x32_bf16 v[68:71], v[228:231], v[212:215], v[68:71]
	s_setprio 0
	s_mov_b32 m0, s51
	ds_read_b128 v[180:183], v145 offset:49152
	ds_read_b128 v[184:187], v145 offset:50176
	ds_read_b128 v[188:191], v145 offset:51200
	ds_read_b128 v[192:195], v145 offset:52224
	ds_read_b128 v[196:199], v145 offset:53248
	ds_read_b128 v[200:203], v145 offset:54272
	ds_read_b128 v[208:211], v145 offset:55296
	ds_read_b128 v[212:215], v145 offset:56320
	global_load_lds_dwordx4 v136, s[100:101]
	s_mov_b32 m0, s52
	s_nop 0
	global_load_lds_dwordx4 v134, s[100:101]
	s_waitcnt vmcnt(10)
	s_barrier
	s_waitcnt lgkmcnt(0)
	s_setprio 1
	s_waitcnt lgkmcnt(0)
	v_mfma_f32_16x16x32_bf16 v[64:67], v[146:149], v[180:183], v[64:67]
	v_mfma_f32_16x16x32_bf16 v[56:59], v[154:157], v[180:183], v[56:59]
	v_mfma_f32_16x16x32_bf16 v[48:51], v[146:149], v[188:191], v[48:51]
	v_mfma_f32_16x16x32_bf16 v[40:43], v[154:157], v[188:191], v[40:43]
	v_mfma_f32_16x16x32_bf16 v[32:35], v[146:149], v[196:199], v[32:35]
	v_mfma_f32_16x16x32_bf16 v[24:27], v[154:157], v[196:199], v[24:27]
	v_mfma_f32_16x16x32_bf16 v[16:19], v[146:149], v[208:211], v[16:19]
	v_mfma_f32_16x16x32_bf16 v[8:11], v[154:157], v[208:211], v[8:11]
	v_mfma_f32_16x16x32_bf16 v[64:67], v[150:153], v[184:187], v[64:67]
	v_mfma_f32_16x16x32_bf16 v[56:59], v[158:161], v[184:187], v[56:59]
	v_mfma_f32_16x16x32_bf16 v[48:51], v[150:153], v[192:195], v[48:51]
	v_mfma_f32_16x16x32_bf16 v[40:43], v[158:161], v[192:195], v[40:43]
	v_mfma_f32_16x16x32_bf16 v[32:35], v[150:153], v[200:203], v[32:35]
	v_mfma_f32_16x16x32_bf16 v[24:27], v[158:161], v[200:203], v[24:27]
	s_setprio 2
	s_barrier
	v_mfma_f32_16x16x32_bf16 v[16:19], v[150:153], v[212:215], v[16:19]
	v_mfma_f32_16x16x32_bf16 v[8:11], v[158:161], v[212:215], v[8:11]
	s_setprio 0
	ds_read_b128 v[146:149], v248
	ds_read_b128 v[150:153], v248 offset:1024
	ds_read_b128 v[154:157], v248 offset:2048
	ds_read_b128 v[158:161], v248 offset:3072
	s_add_u32 s36, s36, 0x80080
	s_addc_u32 s37, s37, 0
	s_add_i32 s40, s40, s47
	s_mov_b32 m0, s40
	s_nop 0
	global_load_lds_dwordx4 v2, s[36:37]
	s_add_i32 m0, s40, 0x2000
	s_nop 0
	global_load_lds_dwordx4 v132, s[36:37]
	s_waitcnt vmcnt(6)
	s_barrier
	s_setprio 1
	v_mfma_f32_16x16x32_bf16 v[60:63], v[216:219], v[180:183], v[60:63]
	v_mfma_f32_16x16x32_bf16 v[52:55], v[224:227], v[180:183], v[52:55]
	v_mfma_f32_16x16x32_bf16 v[44:47], v[216:219], v[188:191], v[44:47]
	v_mfma_f32_16x16x32_bf16 v[36:39], v[224:227], v[188:191], v[36:39]
	v_mfma_f32_16x16x32_bf16 v[28:31], v[216:219], v[196:199], v[28:31]
	v_mfma_f32_16x16x32_bf16 v[20:23], v[224:227], v[196:199], v[20:23]
	v_mfma_f32_16x16x32_bf16 v[12:15], v[216:219], v[208:211], v[12:15]
	v_mfma_f32_16x16x32_bf16 v[4:7], v[224:227], v[208:211], v[4:7]
	v_mfma_f32_16x16x32_bf16 v[60:63], v[220:223], v[184:187], v[60:63]
	v_mfma_f32_16x16x32_bf16 v[52:55], v[228:231], v[184:187], v[52:55]
	v_mfma_f32_16x16x32_bf16 v[44:47], v[220:223], v[192:195], v[44:47]
	v_mfma_f32_16x16x32_bf16 v[36:39], v[228:231], v[192:195], v[36:39]
	v_mfma_f32_16x16x32_bf16 v[28:31], v[220:223], v[200:203], v[28:31]
	v_mfma_f32_16x16x32_bf16 v[20:23], v[228:231], v[200:203], v[20:23]
	s_setprio 2
	s_barrier
	v_mfma_f32_16x16x32_bf16 v[12:15], v[220:223], v[212:215], v[12:15]
	v_mfma_f32_16x16x32_bf16 v[4:7], v[228:231], v[212:215], v[4:7]
	s_setprio 0
	s_add_i32 s59, s59, 2
	s_add_u32 s30, s30, 0x100
	s_addc_u32 s31, s31, 0
	s_add_u32 s57, s57, 0x100
	s_addc_u32 s58, s58, 0
	s_cmp_gt_u32 s59, 29
	s_cbranch_scc0 .LBB0_190

; #define PG8_STAGE(bufoff, gbase, voff) do { _Pragma("unroll") for (int _i = 0; _i < 2; ++_i) \
;     __builtin_amdgcn_global_load_lds((const unsigned*)((const char*)(gbase) + (voff)[_i]), (LAS unsigned*)(lds + (bufoff) + ldsw + _i * 8192), 16, 0, 0); } while (0)
; #define PG8_LDA(dst, b, h) do { _Pragma("unroll") for (int m = 0; m < 4; ++m) _Pragma("unroll") for (int k = 0; k < 2; ++k) dst[m][k] = *(const LAS bf16x8*)(lds + PG8_SA(b, h) + aoff + m * 2048 + k * 1024); } while (0)
; #define PG8_LDB(dst, b, h) do { _Pragma("unroll") for (int n = 0; n < 2; ++n) _Pragma("unroll") for (int k = 0; k < 2; ++k) dst[n][k] = *(const LAS bf16x8*)(lds + PG8_SB(b, h) + boff + n * 2048 + k * 1024); } while (0)
; #define PG8_MMA(ai, bj, At, Bt) do { __builtin_amdgcn_s_setprio(1); _Pragma("unroll") for (int m = 0; m < 4; ++m) _Pragma("unroll") for (int n = 0; n < 2; ++n) _Pragma("unroll") for (int k = 0; k < 2; ++k) \
;     acc[ai][bj][m][n] = __builtin_amdgcn_mfma_f32_16x16x32_bf16(Bt[n][k], At[m][k], acc[ai][bj][m][n], 0, 0, 0); __builtin_amdgcn_s_setprio(0); } while (0)
; #define PG8_WAIT_V(n) asm volatile("s_waitcnt vmcnt(" #n ")" ::: "memory")
; #define PG8_BAR __builtin_amdgcn_s_barrier()
; template <class Epi>
; DI void gemm_phase(LAS unsigned char* lds, const Gemm g, const Epi& E) {
;     ...
;     const bool has_next = S.next(ui + 1, nxt);
;     const char* nA = has_next ? PG8_APTR(nxt) : cA; const char* nB = has_next ? (const char*)g.Bt + (size_t)nxt.pn * tstepB : cB;
;     for (int t = 0; t < nt; t += 2) {
;       const bool last = (t == nt - 2);
;       const char* a1 = cA + (size_t)(t + 1) * kstep;
;       const char* a2 = last ? nA : cA + (size_t)(t + 2) * kstep; const char* b2 = last ? nB : cB + (size_t)(t + 2) * kstep;
;       const char* a3 = a2 + kstep; const char* b3 = b2 + kstep;
;       PG8_LDB(B0, 0, 0); PG8_SCHED; PG8_LDA(At, 0, 0); PG8_STAGE(PG8_SA(1, 1), a1 + hstepA, voffA);
;       PG8_WAIT_L(8); PG8_BAR; PG8_WAIT_L(0); PG8_MMA(0, 0, At, B0); PG8_BAR; PG8_SCHED;
;       PG8_LDB(B1, 0, 1); PG8_STAGE(PG8_SB(0, 0), b2, voffB);
;       PG8_BAR; PG8_WAIT_L(0); PG8_MMA(0, 1, At, B1); PG8_BAR;
;       PG8_LDA(At, 0, 1); PG8_STAGE(PG8_SA(0, 0), a2, voffA);
;       PG8_BAR; PG8_WAIT_L(0); PG8_MMA(1, 0, At, B0); PG8_BAR; PG8_SCHED;
;       PG8_STAGE(PG8_SB(0, 1), b2 + hstepB, voffB);
;       PG8_WAIT_V(6); PG8_BAR; PG8_MMA(1, 1, At, B1); PG8_BAR;
.LBB0_224:
	s_ashr_i32 s27, s26, 31
	v_cmp_lt_i64_e32 vcc, s[30:31], v[174:175]
	s_lshl_b64 s[30:31], s[26:27], 20
	s_add_u32 s30, s49, s30
	s_addc_u32 s31, s50, s31
	s_and_b64 s[36:37], vcc, exec
	s_cselect_b32 s27, s31, s43
	s_cselect_b32 s41, s30, s42
	s_ashr_i32 s23, s22, 31
	s_lshl_b64 s[36:37], s[22:23], 20
	s_add_u32 s36, s51, s36
	s_addc_u32 s37, s52, s37
	s_and_b64 s[46:47], vcc, exec
	s_cselect_b32 s23, s37, s45
	s_cselect_b32 s63, s36, s44
	s_add_u32 s42, s42, 0x80080
	s_addc_u32 s43, s43, 0
	s_add_u32 s64, s44, 0x100
	s_addc_u32 s65, s45, 0
	s_mov_b32 s66, -2
	v_add_u32_e32 v248, 0x10000, v151
	ds_read_b128 v[156:159], v248
	ds_read_b128 v[160:163], v248 offset:1024
	ds_read_b128 v[180:183], v248 offset:2048
	ds_read_b128 v[184:187], v248 offset:3072
	s_add_i32 m0, s55, 0xc000
	ds_read_b128 v[188:191], v154
	ds_read_b128 v[192:195], v154 offset:1024
	ds_read_b128 v[196:199], v154 offset:2048
	ds_read_b128 v[200:203], v154 offset:3072
	ds_read_b128 v[208:211], v154 offset:4096
	ds_read_b128 v[212:215], v154 offset:5120
	ds_read_b128 v[216:219], v154 offset:6144
	ds_read_b128 v[220:223], v154 offset:7168
	global_load_lds_dwordx4 v144, s[42:43]
	s_add_i32 m0, s55, 0xe000
	s_nop 0
	global_load_lds_dwordx4 v146, s[42:43]
	s_waitcnt lgkmcnt(8)
	s_barrier
	s_waitcnt lgkmcnt(0)
	s_setprio 1
	s_waitcnt lgkmcnt(0)
	v_mfma_f32_16x16x32_bf16 v[128:131], v[156:159], v[188:191], 0
	s_add_u32 s44, s42, 0xfff80080
	s_addc_u32 s45, s43, -1
	v_mfma_f32_16x16x32_bf16 v[124:127], v[180:183], v[188:191], 0
	s_add_i32 s67, 0, 0x10000
	v_mfma_f32_16x16x32_bf16 v[120:123], v[156:159], v[196:199], 0
	s_cmp_eq_u32 s66, 28
	s_cselect_b32 s47, s27, s45
	s_cselect_b32 s46, s41, s44
	s_cselect_b32 s45, s23, s65
	s_cselect_b32 s44, s63, s64
	v_mfma_f32_16x16x32_bf16 v[116:119], v[180:183], v[196:199], 0
	v_mfma_f32_16x16x32_bf16 v[104:107], v[156:159], v[208:211], 0
	v_mfma_f32_16x16x32_bf16 v[100:103], v[180:183], v[208:211], 0
	v_mfma_f32_16x16x32_bf16 v[88:91], v[156:159], v[216:219], 0
	v_mfma_f32_16x16x32_bf16 v[84:87], v[180:183], v[216:219], 0
	v_mfma_f32_16x16x32_bf16 v[128:131], v[160:163], v[192:195], v[128:131]
	v_mfma_f32_16x16x32_bf16 v[124:127], v[184:187], v[192:195], v[124:127]
	v_mfma_f32_16x16x32_bf16 v[120:123], v[160:163], v[200:203], v[120:123]
	v_mfma_f32_16x16x32_bf16 v[116:119], v[184:187], v[200:203], v[116:119]
	v_mfma_f32_16x16x32_bf16 v[104:107], v[160:163], v[212:215], v[104:107]
	v_mfma_f32_16x16x32_bf16 v[100:103], v[184:187], v[212:215], v[100:103]
	s_setprio 2
	s_barrier
	v_mfma_f32_16x16x32_bf16 v[88:91], v[160:163], v[220:223], v[88:91]
	v_mfma_f32_16x16x32_bf16 v[84:87], v[184:187], v[220:223], v[84:87]
	s_setprio 0
	s_add_i32 s70, 0, 0x14000
	s_add_i32 s67, s67, s54
	s_add_u32 s98, s44, 0x80
	s_addc_u32 s99, s45, 0
	s_mov_b32 m0, s67
	ds_read_b128 v[224:227], v248 offset:16384
	ds_read_b128 v[228:231], v248 offset:17408
	ds_read_b128 v[232:235], v248 offset:18432
	ds_read_b128 v[236:239], v248 offset:19456
	global_load_lds_dwordx4 v136, s[44:45]
	s_add_i32 m0, s67, 0x2000
	s_nop 0
	global_load_lds_dwordx4 v132, s[44:45]
	s_barrier
	s_waitcnt lgkmcnt(0)
	s_setprio 1
	s_waitcnt lgkmcnt(0)
	v_mfma_f32_16x16x32_bf16 v[112:115], v[224:227], v[188:191], 0
	v_mfma_f32_16x16x32_bf16 v[108:111], v[232:235], v[188:191], 0
	v_mfma_f32_16x16x32_bf16 v[96:99], v[224:227], v[196:199], 0
	v_mfma_f32_16x16x32_bf16 v[92:95], v[232:235], v[196:199], 0
	v_mfma_f32_16x16x32_bf16 v[80:83], v[224:227], v[208:211], 0
	v_mfma_f32_16x16x32_bf16 v[76:79], v[232:235], v[208:211], 0
	v_mfma_f32_16x16x32_bf16 v[72:75], v[224:227], v[216:219], 0
	v_mfma_f32_16x16x32_bf16 v[68:71], v[232:235], v[216:219], 0
	v_mfma_f32_16x16x32_bf16 v[112:115], v[228:231], v[192:195], v[112:115]
	v_mfma_f32_16x16x32_bf16 v[108:111], v[236:239], v[192:195], v[108:111]
	v_mfma_f32_16x16x32_bf16 v[96:99], v[228:231], v[200:203], v[96:99]
	v_mfma_f32_16x16x32_bf16 v[92:95], v[236:239], v[200:203], v[92:95]
	v_mfma_f32_16x16x32_bf16 v[80:83], v[228:231], v[212:215], v[80:83]
	v_mfma_f32_16x16x32_bf16 v[76:79], v[236:239], v[212:215], v[76:79]
	s_setprio 2
	s_barrier
	v_mfma_f32_16x16x32_bf16 v[72:75], v[228:231], v[220:223], v[72:75]
	v_mfma_f32_16x16x32_bf16 v[68:71], v[236:239], v[220:223], v[68:71]
	s_setprio 0
	s_mov_b32 m0, s55
	s_add_u32 s100, s46, 0x80
	s_addc_u32 s101, s47, 0
	ds_read_b128 v[188:191], v154 offset:16384
	ds_read_b128 v[192:195], v154 offset:17408
	ds_read_b128 v[196:199], v154 offset:18432
	ds_read_b128 v[200:203], v154 offset:19456
	ds_read_b128 v[208:211], v154 offset:20480
	ds_read_b128 v[212:215], v154 offset:21504
	ds_read_b128 v[216:219], v154 offset:22528
	ds_read_b128 v[220:223], v154 offset:23552
	global_load_lds_dwordx4 v138, s[46:47]
	s_mov_b32 m0, s56
	s_nop 0
	global_load_lds_dwordx4 v134, s[46:47]
	s_waitcnt vmcnt(10)
	s_barrier
	s_waitcnt lgkmcnt(0)
	s_setprio 1
	s_waitcnt lgkmcnt(0)
	v_mfma_f32_16x16x32_bf16 v[64:67], v[156:159], v[188:191], 0
	v_mfma_f32_16x16x32_bf16 v[60:63], v[180:183], v[188:191], 0
	v_mfma_f32_16x16x32_bf16 v[56:59], v[156:159], v[196:199], 0
	v_mfma_f32_16x16x32_bf16 v[52:55], v[180:183], v[196:199], 0
	v_mfma_f32_16x16x32_bf16 v[40:43], v[156:159], v[208:211], 0
	v_mfma_f32_16x16x32_bf16 v[36:39], v[180:183], v[208:211], 0
	v_mfma_f32_16x16x32_bf16 v[24:27], v[156:159], v[216:219], 0
	v_mfma_f32_16x16x32_bf16 v[20:23], v[180:183], v[216:219], 0
	v_mfma_f32_16x16x32_bf16 v[64:67], v[160:163], v[192:195], v[64:67]
	v_mfma_f32_16x16x32_bf16 v[60:63], v[184:187], v[192:195], v[60:63]
	v_mfma_f32_16x16x32_bf16 v[56:59], v[160:163], v[200:203], v[56:59]
	v_mfma_f32_16x16x32_bf16 v[52:55], v[184:187], v[200:203], v[52:55]
	v_mfma_f32_16x16x32_bf16 v[40:43], v[160:163], v[212:215], v[40:43]
	v_mfma_f32_16x16x32_bf16 v[36:39], v[184:187], v[212:215], v[36:39]
	s_setprio 2
	s_barrier
; #define PG8_STAGE(bufoff, gbase, voff) do { _Pragma("unroll") for (int _i = 0; _i < 2; ++_i) \
;     __builtin_amdgcn_global_load_lds((const unsigned*)((const char*)(gbase) + (voff)[_i]), (LAS unsigned*)(lds + (bufoff) + ldsw + _i * 8192), 16, 0, 0); } while (0)
; #define PG8_LDA(dst, b, h) do { _Pragma("unroll") for (int m = 0; m < 4; ++m) _Pragma("unroll") for (int k = 0; k < 2; ++k) dst[m][k] = *(const LAS bf16x8*)(lds + PG8_SA(b, h) + aoff + m * 2048 + k * 1024); } while (0)
; #define PG8_LDB(dst, b, h) do { _Pragma("unroll") for (int n = 0; n < 2; ++n) _Pragma("unroll") for (int k = 0; k < 2; ++k) dst[n][k] = *(const LAS bf16x8*)(lds + PG8_SB(b, h) + boff + n * 2048 + k * 1024); } while (0)
; #define PG8_MMA(ai, bj, At, Bt) do { __builtin_amdgcn_s_setprio(1); _Pragma("unroll") for (int m = 0; m < 4; ++m) _Pragma("unroll") for (int n = 0; n < 2; ++n) _Pragma("unroll") for (int k = 0; k < 2; ++k) \
;     acc[ai][bj][m][n] = __builtin_amdgcn_mfma_f32_16x16x32_bf16(Bt[n][k], At[m][k], acc[ai][bj][m][n], 0, 0, 0); __builtin_amdgcn_s_setprio(0); } while (0)
; #define PG8_WAIT_V(n) asm volatile("s_waitcnt vmcnt(" #n ")" ::: "memory")
; #define PG8_WAIT_L(n) asm volatile("s_waitcnt lgkmcnt(" #n ")" ::: "memory")
; #define PG8_BAR __builtin_amdgcn_s_barrier()
; #define PG8_SCHED __builtin_amdgcn_sched_barrier(0)
; template <class Epi>
; DI void gemm_phase(LAS unsigned char* lds, const Gemm g, const Epi& E) {
;     ...
;       PG8_WAIT_V(6); PG8_BAR; PG8_MMA(1, 1, At, B1); PG8_BAR;
;       PG8_LDB(B0, 1, 0); PG8_SCHED; PG8_LDA(At, 1, 0); PG8_STAGE(PG8_SA(0, 1), a2 + hstepA, voffA);
;       PG8_WAIT_L(8); PG8_BAR; PG8_WAIT_L(0); PG8_MMA(0, 0, At, B0); PG8_BAR; PG8_SCHED;
;       PG8_LDB(B1, 1, 1); PG8_STAGE(PG8_SB(1, 0), b3, voffB);
;       PG8_BAR; PG8_WAIT_L(0); PG8_MMA(0, 1, At, B1); PG8_BAR;
;       PG8_LDA(At, 1, 1); PG8_STAGE(PG8_SA(1, 0), a3, voffA);
;       PG8_BAR; PG8_WAIT_L(0); PG8_MMA(1, 0, At, B0); PG8_BAR; PG8_SCHED;
	v_mfma_f32_16x16x32_bf16 v[24:27], v[160:163], v[220:223], v[24:27]
	v_mfma_f32_16x16x32_bf16 v[20:23], v[184:187], v[220:223], v[20:23]
	s_setprio 0
	ds_read_b128 v[156:159], v248 offset:32768
	ds_read_b128 v[160:163], v248 offset:33792
	ds_read_b128 v[180:183], v248 offset:34816
	ds_read_b128 v[184:187], v248 offset:35840
	s_add_u32 s68, s44, 0x80000
	s_addc_u32 s69, s45, 0
	s_add_i32 s67, s70, s54
	s_mov_b32 m0, s67
	s_nop 0
	global_load_lds_dwordx4 v136, s[68:69]
	s_add_i32 m0, s67, 0x2000
	s_nop 0
	global_load_lds_dwordx4 v132, s[68:69]
	s_waitcnt vmcnt(6)
	s_barrier
	s_setprio 1
	v_mfma_f32_16x16x32_bf16 v[48:51], v[224:227], v[188:191], 0
	v_mfma_f32_16x16x32_bf16 v[44:47], v[232:235], v[188:191], 0
	v_mfma_f32_16x16x32_bf16 v[32:35], v[224:227], v[196:199], 0
	v_mfma_f32_16x16x32_bf16 v[28:31], v[232:235], v[196:199], 0
	v_mfma_f32_16x16x32_bf16 v[16:19], v[224:227], v[208:211], 0
	v_mfma_f32_16x16x32_bf16 v[12:15], v[232:235], v[208:211], 0
	v_mfma_f32_16x16x32_bf16 v[8:11], v[224:227], v[216:219], 0
	v_mfma_f32_16x16x32_bf16 v[4:7], v[232:235], v[216:219], 0
	v_mfma_f32_16x16x32_bf16 v[48:51], v[228:231], v[192:195], v[48:51]
	v_mfma_f32_16x16x32_bf16 v[44:47], v[236:239], v[192:195], v[44:47]
	v_mfma_f32_16x16x32_bf16 v[32:35], v[228:231], v[200:203], v[32:35]
	v_mfma_f32_16x16x32_bf16 v[28:31], v[236:239], v[200:203], v[28:31]
	v_mfma_f32_16x16x32_bf16 v[16:19], v[228:231], v[212:215], v[16:19]
	v_mfma_f32_16x16x32_bf16 v[12:15], v[236:239], v[212:215], v[12:15]
	s_setprio 2
	s_barrier
	v_mfma_f32_16x16x32_bf16 v[8:11], v[228:231], v[220:223], v[8:11]
	v_mfma_f32_16x16x32_bf16 v[4:7], v[236:239], v[220:223], v[4:7]
	s_setprio 0
	s_add_i32 s67, 0, 0x18000
	s_add_u32 s46, s46, 0x80000
	s_addc_u32 s47, s47, 0
	s_mov_b32 m0, s57
	ds_read_b128 v[188:191], v154 offset:32768
	ds_read_b128 v[192:195], v154 offset:33792
	ds_read_b128 v[196:199], v154 offset:34816
	ds_read_b128 v[200:203], v154 offset:35840
	ds_read_b128 v[208:211], v154 offset:36864
	ds_read_b128 v[212:215], v154 offset:37888
	ds_read_b128 v[216:219], v154 offset:38912
	ds_read_b128 v[220:223], v154 offset:39936
	global_load_lds_dwordx4 v138, s[46:47]
	s_mov_b32 m0, s58
	s_nop 0
	global_load_lds_dwordx4 v134, s[46:47]
	s_waitcnt lgkmcnt(8)
	s_barrier
	s_waitcnt lgkmcnt(0)
	s_setprio 1
	s_waitcnt lgkmcnt(0)
	v_mfma_f32_16x16x32_bf16 v[128:131], v[156:159], v[188:191], v[128:131]
	v_mfma_f32_16x16x32_bf16 v[124:127], v[180:183], v[188:191], v[124:127]
	v_mfma_f32_16x16x32_bf16 v[120:123], v[156:159], v[196:199], v[120:123]
	v_mfma_f32_16x16x32_bf16 v[116:119], v[180:183], v[196:199], v[116:119]
	v_mfma_f32_16x16x32_bf16 v[104:107], v[156:159], v[208:211], v[104:107]
	v_mfma_f32_16x16x32_bf16 v[100:103], v[180:183], v[208:211], v[100:103]
	v_mfma_f32_16x16x32_bf16 v[88:91], v[156:159], v[216:219], v[88:91]
	v_mfma_f32_16x16x32_bf16 v[84:87], v[180:183], v[216:219], v[84:87]
	v_mfma_f32_16x16x32_bf16 v[128:131], v[160:163], v[192:195], v[128:131]
	v_mfma_f32_16x16x32_bf16 v[124:127], v[184:187], v[192:195], v[124:127]
	v_mfma_f32_16x16x32_bf16 v[120:123], v[160:163], v[200:203], v[120:123]
	v_mfma_f32_16x16x32_bf16 v[116:119], v[184:187], v[200:203], v[116:119]
	v_mfma_f32_16x16x32_bf16 v[104:107], v[160:163], v[212:215], v[104:107]
	v_mfma_f32_16x16x32_bf16 v[100:103], v[184:187], v[212:215], v[100:103]
	s_setprio 2
	s_barrier
	v_mfma_f32_16x16x32_bf16 v[88:91], v[160:163], v[220:223], v[88:91]
	v_mfma_f32_16x16x32_bf16 v[84:87], v[184:187], v[220:223], v[84:87]
	s_setprio 0
	s_add_i32 s46, 0, 0x1c000
	s_add_i32 s47, s67, s54
	s_mov_b32 m0, s47
	ds_read_b128 v[224:227], v248 offset:49152
	ds_read_b128 v[228:231], v248 offset:50176
	ds_read_b128 v[232:235], v248 offset:51200
	ds_read_b128 v[236:239], v248 offset:52224
	global_load_lds_dwordx4 v136, s[98:99]
	s_add_i32 m0, s47, 0x2000
	s_nop 0
	global_load_lds_dwordx4 v132, s[98:99]
	s_barrier
	s_waitcnt lgkmcnt(0)
	s_setprio 1
	s_waitcnt lgkmcnt(0)
	v_mfma_f32_16x16x32_bf16 v[112:115], v[224:227], v[188:191], v[112:115]
	v_mfma_f32_16x16x32_bf16 v[108:111], v[232:235], v[188:191], v[108:111]
	v_mfma_f32_16x16x32_bf16 v[96:99], v[224:227], v[196:199], v[96:99]
	v_mfma_f32_16x16x32_bf16 v[92:95], v[232:235], v[196:199], v[92:95]
	v_mfma_f32_16x16x32_bf16 v[80:83], v[224:227], v[208:211], v[80:83]
	v_mfma_f32_16x16x32_bf16 v[76:79], v[232:235], v[208:211], v[76:79]
	v_mfma_f32_16x16x32_bf16 v[72:75], v[224:227], v[216:219], v[72:75]
	v_mfma_f32_16x16x32_bf16 v[68:71], v[232:235], v[216:219], v[68:71]
	v_mfma_f32_16x16x32_bf16 v[112:115], v[228:231], v[192:195], v[112:115]
	v_mfma_f32_16x16x32_bf16 v[108:111], v[236:239], v[192:195], v[108:111]
	v_mfma_f32_16x16x32_bf16 v[96:99], v[228:231], v[200:203], v[96:99]
	v_mfma_f32_16x16x32_bf16 v[92:95], v[236:239], v[200:203], v[92:95]
	v_mfma_f32_16x16x32_bf16 v[80:83], v[228:231], v[212:215], v[80:83]
	v_mfma_f32_16x16x32_bf16 v[76:79], v[236:239], v[212:215], v[76:79]
	s_setprio 2
	s_barrier
	v_mfma_f32_16x16x32_bf16 v[72:75], v[228:231], v[220:223], v[72:75]
	v_mfma_f32_16x16x32_bf16 v[68:71], v[236:239], v[220:223], v[68:71]
	s_setprio 0
	s_mov_b32 m0, s60
	ds_read_b128 v[188:191], v154 offset:49152
	ds_read_b128 v[192:195], v154 offset:50176
	ds_read_b128 v[196:199], v154 offset:51200
	ds_read_b128 v[200:203], v154 offset:52224
	ds_read_b128 v[208:211], v154 offset:53248
	ds_read_b128 v[212:215], v154 offset:54272
	ds_read_b128 v[216:219], v154 offset:55296
	ds_read_b128 v[220:223], v154 offset:56320
	global_load_lds_dwordx4 v138, s[100:101]
	s_mov_b32 m0, s61
	s_nop 0
	global_load_lds_dwordx4 v134, s[100:101]
	s_waitcnt vmcnt(10)
	s_barrier
; #define PG8_STAGE(bufoff, gbase, voff) do { _Pragma("unroll") for (int _i = 0; _i < 2; ++_i) \
;     __builtin_amdgcn_global_load_lds((const unsigned*)((const char*)(gbase) + (voff)[_i]), (LAS unsigned*)(lds + (bufoff) + ldsw + _i * 8192), 16, 0, 0); } while (0)
; #define PG8_LDA(dst, b, h) do { _Pragma("unroll") for (int m = 0; m < 4; ++m) _Pragma("unroll") for (int k = 0; k < 2; ++k) dst[m][k] = *(const LAS bf16x8*)(lds + PG8_SA(b, h) + aoff + m * 2048 + k * 1024); } while (0)
; #define PG8_LDB(dst, b, h) do { _Pragma("unroll") for (int n = 0; n < 2; ++n) _Pragma("unroll") for (int k = 0; k < 2; ++k) dst[n][k] = *(const LAS bf16x8*)(lds + PG8_SB(b, h) + boff + n * 2048 + k * 1024); } while (0)
; #define PG8_MMA(ai, bj, At, Bt) do { __builtin_amdgcn_s_setprio(1); _Pragma("unroll") for (int m = 0; m < 4; ++m) _Pragma("unroll") for (int n = 0; n < 2; ++n) _Pragma("unroll") for (int k = 0; k < 2; ++k) \
;     acc[ai][bj][m][n] = __builtin_amdgcn_mfma_f32_16x16x32_bf16(Bt[n][k], At[m][k], acc[ai][bj][m][n], 0, 0, 0); __builtin_amdgcn_s_setprio(0); } while (0)
; #define PG8_WAIT_V(n) asm volatile("s_waitcnt vmcnt(" #n ")" ::: "memory")
; #define PG8_WAIT_L(n) asm volatile("s_waitcnt lgkmcnt(" #n ")" ::: "memory")
; #define PG8_BAR __builtin_amdgcn_s_barrier()
; #define PG8_SCHED __builtin_amdgcn_sched_barrier(0)
; template <class Epi>
; DI void gemm_phase(LAS unsigned char* lds, const Gemm g, const Epi& E) {
;     ...
;       PG8_LDB(B0, 0, 0); PG8_SCHED; PG8_LDA(At, 0, 0); PG8_STAGE(PG8_SA(1, 1), a1 + hstepA, voffA);
;       PG8_WAIT_L(8); PG8_BAR; PG8_WAIT_L(0); PG8_MMA(0, 0, At, B0); PG8_BAR; PG8_SCHED;
;       PG8_LDB(B1, 0, 1); PG8_STAGE(PG8_SB(0, 0), b2, voffB);
;       PG8_BAR; PG8_WAIT_L(0); PG8_MMA(0, 1, At, B1); PG8_BAR;
;     ...
;       PG8_BAR; PG8_WAIT_L(0); PG8_MMA(1, 0, At, B0); PG8_BAR; PG8_SCHED;
;       PG8_STAGE(PG8_SB(1, 1), b3 + hstepB, voffB);
;       PG8_WAIT_V(6); PG8_BAR; PG8_MMA(1, 1, At, B1); PG8_BAR;
	s_waitcnt lgkmcnt(0)
	s_setprio 1
	s_waitcnt lgkmcnt(0)
	v_mfma_f32_16x16x32_bf16 v[64:67], v[156:159], v[188:191], v[64:67]
	v_mfma_f32_16x16x32_bf16 v[60:63], v[180:183], v[188:191], v[60:63]
	v_mfma_f32_16x16x32_bf16 v[56:59], v[156:159], v[196:199], v[56:59]
	v_mfma_f32_16x16x32_bf16 v[52:55], v[180:183], v[196:199], v[52:55]
	v_mfma_f32_16x16x32_bf16 v[40:43], v[156:159], v[208:211], v[40:43]
	v_mfma_f32_16x16x32_bf16 v[36:39], v[180:183], v[208:211], v[36:39]
	v_mfma_f32_16x16x32_bf16 v[24:27], v[156:159], v[216:219], v[24:27]
	v_mfma_f32_16x16x32_bf16 v[20:23], v[180:183], v[216:219], v[20:23]
	v_mfma_f32_16x16x32_bf16 v[64:67], v[160:163], v[192:195], v[64:67]
	v_mfma_f32_16x16x32_bf16 v[60:63], v[184:187], v[192:195], v[60:63]
	v_mfma_f32_16x16x32_bf16 v[56:59], v[160:163], v[200:203], v[56:59]
	v_mfma_f32_16x16x32_bf16 v[52:55], v[184:187], v[200:203], v[52:55]
	v_mfma_f32_16x16x32_bf16 v[40:43], v[160:163], v[212:215], v[40:43]
	v_mfma_f32_16x16x32_bf16 v[36:39], v[184:187], v[212:215], v[36:39]
	s_setprio 2
	s_barrier
	v_mfma_f32_16x16x32_bf16 v[24:27], v[160:163], v[220:223], v[24:27]
	v_mfma_f32_16x16x32_bf16 v[20:23], v[184:187], v[220:223], v[20:23]
	s_setprio 0
	ds_read_b128 v[156:159], v248
	ds_read_b128 v[160:163], v248 offset:1024
	ds_read_b128 v[180:183], v248 offset:2048
	ds_read_b128 v[184:187], v248 offset:3072
	s_add_u32 s44, s44, 0x80080
	s_addc_u32 s45, s45, 0
	s_add_i32 s46, s46, s54
	s_mov_b32 m0, s46
	s_nop 0
	global_load_lds_dwordx4 v136, s[44:45]
	s_add_i32 m0, s46, 0x2000
	s_nop 0
	global_load_lds_dwordx4 v132, s[44:45]
	s_waitcnt vmcnt(6)
	s_barrier
	s_setprio 1
	v_mfma_f32_16x16x32_bf16 v[48:51], v[224:227], v[188:191], v[48:51]
	v_mfma_f32_16x16x32_bf16 v[44:47], v[232:235], v[188:191], v[44:47]
	v_mfma_f32_16x16x32_bf16 v[32:35], v[224:227], v[196:199], v[32:35]
	v_mfma_f32_16x16x32_bf16 v[28:31], v[232:235], v[196:199], v[28:31]
	v_mfma_f32_16x16x32_bf16 v[16:19], v[224:227], v[208:211], v[16:19]
	v_mfma_f32_16x16x32_bf16 v[12:15], v[232:235], v[208:211], v[12:15]
	v_mfma_f32_16x16x32_bf16 v[8:11], v[224:227], v[216:219], v[8:11]
	v_mfma_f32_16x16x32_bf16 v[4:7], v[232:235], v[216:219], v[4:7]
	v_mfma_f32_16x16x32_bf16 v[48:51], v[228:231], v[192:195], v[48:51]
	v_mfma_f32_16x16x32_bf16 v[44:47], v[236:239], v[192:195], v[44:47]
	v_mfma_f32_16x16x32_bf16 v[32:35], v[228:231], v[200:203], v[32:35]
	v_mfma_f32_16x16x32_bf16 v[28:31], v[236:239], v[200:203], v[28:31]
	v_mfma_f32_16x16x32_bf16 v[16:19], v[228:231], v[212:215], v[16:19]
	v_mfma_f32_16x16x32_bf16 v[12:15], v[236:239], v[212:215], v[12:15]
	s_setprio 2
	s_barrier
	v_mfma_f32_16x16x32_bf16 v[8:11], v[228:231], v[220:223], v[8:11]
	v_mfma_f32_16x16x32_bf16 v[4:7], v[236:239], v[220:223], v[4:7]
	s_setprio 0
	s_add_i32 s66, s66, 2
	s_add_u32 s42, s42, 0x100
	s_addc_u32 s43, s43, 0
	s_add_u32 s64, s64, 0x100
	s_addc_u32 s65, s65, 0
	s_cmp_gt_u32 s66, 29
	s_cbranch_scc1 .Lpeel_exit_225
.LBB0_225:
	s_add_i32 m0, s55, 0xc000
	ds_read_b128 v[188:191], v154
	ds_read_b128 v[192:195], v154 offset:1024
	ds_read_b128 v[196:199], v154 offset:2048
	ds_read_b128 v[200:203], v154 offset:3072
	ds_read_b128 v[208:211], v154 offset:4096
	ds_read_b128 v[212:215], v154 offset:5120
	ds_read_b128 v[216:219], v154 offset:6144
	ds_read_b128 v[220:223], v154 offset:7168
	global_load_lds_dwordx4 v144, s[42:43]
	s_add_i32 m0, s55, 0xe000
	s_nop 0
	global_load_lds_dwordx4 v146, s[42:43]
	s_waitcnt lgkmcnt(8)
	s_barrier
	s_waitcnt lgkmcnt(0)
	s_setprio 1
	s_waitcnt lgkmcnt(0)
	v_mfma_f32_16x16x32_bf16 v[128:131], v[156:159], v[188:191], v[128:131]
	s_add_u32 s44, s42, 0xfff80080
	s_addc_u32 s45, s43, -1
	v_mfma_f32_16x16x32_bf16 v[124:127], v[180:183], v[188:191], v[124:127]
	s_add_i32 s67, 0, 0x10000
	v_mfma_f32_16x16x32_bf16 v[120:123], v[156:159], v[196:199], v[120:123]
	s_cmp_eq_u32 s66, 28
	s_cselect_b32 s47, s27, s45
	s_cselect_b32 s46, s41, s44
	s_cselect_b32 s45, s23, s65
	s_cselect_b32 s44, s63, s64
	v_mfma_f32_16x16x32_bf16 v[116:119], v[180:183], v[196:199], v[116:119]
	v_mfma_f32_16x16x32_bf16 v[104:107], v[156:159], v[208:211], v[104:107]
	v_mfma_f32_16x16x32_bf16 v[100:103], v[180:183], v[208:211], v[100:103]
	v_mfma_f32_16x16x32_bf16 v[88:91], v[156:159], v[216:219], v[88:91]
	v_mfma_f32_16x16x32_bf16 v[84:87], v[180:183], v[216:219], v[84:87]
	v_mfma_f32_16x16x32_bf16 v[128:131], v[160:163], v[192:195], v[128:131]
	v_mfma_f32_16x16x32_bf16 v[124:127], v[184:187], v[192:195], v[124:127]
	v_mfma_f32_16x16x32_bf16 v[120:123], v[160:163], v[200:203], v[120:123]
	v_mfma_f32_16x16x32_bf16 v[116:119], v[184:187], v[200:203], v[116:119]
	v_mfma_f32_16x16x32_bf16 v[104:107], v[160:163], v[212:215], v[104:107]
	v_mfma_f32_16x16x32_bf16 v[100:103], v[184:187], v[212:215], v[100:103]
	s_setprio 2
	s_barrier
	v_mfma_f32_16x16x32_bf16 v[88:91], v[160:163], v[220:223], v[88:91]
	v_mfma_f32_16x16x32_bf16 v[84:87], v[184:187], v[220:223], v[84:87]
	s_setprio 0
	s_add_i32 s70, 0, 0x14000
	s_add_i32 s67, s67, s54
	s_add_u32 s98, s44, 0x80
	s_addc_u32 s99, s45, 0
	s_mov_b32 m0, s67
	ds_read_b128 v[224:227], v248 offset:16384
	ds_read_b128 v[228:231], v248 offset:17408
	ds_read_b128 v[232:235], v248 offset:18432
	ds_read_b128 v[236:239], v248 offset:19456
	global_load_lds_dwordx4 v136, s[44:45]
	s_add_i32 m0, s67, 0x2000
	s_nop 0
	global_load_lds_dwordx4 v132, s[44:45]
	s_barrier
; #define PG8_STAGE(bufoff, gbase, voff) do { _Pragma("unroll") for (int _i = 0; _i < 2; ++_i) \
;     __builtin_amdgcn_global_load_lds((const unsigned*)((const char*)(gbase) + (voff)[_i]), (LAS unsigned*)(lds + (bufoff) + ldsw + _i * 8192), 16, 0, 0); } while (0)
; #define PG8_LDA(dst, b, h) do { _Pragma("unroll") for (int m = 0; m < 4; ++m) _Pragma("unroll") for (int k = 0; k < 2; ++k) dst[m][k] = *(const LAS bf16x8*)(lds + PG8_SA(b, h) + aoff + m * 2048 + k * 1024); } while (0)
; #define PG8_LDB(dst, b, h) do { _Pragma("unroll") for (int n = 0; n < 2; ++n) _Pragma("unroll") for (int k = 0; k < 2; ++k) dst[n][k] = *(const LAS bf16x8*)(lds + PG8_SB(b, h) + boff + n * 2048 + k * 1024); } while (0)
; #define PG8_MMA(ai, bj, At, Bt) do { __builtin_amdgcn_s_setprio(1); _Pragma("unroll") for (int m = 0; m < 4; ++m) _Pragma("unroll") for (int n = 0; n < 2; ++n) _Pragma("unroll") for (int k = 0; k < 2; ++k) \
;     acc[ai][bj][m][n] = __builtin_amdgcn_mfma_f32_16x16x32_bf16(Bt[n][k], At[m][k], acc[ai][bj][m][n], 0, 0, 0); __builtin_amdgcn_s_setprio(0); } while (0)
; #define PG8_WAIT_V(n) asm volatile("s_waitcnt vmcnt(" #n ")" ::: "memory")
; #define PG8_WAIT_L(n) asm volatile("s_waitcnt lgkmcnt(" #n ")" ::: "memory")
; #define PG8_BAR __builtin_amdgcn_s_barrier()
; #define PG8_SCHED __builtin_amdgcn_sched_barrier(0)
; template <class Epi>
; DI void gemm_phase(LAS unsigned char* lds, const Gemm g, const Epi& E) {
;     ...
;       PG8_BAR; PG8_WAIT_L(0); PG8_MMA(0, 1, At, B1); PG8_BAR;
;       PG8_LDA(At, 0, 1); PG8_STAGE(PG8_SA(0, 0), a2, voffA);
;       PG8_BAR; PG8_WAIT_L(0); PG8_MMA(1, 0, At, B0); PG8_BAR; PG8_SCHED;
;       PG8_STAGE(PG8_SB(0, 1), b2 + hstepB, voffB);
;       PG8_WAIT_V(6); PG8_BAR; PG8_MMA(1, 1, At, B1); PG8_BAR;
;       PG8_LDB(B0, 1, 0); PG8_SCHED; PG8_LDA(At, 1, 0); PG8_STAGE(PG8_SA(0, 1), a2 + hstepA, voffA);
;       PG8_WAIT_L(8); PG8_BAR; PG8_WAIT_L(0); PG8_MMA(0, 0, At, B0); PG8_BAR; PG8_SCHED;
;       PG8_LDB(B1, 1, 1); PG8_STAGE(PG8_SB(1, 0), b3, voffB);
;       PG8_BAR; PG8_WAIT_L(0); PG8_MMA(0, 1, At, B1); PG8_BAR;
;       PG8_LDA(At, 1, 1); PG8_STAGE(PG8_SA(1, 0), a3, voffA);
	s_waitcnt lgkmcnt(0)
	s_setprio 1
	s_waitcnt lgkmcnt(0)
	v_mfma_f32_16x16x32_bf16 v[112:115], v[224:227], v[188:191], v[112:115]
	v_mfma_f32_16x16x32_bf16 v[108:111], v[232:235], v[188:191], v[108:111]
	v_mfma_f32_16x16x32_bf16 v[96:99], v[224:227], v[196:199], v[96:99]
	v_mfma_f32_16x16x32_bf16 v[92:95], v[232:235], v[196:199], v[92:95]
	v_mfma_f32_16x16x32_bf16 v[80:83], v[224:227], v[208:211], v[80:83]
	v_mfma_f32_16x16x32_bf16 v[76:79], v[232:235], v[208:211], v[76:79]
	v_mfma_f32_16x16x32_bf16 v[72:75], v[224:227], v[216:219], v[72:75]
	v_mfma_f32_16x16x32_bf16 v[68:71], v[232:235], v[216:219], v[68:71]
	v_mfma_f32_16x16x32_bf16 v[112:115], v[228:231], v[192:195], v[112:115]
	v_mfma_f32_16x16x32_bf16 v[108:111], v[236:239], v[192:195], v[108:111]
	v_mfma_f32_16x16x32_bf16 v[96:99], v[228:231], v[200:203], v[96:99]
	v_mfma_f32_16x16x32_bf16 v[92:95], v[236:239], v[200:203], v[92:95]
	v_mfma_f32_16x16x32_bf16 v[80:83], v[228:231], v[212:215], v[80:83]
	v_mfma_f32_16x16x32_bf16 v[76:79], v[236:239], v[212:215], v[76:79]
	s_setprio 2
	s_barrier
	v_mfma_f32_16x16x32_bf16 v[72:75], v[228:231], v[220:223], v[72:75]
	v_mfma_f32_16x16x32_bf16 v[68:71], v[236:239], v[220:223], v[68:71]
	s_setprio 0
	s_mov_b32 m0, s55
	s_add_u32 s100, s46, 0x80
	s_addc_u32 s101, s47, 0
	ds_read_b128 v[188:191], v154 offset:16384
	ds_read_b128 v[192:195], v154 offset:17408
	ds_read_b128 v[196:199], v154 offset:18432
	ds_read_b128 v[200:203], v154 offset:19456
	ds_read_b128 v[208:211], v154 offset:20480
	ds_read_b128 v[212:215], v154 offset:21504
	ds_read_b128 v[216:219], v154 offset:22528
	ds_read_b128 v[220:223], v154 offset:23552
	global_load_lds_dwordx4 v138, s[46:47]
	s_mov_b32 m0, s56
	s_nop 0
	global_load_lds_dwordx4 v134, s[46:47]
	s_waitcnt vmcnt(10)
	s_barrier
	s_waitcnt lgkmcnt(0)
	s_setprio 1
	s_waitcnt lgkmcnt(0)
	v_mfma_f32_16x16x32_bf16 v[64:67], v[156:159], v[188:191], v[64:67]
	v_mfma_f32_16x16x32_bf16 v[60:63], v[180:183], v[188:191], v[60:63]
	v_mfma_f32_16x16x32_bf16 v[56:59], v[156:159], v[196:199], v[56:59]
	v_mfma_f32_16x16x32_bf16 v[52:55], v[180:183], v[196:199], v[52:55]
	v_mfma_f32_16x16x32_bf16 v[40:43], v[156:159], v[208:211], v[40:43]
	v_mfma_f32_16x16x32_bf16 v[36:39], v[180:183], v[208:211], v[36:39]
	v_mfma_f32_16x16x32_bf16 v[24:27], v[156:159], v[216:219], v[24:27]
	v_mfma_f32_16x16x32_bf16 v[20:23], v[180:183], v[216:219], v[20:23]
	v_mfma_f32_16x16x32_bf16 v[64:67], v[160:163], v[192:195], v[64:67]
	v_mfma_f32_16x16x32_bf16 v[60:63], v[184:187], v[192:195], v[60:63]
	v_mfma_f32_16x16x32_bf16 v[56:59], v[160:163], v[200:203], v[56:59]
	v_mfma_f32_16x16x32_bf16 v[52:55], v[184:187], v[200:203], v[52:55]
	v_mfma_f32_16x16x32_bf16 v[40:43], v[160:163], v[212:215], v[40:43]
	v_mfma_f32_16x16x32_bf16 v[36:39], v[184:187], v[212:215], v[36:39]
	s_setprio 2
	s_barrier
	v_mfma_f32_16x16x32_bf16 v[24:27], v[160:163], v[220:223], v[24:27]
	v_mfma_f32_16x16x32_bf16 v[20:23], v[184:187], v[220:223], v[20:23]
	s_setprio 0
	ds_read_b128 v[156:159], v248 offset:32768
	ds_read_b128 v[160:163], v248 offset:33792
	ds_read_b128 v[180:183], v248 offset:34816
	ds_read_b128 v[184:187], v248 offset:35840
	s_add_u32 s68, s44, 0x80000
	s_addc_u32 s69, s45, 0
	s_add_i32 s67, s70, s54
	s_mov_b32 m0, s67
	s_nop 0
	global_load_lds_dwordx4 v136, s[68:69]
	s_add_i32 m0, s67, 0x2000
	s_nop 0
	global_load_lds_dwordx4 v132, s[68:69]
	s_waitcnt vmcnt(6)
	s_barrier
	s_setprio 1
	v_mfma_f32_16x16x32_bf16 v[48:51], v[224:227], v[188:191], v[48:51]
	v_mfma_f32_16x16x32_bf16 v[44:47], v[232:235], v[188:191], v[44:47]
	v_mfma_f32_16x16x32_bf16 v[32:35], v[224:227], v[196:199], v[32:35]
	v_mfma_f32_16x16x32_bf16 v[28:31], v[232:235], v[196:199], v[28:31]
	v_mfma_f32_16x16x32_bf16 v[16:19], v[224:227], v[208:211], v[16:19]
	v_mfma_f32_16x16x32_bf16 v[12:15], v[232:235], v[208:211], v[12:15]
	v_mfma_f32_16x16x32_bf16 v[8:11], v[224:227], v[216:219], v[8:11]
	v_mfma_f32_16x16x32_bf16 v[4:7], v[232:235], v[216:219], v[4:7]
	v_mfma_f32_16x16x32_bf16 v[48:51], v[228:231], v[192:195], v[48:51]
	v_mfma_f32_16x16x32_bf16 v[44:47], v[236:239], v[192:195], v[44:47]
	v_mfma_f32_16x16x32_bf16 v[32:35], v[228:231], v[200:203], v[32:35]
	v_mfma_f32_16x16x32_bf16 v[28:31], v[236:239], v[200:203], v[28:31]
	v_mfma_f32_16x16x32_bf16 v[16:19], v[228:231], v[212:215], v[16:19]
	v_mfma_f32_16x16x32_bf16 v[12:15], v[236:239], v[212:215], v[12:15]
	s_setprio 2
	s_barrier
	v_mfma_f32_16x16x32_bf16 v[8:11], v[228:231], v[220:223], v[8:11]
	v_mfma_f32_16x16x32_bf16 v[4:7], v[236:239], v[220:223], v[4:7]
	s_setprio 0
	s_add_i32 s67, 0, 0x18000
	s_add_u32 s46, s46, 0x80000
	s_addc_u32 s47, s47, 0
	s_mov_b32 m0, s57
	ds_read_b128 v[188:191], v154 offset:32768
	ds_read_b128 v[192:195], v154 offset:33792
	ds_read_b128 v[196:199], v154 offset:34816
	ds_read_b128 v[200:203], v154 offset:35840
	ds_read_b128 v[208:211], v154 offset:36864
	ds_read_b128 v[212:215], v154 offset:37888
	ds_read_b128 v[216:219], v154 offset:38912
	ds_read_b128 v[220:223], v154 offset:39936
	global_load_lds_dwordx4 v138, s[46:47]
	s_mov_b32 m0, s58
	s_nop 0
	global_load_lds_dwordx4 v134, s[46:47]
	s_waitcnt lgkmcnt(8)
	s_barrier
; #define PG8_STAGE(bufoff, gbase, voff) do { _Pragma("unroll") for (int _i = 0; _i < 2; ++_i) \
;     __builtin_amdgcn_global_load_lds((const unsigned*)((const char*)(gbase) + (voff)[_i]), (LAS unsigned*)(lds + (bufoff) + ldsw + _i * 8192), 16, 0, 0); } while (0)
; #define PG8_LDA(dst, b, h) do { _Pragma("unroll") for (int m = 0; m < 4; ++m) _Pragma("unroll") for (int k = 0; k < 2; ++k) dst[m][k] = *(const LAS bf16x8*)(lds + PG8_SA(b, h) + aoff + m * 2048 + k * 1024); } while (0)
; #define PG8_MMA(ai, bj, At, Bt) do { __builtin_amdgcn_s_setprio(1); _Pragma("unroll") for (int m = 0; m < 4; ++m) _Pragma("unroll") for (int n = 0; n < 2; ++n) _Pragma("unroll") for (int k = 0; k < 2; ++k) \
;     acc[ai][bj][m][n] = __builtin_amdgcn_mfma_f32_16x16x32_bf16(Bt[n][k], At[m][k], acc[ai][bj][m][n], 0, 0, 0); __builtin_amdgcn_s_setprio(0); } while (0)
; #define PG8_WAIT_V(n) asm volatile("s_waitcnt vmcnt(" #n ")" ::: "memory")
; #define PG8_WAIT_L(n) asm volatile("s_waitcnt lgkmcnt(" #n ")" ::: "memory")
; #define PG8_BAR __builtin_amdgcn_s_barrier()
; #define PG8_SCHED __builtin_amdgcn_sched_barrier(0)
; template <class Epi>
; DI void gemm_phase(LAS unsigned char* lds, const Gemm g, const Epi& E) {
;     ...
;       PG8_LDA(At, 1, 1); PG8_STAGE(PG8_SA(1, 0), a3, voffA);
;       PG8_BAR; PG8_WAIT_L(0); PG8_MMA(1, 0, At, B0); PG8_BAR; PG8_SCHED;
;       PG8_STAGE(PG8_SB(1, 1), b3 + hstepB, voffB);
;       PG8_WAIT_V(6); PG8_BAR; PG8_MMA(1, 1, At, B1); PG8_BAR;
	s_waitcnt lgkmcnt(0)
	s_setprio 1
	s_waitcnt lgkmcnt(0)
	v_mfma_f32_16x16x32_bf16 v[128:131], v[156:159], v[188:191], v[128:131]
	v_mfma_f32_16x16x32_bf16 v[124:127], v[180:183], v[188:191], v[124:127]
	v_mfma_f32_16x16x32_bf16 v[120:123], v[156:159], v[196:199], v[120:123]
	v_mfma_f32_16x16x32_bf16 v[116:119], v[180:183], v[196:199], v[116:119]
	v_mfma_f32_16x16x32_bf16 v[104:107], v[156:159], v[208:211], v[104:107]
	v_mfma_f32_16x16x32_bf16 v[100:103], v[180:183], v[208:211], v[100:103]
	v_mfma_f32_16x16x32_bf16 v[88:91], v[156:159], v[216:219], v[88:91]
	v_mfma_f32_16x16x32_bf16 v[84:87], v[180:183], v[216:219], v[84:87]
	v_mfma_f32_16x16x32_bf16 v[128:131], v[160:163], v[192:195], v[128:131]
	v_mfma_f32_16x16x32_bf16 v[124:127], v[184:187], v[192:195], v[124:127]
	v_mfma_f32_16x16x32_bf16 v[120:123], v[160:163], v[200:203], v[120:123]
	v_mfma_f32_16x16x32_bf16 v[116:119], v[184:187], v[200:203], v[116:119]
	v_mfma_f32_16x16x32_bf16 v[104:107], v[160:163], v[212:215], v[104:107]
	v_mfma_f32_16x16x32_bf16 v[100:103], v[184:187], v[212:215], v[100:103]
	s_setprio 2
	s_barrier
	v_mfma_f32_16x16x32_bf16 v[88:91], v[160:163], v[220:223], v[88:91]
	v_mfma_f32_16x16x32_bf16 v[84:87], v[184:187], v[220:223], v[84:87]
	s_setprio 0
	s_add_i32 s46, 0, 0x1c000
	s_add_i32 s47, s67, s54
	s_mov_b32 m0, s47
	ds_read_b128 v[224:227], v248 offset:49152
	ds_read_b128 v[228:231], v248 offset:50176
	ds_read_b128 v[232:235], v248 offset:51200
	ds_read_b128 v[236:239], v248 offset:52224
	global_load_lds_dwordx4 v136, s[98:99]
	s_add_i32 m0, s47, 0x2000
	s_nop 0
	global_load_lds_dwordx4 v132, s[98:99]
	s_barrier
	s_waitcnt lgkmcnt(0)
	s_setprio 1
	s_waitcnt lgkmcnt(0)
	v_mfma_f32_16x16x32_bf16 v[112:115], v[224:227], v[188:191], v[112:115]
	v_mfma_f32_16x16x32_bf16 v[108:111], v[232:235], v[188:191], v[108:111]
	v_mfma_f32_16x16x32_bf16 v[96:99], v[224:227], v[196:199], v[96:99]
	v_mfma_f32_16x16x32_bf16 v[92:95], v[232:235], v[196:199], v[92:95]
	v_mfma_f32_16x16x32_bf16 v[80:83], v[224:227], v[208:211], v[80:83]
	v_mfma_f32_16x16x32_bf16 v[76:79], v[232:235], v[208:211], v[76:79]
	v_mfma_f32_16x16x32_bf16 v[72:75], v[224:227], v[216:219], v[72:75]
	v_mfma_f32_16x16x32_bf16 v[68:71], v[232:235], v[216:219], v[68:71]
	v_mfma_f32_16x16x32_bf16 v[112:115], v[228:231], v[192:195], v[112:115]
	v_mfma_f32_16x16x32_bf16 v[108:111], v[236:239], v[192:195], v[108:111]
	v_mfma_f32_16x16x32_bf16 v[96:99], v[228:231], v[200:203], v[96:99]
	v_mfma_f32_16x16x32_bf16 v[92:95], v[236:239], v[200:203], v[92:95]
	v_mfma_f32_16x16x32_bf16 v[80:83], v[228:231], v[212:215], v[80:83]
	v_mfma_f32_16x16x32_bf16 v[76:79], v[236:239], v[212:215], v[76:79]
	s_setprio 2
	s_barrier
	v_mfma_f32_16x16x32_bf16 v[72:75], v[228:231], v[220:223], v[72:75]
	v_mfma_f32_16x16x32_bf16 v[68:71], v[236:239], v[220:223], v[68:71]
	s_setprio 0
	s_mov_b32 m0, s60
	ds_read_b128 v[188:191], v154 offset:49152
	ds_read_b128 v[192:195], v154 offset:50176
	ds_read_b128 v[196:199], v154 offset:51200
	ds_read_b128 v[200:203], v154 offset:52224
	ds_read_b128 v[208:211], v154 offset:53248
	ds_read_b128 v[212:215], v154 offset:54272
	ds_read_b128 v[216:219], v154 offset:55296
	ds_read_b128 v[220:223], v154 offset:56320
	global_load_lds_dwordx4 v138, s[100:101]
	s_mov_b32 m0, s61
	s_nop 0
	global_load_lds_dwordx4 v134, s[100:101]
	s_waitcnt vmcnt(10)
	s_barrier
	s_waitcnt lgkmcnt(0)
	s_setprio 1
	s_waitcnt lgkmcnt(0)
	v_mfma_f32_16x16x32_bf16 v[64:67], v[156:159], v[188:191], v[64:67]
	v_mfma_f32_16x16x32_bf16 v[60:63], v[180:183], v[188:191], v[60:63]
	v_mfma_f32_16x16x32_bf16 v[56:59], v[156:159], v[196:199], v[56:59]
	v_mfma_f32_16x16x32_bf16 v[52:55], v[180:183], v[196:199], v[52:55]
	v_mfma_f32_16x16x32_bf16 v[40:43], v[156:159], v[208:211], v[40:43]
	v_mfma_f32_16x16x32_bf16 v[36:39], v[180:183], v[208:211], v[36:39]
	v_mfma_f32_16x16x32_bf16 v[24:27], v[156:159], v[216:219], v[24:27]
	v_mfma_f32_16x16x32_bf16 v[20:23], v[180:183], v[216:219], v[20:23]
	v_mfma_f32_16x16x32_bf16 v[64:67], v[160:163], v[192:195], v[64:67]
	v_mfma_f32_16x16x32_bf16 v[60:63], v[184:187], v[192:195], v[60:63]
	v_mfma_f32_16x16x32_bf16 v[56:59], v[160:163], v[200:203], v[56:59]
	v_mfma_f32_16x16x32_bf16 v[52:55], v[184:187], v[200:203], v[52:55]
	v_mfma_f32_16x16x32_bf16 v[40:43], v[160:163], v[212:215], v[40:43]
	v_mfma_f32_16x16x32_bf16 v[36:39], v[184:187], v[212:215], v[36:39]
	s_setprio 2
	s_barrier
	v_mfma_f32_16x16x32_bf16 v[24:27], v[160:163], v[220:223], v[24:27]
	v_mfma_f32_16x16x32_bf16 v[20:23], v[184:187], v[220:223], v[20:23]
	s_setprio 0
	ds_read_b128 v[156:159], v248
	ds_read_b128 v[160:163], v248 offset:1024
	ds_read_b128 v[180:183], v248 offset:2048
	ds_read_b128 v[184:187], v248 offset:3072
	s_add_u32 s44, s44, 0x80080
	s_addc_u32 s45, s45, 0
	s_add_i32 s46, s46, s54
	s_mov_b32 m0, s46
	s_nop 0
	global_load_lds_dwordx4 v136, s[44:45]
	s_add_i32 m0, s46, 0x2000
	s_nop 0
	global_load_lds_dwordx4 v132, s[44:45]
	s_waitcnt vmcnt(6)
	s_barrier
	s_setprio 1
	v_mfma_f32_16x16x32_bf16 v[48:51], v[224:227], v[188:191], v[48:51]
	v_mfma_f32_16x16x32_bf16 v[44:47], v[232:235], v[188:191], v[44:47]
	v_mfma_f32_16x16x32_bf16 v[32:35], v[224:227], v[196:199], v[32:35]
	v_mfma_f32_16x16x32_bf16 v[28:31], v[232:235], v[196:199], v[28:31]
	v_mfma_f32_16x16x32_bf16 v[16:19], v[224:227], v[208:211], v[16:19]
	v_mfma_f32_16x16x32_bf16 v[12:15], v[232:235], v[208:211], v[12:15]
	v_mfma_f32_16x16x32_bf16 v[8:11], v[224:227], v[216:219], v[8:11]
	v_mfma_f32_16x16x32_bf16 v[4:7], v[232:235], v[216:219], v[4:7]
	v_mfma_f32_16x16x32_bf16 v[48:51], v[228:231], v[192:195], v[48:51]
	v_mfma_f32_16x16x32_bf16 v[44:47], v[236:239], v[192:195], v[44:47]
	v_mfma_f32_16x16x32_bf16 v[32:35], v[228:231], v[200:203], v[32:35]
	v_mfma_f32_16x16x32_bf16 v[28:31], v[236:239], v[200:203], v[28:31]
	v_mfma_f32_16x16x32_bf16 v[16:19], v[228:231], v[212:215], v[16:19]
	v_mfma_f32_16x16x32_bf16 v[12:15], v[236:239], v[212:215], v[12:15]
	s_setprio 2
	s_barrier
	v_mfma_f32_16x16x32_bf16 v[8:11], v[228:231], v[220:223], v[8:11]
	v_mfma_f32_16x16x32_bf16 v[4:7], v[236:239], v[220:223], v[4:7]
	s_setprio 0
	s_add_i32 s66, s66, 2
	s_add_u32 s42, s42, 0x100
	s_addc_u32 s43, s43, 0
	s_add_u32 s64, s64, 0x100
	s_addc_u32 s65, s65, 0
	s_cmp_gt_u32 s66, 29
	s_cbranch_scc0 .LBB0_225

.LBB0_358:
	s_or_b64 exec, exec, s[36:37]
	s_lshl_b64 s[36:37], s[46:47], 8
	v_lshl_add_u64 v[28:29], s[36:37], 0, v[114:115]
	v_lshlrev_b64 v[28:29], 7, v[28:29]
	v_lshl_add_u64 v[28:29], s[44:45], 0, v[28:29]
	s_lshl_b64 s[36:37], s[46:47], 10
	v_lshl_add_u64 v[36:37], v[28:29], 0, v[2:3]
	global_load_dwordx4 v[44:47], v[36:37], off offset:0
	s_add_u32 s36, s76, s36
	global_load_dwordx4 v[40:43], v[36:37], off offset:64
	s_addc_u32 s37, s77, s37
	global_load_dwordx4 v[28:31], v[36:37], off offset:0x800
	s_add_u32 s36, s36, s12
	global_load_dwordx4 v[32:35], v[36:37], off offset:0x840
	s_addc_u32 s37, s37, s13
	v_lshl_add_u64 v[92:93], s[36:37], 0, v[130:131]
	global_load_dwordx4 v[48:51], v[92:93], off offset:0
	global_load_dwordx4 v[36:39], v[92:93], off offset:64
	ds_read_b128 v[104:107], v199
	ds_read_b128 v[96:99], v200
	ds_read_b128 v[100:103], v201
	ds_read_b128 v[92:95], v202
	ds_read_b128 v[142:145], v203 offset:36864
	ds_read_b128 v[200:203], v207 offset:36864
	s_waitcnt lgkmcnt(0)
	v_cndmask_b32_e64 v141, v99, v107, s[42:43]
	v_cndmask_b32_e64 v140, v98, v106, s[42:43]
	v_cndmask_b32_e64 v139, v97, v105, s[42:43]
	v_cndmask_b32_e64 v138, v96, v104, s[42:43]
	v_mul_f32_e32 v86, v26, v86
	v_mul_f32_e32 v87, v27, v87
	v_mul_f32_e32 v84, v24, v84
	v_mul_f32_e32 v85, v25, v85
	v_mfma_f32_16x16x32_bf16 v[138:141], v[138:141], v[142:145], 0
	v_cndmask_b32_e64 v145, v95, v103, s[42:43]
	v_cndmask_b32_e64 v144, v94, v102, s[42:43]
	v_cndmask_b32_e64 v143, v93, v101, s[42:43]
	v_cndmask_b32_e64 v142, v92, v100, s[42:43]
	v_mul_f32_e32 v26, v26, v90
	v_mul_f32_e32 v27, v27, v91
	v_mul_f32_e32 v24, v24, v88
	v_mul_f32_e32 v25, v25, v89
	v_mfma_f32_16x16x32_bf16 v[138:141], v[142:145], v[200:203], v[138:141]
	ds_read_b128 v[142:145], v184
	ds_read_b128 v[200:203], v194 offset:45056
	s_and_b64 s[30:31], s[30:31], exec
	s_movk_i32 s30, 0x3f40
	s_waitcnt lgkmcnt(0)
	v_mfma_f32_16x16x32_bf16 v[138:141], v[142:145], v[200:203], v[138:141]
	ds_read_b128 v[142:145], v184 offset:64
	ds_read_b128 v[200:203], v193 offset:45056
	s_cselect_b32 s30, s30, 0x80
	v_mov_b32_e32 v2, s22
	s_waitcnt lgkmcnt(0)
	v_mfma_f32_16x16x32_bf16 v[138:141], v[142:145], v[200:203], v[138:141]
	ds_read_b128 v[142:145], v184 offset:128
	ds_read_b128 v[200:203], v192 offset:45056
	v_or3_b32 v136, s30, v112, v2
	v_lshlrev_b64 v[136:137], 6, v[136:137]
	s_waitcnt lgkmcnt(0)
	v_mfma_f32_16x16x32_bf16 v[138:141], v[142:145], v[200:203], v[138:141]
	ds_read_b128 v[142:145], v184 offset:192
	ds_read_b128 v[200:203], v191 offset:45056
	v_lshl_add_u64 v[136:137], s[18:19], 0, v[136:137]
	v_lshl_add_u64 v[136:137], v[136:137], 0, s[26:27]
	s_waitcnt lgkmcnt(0)
	v_mfma_f32_16x16x32_bf16 v[138:141], v[142:145], v[200:203], v[138:141]
	ds_read_b128 v[142:145], v184 offset:256
	ds_read_b128 v[200:203], v188 offset:45056
	v_lshl_add_u64 v[136:137], v[136:137], 0, v[132:133]
	v_mov_b32_e32 v135, s23
	s_waitcnt lgkmcnt(0)
	v_mfma_f32_16x16x32_bf16 v[138:141], v[142:145], v[200:203], v[138:141]
	ds_read_b128 v[142:145], v184 offset:320
	ds_read_b128 v[200:203], v187 offset:45056
	s_waitcnt lgkmcnt(0)
	v_mfma_f32_16x16x32_bf16 v[138:141], v[142:145], v[200:203], v[138:141]
	ds_read_b128 v[142:145], v184 offset:384
	ds_read_b128 v[200:203], v189 offset:45056
	v_mfma_f32_16x16x32_bf16 v[84:87], v[20:23], v[104:107], v[84:87]
	v_mfma_f32_16x16x32_bf16 v[20:23], v[20:23], v[96:99], v[24:27]
	s_waitcnt lgkmcnt(0)
	v_mfma_f32_16x16x32_bf16 v[138:141], v[142:145], v[200:203], v[138:141]
	ds_read_b128 v[142:145], v184 offset:448
	ds_read_b128 v[200:203], v190 offset:45056
	v_mfma_f32_16x16x32_bf16 v[84:87], v[16:19], v[100:103], v[84:87]
	v_mfma_f32_16x16x32_bf16 v[20:23], v[16:19], v[92:95], v[20:23]
	v_mul_f32_e64 v18, v14, v82
	v_mul_f32_e64 v19, v15, v83
	v_mul_f32_e32 v16, v12, v80
	v_mul_f32_e32 v17, v13, v81
	v_mul_f32_e32 v14, v14, v78
	v_mul_f32_e32 v15, v15, v79
	v_mul_f32_e32 v12, v12, v76
	v_mul_f32_e32 v13, v13, v77
	v_mfma_f32_16x16x32_bf16 v[16:19], v[8:11], v[104:107], v[16:19]
	s_waitcnt lgkmcnt(0)
	v_mfma_f32_16x16x32_bf16 v[138:141], v[142:145], v[200:203], v[138:141]
	v_mfma_f32_16x16x32_bf16 v[8:11], v[8:11], v[96:99], v[12:15]
	v_mfma_f32_16x16x32_bf16 v[16:19], v[4:7], v[100:103], v[16:19]
	s_nop 5
	v_cvt_pk_bf16_f32 v138, v138, v139
	v_cvt_pk_bf16_f32 v139, v140, v141
	global_store_dwordx2 v[136:137], v[138:139], off
	v_mfma_f32_16x16x32_bf16 v[4:7], v[4:7], v[92:95], v[8:11]
	s_waitcnt lgkmcnt(0)
	s_barrier
	s_nop 1
	v_cvt_pk_bf16_f32 v8, v84, v85
	v_cvt_pk_bf16_f32 v9, v86, v87
	ds_write_b64 v185, v[8:9]
	v_cvt_pk_bf16_f32 v8, v20, v21
	v_cvt_pk_bf16_f32 v9, v22, v23
	ds_write_b64 v185, v[8:9] offset:8448
	v_cvt_pk_bf16_f32 v8, v16, v17
	v_cvt_pk_bf16_f32 v9, v18, v19
	ds_write_b64 v186, v[8:9]
	v_cvt_pk_bf16_f32 v8, v4, v5
	v_cvt_pk_bf16_f32 v9, v6, v7
	ds_write_b64 v186, v[8:9] offset:8448
	s_waitcnt vmcnt(14) lgkmcnt(0)
	s_barrier
	ds_read_b128 v[8:11], v208
	ds_read_b128 v[24:27], v212
	ds_read_b128 v[80:83], v214
	ds_read_b128 v[76:79], v218
	ds_read_b128 v[88:91], v216 offset:36864
	ds_read_b128 v[92:95], v215 offset:36864
	s_waitcnt lgkmcnt(0)
	v_cndmask_b32_e64 v15, v27, v11, s[42:43]
	v_cndmask_b32_e64 v14, v26, v10, s[42:43]
	v_cndmask_b32_e64 v13, v25, v9, s[42:43]
	v_cndmask_b32_e64 v12, v24, v8, s[42:43]
	v_or_b32_e32 v2, s8, v112
	v_or_b32_e32 v134, s22, v2
	v_mfma_f32_16x16x32_bf16 v[12:15], v[12:15], v[88:91], 0
	v_cndmask_b32_e64 v91, v79, v83, s[42:43]
	v_cndmask_b32_e64 v90, v78, v82, s[42:43]
	v_cndmask_b32_e64 v89, v77, v81, s[42:43]
	v_cndmask_b32_e64 v88, v76, v80, s[42:43]
	v_mul_f32_e32 v22, v74, v22
	v_mul_f32_e32 v23, v75, v23
	v_mul_f32_e32 v20, v72, v20
	v_mul_f32_e32 v21, v73, v21
	v_mfma_f32_16x16x32_bf16 v[12:15], v[88:91], v[92:95], v[12:15]
	ds_read_b128 v[88:91], v184
	ds_read_b128 v[92:95], v219
	v_mul_f32_e32 v18, v62, v18
	v_mul_f32_e32 v19, v63, v19
	v_mul_f32_e32 v16, v60, v16
	v_mul_f32_e32 v17, v61, v17
	s_waitcnt lgkmcnt(0)
	v_mfma_f32_16x16x32_bf16 v[12:15], v[88:91], v[92:95], v[12:15]
	ds_read_b128 v[88:91], v184 offset:64
	ds_read_b128 v[92:95], v213
	v_mul_f32_e32 v6, v62, v6
	v_mul_f32_e32 v7, v63, v7
	v_mul_f32_e32 v4, v60, v4
	v_mul_f32_e32 v5, v61, v5
	s_waitcnt lgkmcnt(0)
	v_mfma_f32_16x16x32_bf16 v[12:15], v[88:91], v[92:95], v[12:15]
	ds_read_b128 v[88:91], v184 offset:128
	ds_read_b128 v[92:95], v217
	s_waitcnt lgkmcnt(0)
	v_mfma_f32_16x16x32_bf16 v[12:15], v[88:91], v[92:95], v[12:15]
	ds_read_b128 v[88:91], v184 offset:192
	ds_read_b128 v[92:95], v209
	s_waitcnt lgkmcnt(0)
	v_mfma_f32_16x16x32_bf16 v[12:15], v[88:91], v[92:95], v[12:15]
	ds_read_b128 v[88:91], v184 offset:256
	ds_read_b128 v[92:95], v210
	s_waitcnt lgkmcnt(0)
	v_mfma_f32_16x16x32_bf16 v[12:15], v[88:91], v[92:95], v[12:15]
	ds_read_b128 v[88:91], v184 offset:320
	ds_read_b128 v[92:95], v211
	s_waitcnt lgkmcnt(0)
	v_mfma_f32_16x16x32_bf16 v[12:15], v[88:91], v[92:95], v[12:15]
	ds_read_b128 v[88:91], v184 offset:384
	ds_read_b128 v[92:95], v220
	s_waitcnt lgkmcnt(0)
	v_mfma_f32_16x16x32_bf16 v[12:15], v[88:91], v[92:95], v[12:15]
	ds_read_b128 v[88:91], v184 offset:448
	ds_read_b128 v[92:95], v221
	s_waitcnt lgkmcnt(0)
	v_mfma_f32_16x16x32_bf16 v[12:15], v[88:91], v[92:95], v[12:15]
	v_mfma_f32_16x16x32_bf16 v[20:23], v[68:71], v[24:27], v[20:23]
	s_nop 6
	v_cvt_pk_bf16_f32 v12, v12, v13
	v_cvt_pk_bf16_f32 v13, v14, v15
	v_lshlrev_b64 v[14:15], 6, v[134:135]
	v_lshl_add_u64 v[14:15], s[18:19], 0, v[14:15]
	v_lshl_add_u64 v[14:15], v[14:15], 0, s[26:27]
	v_lshl_add_u64 v[14:15], v[14:15], 0, v[132:133]
	global_store_dwordx2 v[14:15], v[12:13], off
	v_mul_f32_e32 v14, v74, v86
	v_mul_f32_e32 v15, v75, v87
	v_mul_f32_e32 v12, v72, v84
	v_mul_f32_e32 v13, v73, v85
	v_mfma_f32_16x16x32_bf16 v[4:7], v[52:55], v[24:27], v[4:7]
	s_waitcnt lgkmcnt(0)
	s_barrier
	v_mfma_f32_16x16x32_bf16 v[12:15], v[68:71], v[8:11], v[12:15]
	v_mfma_f32_16x16x32_bf16 v[8:11], v[52:55], v[8:11], v[16:19]
	v_mfma_f32_16x16x32_bf16 v[12:15], v[64:67], v[80:83], v[12:15]
	v_mfma_f32_16x16x32_bf16 v[20:23], v[64:67], v[76:79], v[20:23]
	v_mfma_f32_16x16x32_bf16 v[8:11], v[56:59], v[80:83], v[8:11]
	s_nop 5
	v_cvt_pk_bf16_f32 v16, v12, v13
	v_cvt_pk_bf16_f32 v17, v14, v15
	ds_write_b64 v185, v[16:17]
	v_mfma_f32_16x16x32_bf16 v[4:7], v[56:59], v[76:79], v[4:7]
	v_cvt_pk_bf16_f32 v16, v20, v21
	v_cvt_pk_bf16_f32 v17, v22, v23
	ds_write_b64 v185, v[16:17] offset:8448
	v_cvt_pk_bf16_f32 v16, v8, v9
	v_cvt_pk_bf16_f32 v17, v10, v11
	ds_write_b64 v186, v[16:17]
	s_nop 1
	v_cvt_pk_bf16_f32 v16, v4, v5
	v_cvt_pk_bf16_f32 v17, v6, v7
	ds_write_b64 v186, v[16:17] offset:8448
	s_waitcnt vmcnt(2) lgkmcnt(0)
	s_barrier
; DI void gla_scan_phase(LAS unsigned char* lds, LAS unsigned char* sml, const bf16_t* QF, const bf16_t* QB, const bf16_t* KEF, const bf16_t* KEB, const bf16_t* VT, const float* DEC, const bf16_t* PF, const bf16_t* PB, bf16_t* OF, bf16_t* OB) {
;     ...
;     SCAN_ISSUE(0, 0, R0); SCAN_ISSUE(1, 1, R1);
;     asm volatile("s_waitcnt vmcnt(12) lgkmcnt(0)" ::: "memory"); __builtin_amdgcn_s_barrier(); asm volatile("" ::: "memory"); __builtin_amdgcn_sched_barrier(0);
; #pragma unroll 1
;     for (int jb = 0; jb < NCH - 4; jb += 3) { SCAN_STEP(jb, 0, R0, 2, R2, 1, 14); SCAN_STEP(jb + 1, 1, R1, 0, R0, 1, 14); SCAN_STEP(jb + 2, 2, R2, 1, R1, 1, 14); }
;     SCAN_STEP(NCH - 4, 0, R0, 2, R2, 1, 14); SCAN_STEP(NCH - 3, 1, R1, 0, R0, 1, 14); SCAN_STEP(NCH - 2, 2, R2, 1, R1, 0, 2); SCAN_STEP(NCH - 1, 0, R0, 2, R2, 0, 0);
;     asm volatile("s_waitcnt vmcnt(0)" ::: "memory");
;     ...
;   }
	ds_read_b128 v[52:55], v197 offset:32768
	ds_read_b128 v[16:19], v197 offset:34816
	ds_read_b128 v[56:59], v198 offset:32768
	ds_read_b128 v[24:27], v198 offset:34816
	ds_read_b128 v[64:67], v196 offset:36864
	ds_read_b128 v[68:71], v195 offset:36864
	s_waitcnt lgkmcnt(0)
	v_cndmask_b32_e64 v63, v19, v55, s[42:43]
	v_cndmask_b32_e64 v62, v18, v54, s[42:43]
	v_cndmask_b32_e64 v61, v17, v53, s[42:43]
	v_cndmask_b32_e64 v60, v16, v52, s[42:43]
	v_mul_f32_e32 v14, v50, v14
	v_mul_f32_e32 v15, v51, v15
	v_mul_f32_e32 v12, v48, v12
	v_mul_f32_e32 v13, v49, v13
	v_mfma_f32_16x16x32_bf16 v[60:63], v[60:63], v[64:67], 0
	v_cndmask_b32_e64 v67, v27, v59, s[42:43]
	v_cndmask_b32_e64 v66, v26, v58, s[42:43]
	v_cndmask_b32_e64 v65, v25, v57, s[42:43]
	v_cndmask_b32_e64 v64, v24, v56, s[42:43]
	v_mfma_f32_16x16x32_bf16 v[12:15], v[44:47], v[52:55], v[12:15]
	v_mul_f32_e64 v22, v50, v22
	v_mul_f32_e64 v23, v51, v23
	v_mul_f32_e32 v20, v48, v20
	v_mul_f32_e32 v21, v49, v21
	v_mul_f32_e32 v10, v38, v10
	v_mul_f32_e32 v11, v39, v11
	v_mfma_f32_16x16x32_bf16 v[60:63], v[64:67], v[68:71], v[60:63]
	ds_read_b128 v[64:67], v184
	ds_read_b128 v[68:71], v194
	v_mul_f32_e32 v8, v36, v8
	v_mul_f32_e32 v9, v37, v9
	v_mul_f32_e32 v6, v38, v6
	v_mul_f32_e32 v7, v39, v7
	s_waitcnt lgkmcnt(0)
	v_mfma_f32_16x16x32_bf16 v[60:63], v[64:67], v[68:71], v[60:63]
	ds_read_b128 v[64:67], v184 offset:64
	ds_read_b128 v[68:71], v193
	v_mul_f32_e32 v4, v36, v4
	v_mul_f32_e32 v5, v37, v5
	v_or_b32_e32 v2, s52, v112
	s_waitcnt lgkmcnt(0)
	v_mfma_f32_16x16x32_bf16 v[60:63], v[64:67], v[68:71], v[60:63]
	ds_read_b128 v[64:67], v184 offset:128
	ds_read_b128 v[68:71], v192
	v_or_b32_e32 v134, s22, v2
	s_waitcnt lgkmcnt(0)
	v_mfma_f32_16x16x32_bf16 v[60:63], v[64:67], v[68:71], v[60:63]
	ds_read_b128 v[64:67], v184 offset:192
	ds_read_b128 v[68:71], v191
	s_waitcnt lgkmcnt(0)
	v_mfma_f32_16x16x32_bf16 v[60:63], v[64:67], v[68:71], v[60:63]
	ds_read_b128 v[64:67], v184 offset:256
	ds_read_b128 v[68:71], v188
	s_waitcnt lgkmcnt(0)
	v_mfma_f32_16x16x32_bf16 v[60:63], v[64:67], v[68:71], v[60:63]
	ds_read_b128 v[64:67], v184 offset:320
	ds_read_b128 v[68:71], v187
	s_waitcnt lgkmcnt(0)
	v_mfma_f32_16x16x32_bf16 v[60:63], v[64:67], v[68:71], v[60:63]
	ds_read_b128 v[64:67], v184 offset:384
	ds_read_b128 v[68:71], v189
	s_waitcnt lgkmcnt(0)
	v_mfma_f32_16x16x32_bf16 v[60:63], v[64:67], v[68:71], v[60:63]
	ds_read_b128 v[64:67], v184 offset:448
	ds_read_b128 v[68:71], v190
	s_waitcnt lgkmcnt(0)
	v_mfma_f32_16x16x32_bf16 v[60:63], v[64:67], v[68:71], v[60:63]
	v_mfma_f32_16x16x32_bf16 v[20:23], v[44:47], v[16:19], v[20:23]
	s_nop 6
	v_cvt_pk_bf16_f32 v60, v60, v61
	v_cvt_pk_bf16_f32 v61, v62, v63
	v_lshlrev_b64 v[62:63], 6, v[134:135]
	v_mfma_f32_16x16x32_bf16 v[8:11], v[28:31], v[52:55], v[8:11]
	v_lshl_add_u64 v[62:63], s[18:19], 0, v[62:63]
	v_lshl_add_u64 v[62:63], v[62:63], 0, s[26:27]
	v_lshl_add_u64 v[62:63], v[62:63], 0, v[132:133]
	v_mfma_f32_16x16x32_bf16 v[4:7], v[28:31], v[16:19], v[4:7]
	global_store_dwordx2 v[62:63], v[60:61], off
	s_waitcnt lgkmcnt(0)
	s_barrier
	v_mfma_f32_16x16x32_bf16 v[12:15], v[40:43], v[56:59], v[12:15]
	v_mfma_f32_16x16x32_bf16 v[20:23], v[40:43], v[24:27], v[20:23]
	v_mfma_f32_16x16x32_bf16 v[8:11], v[32:35], v[56:59], v[8:11]
	s_nop 5
	v_cvt_pk_bf16_f32 v12, v12, v13
	v_cvt_pk_bf16_f32 v13, v14, v15
	ds_write_b64 v185, v[12:13]
	v_mfma_f32_16x16x32_bf16 v[4:7], v[32:35], v[24:27], v[4:7]
	v_cvt_pk_bf16_f32 v12, v20, v21
	v_cvt_pk_bf16_f32 v13, v22, v23
	v_cvt_pk_bf16_f32 v8, v8, v9
	v_cvt_pk_bf16_f32 v9, v10, v11
	ds_write_b64 v185, v[12:13] offset:8448
	s_nop 2
	v_cvt_pk_bf16_f32 v4, v4, v5
	v_cvt_pk_bf16_f32 v5, v6, v7
	ds_write_b64 v186, v[8:9]
	ds_write_b64 v186, v[4:5] offset:8448
	s_waitcnt vmcnt(0) lgkmcnt(0)
	s_barrier
	s_waitcnt vmcnt(0)
	s_add_i32 s25, s25, s33
	s_cmpk_lt_i32 s25, 0x100
	s_cbranch_scc0 .LBB0_380

.LBB0_369:
	s_or_b64 exec, exec, s[54:55]
	s_lshl_b64 s[54:55], s[52:53], 8
	v_lshl_add_u64 v[4:5], s[54:55], 0, v[114:115]
	v_lshlrev_b64 v[4:5], 7, v[4:5]
	v_lshl_add_u64 v[244:245], v[138:139], 0, v[4:5]
	s_lshl_b64 s[52:53], s[52:53], 10
	v_lshl_add_u64 v[250:251], v[140:141], 0, s[52:53]
	v_add_u32_e32 v208, v180, v117
	v_add_u32_e32 v212, v180, v119
	ds_read_b128 v[100:103], v208
	ds_read_b128 v[96:99], v212
	v_add_u32_e32 v214, v181, v117
	v_add_u32_e32 v218, v181, v119
	v_add_u32_e32 v216, v180, v113
	ds_read_b128 v[104:107], v214
	ds_read_b128 v[92:95], v218
	ds_read_b128 v[224:227], v216 offset:36864
	s_mov_b32 m0, s67
	s_nop 0
	global_load_lds_dwordx4 v[234:235], off
	s_mov_b32 m0, s79
	s_nop 0
	global_load_lds_dwordx4 v[236:237], off
	s_waitcnt lgkmcnt(0)
	v_cndmask_b32_e64 v223, v99, v103, s[42:43]
	v_cndmask_b32_e64 v222, v98, v102, s[42:43]
	v_cndmask_b32_e64 v221, v97, v101, s[42:43]
	v_cndmask_b32_e64 v220, v96, v100, s[42:43]
	v_add_u32_e32 v215, v181, v113
	ds_read_b128 v[228:231], v215 offset:36864
	v_mfma_f32_16x16x32_bf16 v[220:223], v[220:223], v[224:227], 0
	v_cndmask_b32_e64 v227, v95, v107, s[42:43]
	v_cndmask_b32_e64 v226, v94, v106, s[42:43]
	v_cndmask_b32_e64 v225, v93, v105, s[42:43]
	v_cndmask_b32_e64 v224, v92, v104, s[42:43]
	v_add_u32_e32 v219, v151, v154
	v_add_u32_e32 v213, v151, v155
	s_mov_b32 m0, s80
	s_nop 0
	global_load_lds_dwordx4 v[238:239], off
	s_waitcnt lgkmcnt(0)
	v_mfma_f32_16x16x32_bf16 v[220:223], v[224:227], v[228:231], v[220:223]
	ds_read_b128 v[224:227], v184
	ds_read_b128 v[228:231], v219
	v_add_u32_e32 v217, v151, v156
	s_mov_b32 m0, s81
	s_nop 0
	global_load_lds_dwordx4 v[240:241], off
	s_waitcnt lgkmcnt(0)
	v_mfma_f32_16x16x32_bf16 v[220:223], v[224:227], v[228:231], v[220:223]
	ds_read_b128 v[224:227], v184 offset:64
	ds_read_b128 v[228:231], v213
	v_add_u32_e32 v209, v151, v157
	s_mov_b32 m0, s82
	s_nop 0
	global_load_lds_dwordx4 v[242:243], off
	s_waitcnt lgkmcnt(0)
	v_mfma_f32_16x16x32_bf16 v[220:223], v[224:227], v[228:231], v[220:223]
	ds_read_b128 v[224:227], v184 offset:128
	ds_read_b128 v[228:231], v217
	v_add_u32_e32 v210, v151, v158
	global_load_dwordx4 v[20:23], v[244:245], off offset:0
	s_waitcnt lgkmcnt(0)
	v_mfma_f32_16x16x32_bf16 v[220:223], v[224:227], v[228:231], v[220:223]
	ds_read_b128 v[224:227], v184 offset:192
	ds_read_b128 v[228:231], v209
	v_add_u32_e32 v211, v151, v159
	global_load_dwordx4 v[16:19], v[244:245], off offset:64
	s_waitcnt lgkmcnt(0)
	v_mfma_f32_16x16x32_bf16 v[220:223], v[224:227], v[228:231], v[220:223]
	ds_read_b128 v[224:227], v184 offset:256
	ds_read_b128 v[228:231], v210
	v_mul_f32_e32 v86, v74, v86
	v_mul_f32_e32 v87, v75, v87
	global_load_dwordx4 v[8:11], v[244:245], off offset:0x800
	s_waitcnt lgkmcnt(0)
	v_mfma_f32_16x16x32_bf16 v[220:223], v[224:227], v[228:231], v[220:223]
	ds_read_b128 v[224:227], v184 offset:320
	ds_read_b128 v[228:231], v211
	v_mul_f32_e32 v84, v72, v84
	v_mul_f32_e32 v85, v73, v85
	global_load_dwordx4 v[4:7], v[244:245], off offset:0x840
	s_waitcnt lgkmcnt(0)
	v_mfma_f32_16x16x32_bf16 v[222:225], v[224:227], v[228:231], v[220:223]
	ds_read_b128 v[226:229], v184 offset:384
	s_nop 1
	v_add_u32_e32 v220, v151, v160
	ds_read_b128 v[230:233], v220
	global_load_dwordx4 v[24:27], v[250:251], off offset:0
	s_waitcnt lgkmcnt(0)
	v_mfma_f32_16x16x32_bf16 v[222:225], v[226:229], v[230:233], v[222:225]
	ds_read_b128 v[226:229], v184 offset:448
	v_add_u32_e32 v221, v151, v161
	ds_read_b128 v[230:233], v221
	v_mul_f32_e32 v74, v74, v90
	v_mul_f32_e32 v75, v75, v91
	v_mul_f32_e32 v72, v72, v88
	v_mul_f32_e32 v73, v73, v89
	v_mfma_f32_16x16x32_bf16 v[84:87], v[64:67], v[100:103], v[84:87]
	s_mov_b32 s47, s9
	v_mfma_f32_16x16x32_bf16 v[64:67], v[64:67], v[96:99], v[72:75]
	global_load_dwordx4 v[12:15], v[250:251], off offset:64
	s_waitcnt lgkmcnt(0)
	v_mfma_f32_16x16x32_bf16 v[222:225], v[226:229], v[230:233], v[222:225]
	v_mfma_f32_16x16x32_bf16 v[88:91], v[68:71], v[92:95], v[64:67]
	s_nop 4
	v_mul_f32_e64 v66, v62, v82
	v_mul_f32_e64 v67, v63, v83
	v_mul_f32_e32 v64, v60, v80
	v_mul_f32_e32 v65, v61, v81
	v_mul_f32_e32 v62, v62, v78
	v_mul_f32_e32 v63, v63, v79
	v_mul_f32_e32 v60, v60, v76
	v_mul_f32_e32 v61, v61, v77
	v_mfma_f32_16x16x32_bf16 v[64:67], v[56:59], v[100:103], v[64:67]
	v_cvt_pk_bf16_f32 v222, v222, v223
	v_cvt_pk_bf16_f32 v223, v224, v225
	v_lshl_add_u64 v[224:225], v[144:145], 0, s[46:47]
	v_mfma_f32_16x16x32_bf16 v[56:59], v[56:59], v[96:99], v[60:63]
	v_lshlrev_b64 v[224:225], 6, v[224:225]
	v_lshl_add_u64 v[224:225], v[146:147], 0, v[224:225]
	global_store_dwordx2 v[224:225], v[222:223], off
	v_mfma_f32_16x16x32_bf16 v[84:87], v[68:71], v[104:107], v[84:87]
	s_waitcnt lgkmcnt(0)
	s_barrier
	v_mfma_f32_16x16x32_bf16 v[80:83], v[52:55], v[104:107], v[64:67]
	v_mfma_f32_16x16x32_bf16 v[76:79], v[52:55], v[92:95], v[56:59]
	s_nop 4
	v_cvt_pk_bf16_f32 v52, v84, v85
	v_cvt_pk_bf16_f32 v53, v86, v87
	ds_write_b64 v185, v[52:53]
	v_cvt_pk_bf16_f32 v52, v88, v89
	v_cvt_pk_bf16_f32 v53, v90, v91
	ds_write_b64 v185, v[52:53] offset:8448
	v_cvt_pk_bf16_f32 v52, v80, v81
	v_cvt_pk_bf16_f32 v53, v82, v83
	ds_write_b64 v186, v[52:53]
	v_cvt_pk_bf16_f32 v52, v76, v77
	v_cvt_pk_bf16_f32 v53, v78, v79
	ds_write_b64 v186, v[52:53] offset:8448
	s_waitcnt vmcnt(14) lgkmcnt(0)
	s_barrier
	s_add_i32 s87, s87, -3
	s_cmpk_gt_u32 s93, 0xf8
	s_mov_b32 s47, s93
	s_cbranch_scc1 .LBB0_376

.LBB0_372:
	s_or_b64 exec, exec, s[54:55]
	s_lshl_b64 s[54:55], s[52:53], 8
	v_lshl_add_u64 v[52:53], s[54:55], 0, v[114:115]
	v_lshlrev_b64 v[52:53], 7, v[52:53]
	v_lshl_add_u64 v[244:245], v[138:139], 0, v[52:53]
	s_lshl_b64 s[52:53], s[52:53], 10
	v_lshl_add_u64 v[250:251], v[140:141], 0, s[52:53]
	v_add_u32_e32 v197, v148, v152
	ds_read_b128 v[92:95], v197 offset:32768
	ds_read_b128 v[96:99], v197 offset:34816
	v_add_u32_e32 v196, v149, v152
	v_add_u32_e32 v198, v148, v153
	ds_read_b128 v[104:107], v196 offset:36864
	ds_read_b128 v[200:203], v198 offset:32768
	ds_read_b128 v[208:211], v198 offset:34816
	v_add_u32_e32 v195, v149, v153
	s_mov_b32 m0, s92
	s_nop 0
	global_load_lds_dwordx4 v[234:235], off
	s_mov_b32 m0, s89
	s_nop 0
	global_load_lds_dwordx4 v[236:237], off
	s_waitcnt lgkmcnt(0)
	v_cndmask_b32_e64 v103, v99, v95, s[42:43]
	v_cndmask_b32_e64 v102, v98, v94, s[42:43]
	v_cndmask_b32_e64 v101, v97, v93, s[42:43]
	v_cndmask_b32_e64 v100, v96, v92, s[42:43]
	ds_read_b128 v[188:191], v195 offset:36864
	ds_read_b128 v[212:215], v184
	v_mfma_f32_16x16x32_bf16 v[100:103], v[100:103], v[104:107], 0
	v_cndmask_b32_e64 v107, v211, v203, s[42:43]
	v_cndmask_b32_e64 v106, v210, v202, s[42:43]
	v_cndmask_b32_e64 v105, v209, v201, s[42:43]
	v_cndmask_b32_e64 v104, v208, v200, s[42:43]
	v_add_u32_e32 v194, v150, v154
	ds_read_b128 v[216:219], v194
	s_mov_b32 m0, s90
	s_nop 0
	global_load_lds_dwordx4 v[238:239], off
	s_mov_b32 m0, s91
	s_nop 0
	global_load_lds_dwordx4 v[240:241], off
	s_waitcnt lgkmcnt(0)
	v_mfma_f32_16x16x32_bf16 v[100:103], v[104:107], v[188:191], v[100:103]
	ds_read_b128 v[104:107], v184 offset:64
	v_add_u32_e32 v193, v150, v155
	ds_read_b128 v[188:191], v193
	v_mfma_f32_16x16x32_bf16 v[100:103], v[212:215], v[216:219], v[100:103]
	ds_read_b128 v[212:215], v184 offset:128
	v_add_u32_e32 v192, v150, v156
	ds_read_b128 v[216:219], v192
	s_mov_b32 m0, s88
	s_nop 0
	global_load_lds_dwordx4 v[242:243], off
	global_load_dwordx4 v[64:67], v[244:245], off offset:0
	s_waitcnt lgkmcnt(0)
	v_mfma_f32_16x16x32_bf16 v[100:103], v[104:107], v[188:191], v[100:103]
	ds_read_b128 v[104:107], v184 offset:192
	v_add_u32_e32 v191, v150, v157
	ds_read_b128 v[220:223], v191
	v_mfma_f32_16x16x32_bf16 v[100:103], v[212:215], v[216:219], v[100:103]
	ds_read_b128 v[212:215], v184 offset:256
	v_add_u32_e32 v188, v150, v158
	ds_read_b128 v[216:219], v188
	global_load_dwordx4 v[68:71], v[244:245], off offset:64
	global_load_dwordx4 v[56:59], v[244:245], off offset:0x800
	s_waitcnt lgkmcnt(0)
	v_mfma_f32_16x16x32_bf16 v[100:103], v[104:107], v[220:223], v[100:103]
	ds_read_b128 v[104:107], v184 offset:320
	v_add_u32_e32 v187, v150, v159
	ds_read_b128 v[220:223], v187
	v_mfma_f32_16x16x32_bf16 v[100:103], v[212:215], v[216:219], v[100:103]
	ds_read_b128 v[212:215], v184 offset:384
	v_add_u32_e32 v189, v150, v160
	ds_read_b128 v[216:219], v189
	global_load_dwordx4 v[52:55], v[244:245], off offset:0x840
	global_load_dwordx4 v[72:75], v[250:251], off offset:0
	s_waitcnt lgkmcnt(0)
	v_mfma_f32_16x16x32_bf16 v[100:103], v[104:107], v[220:223], v[100:103]
	ds_read_b128 v[104:107], v184 offset:448
	v_mul_f32_e32 v86, v50, v86
	v_mul_f32_e32 v87, v51, v87
	v_mul_f32_e32 v84, v48, v84
	v_mul_f32_e32 v85, v49, v85
	v_mul_f32_e32 v50, v50, v90
	v_mul_f32_e32 v51, v51, v91
	v_mul_f32_e32 v48, v48, v88
	v_mul_f32_e32 v49, v49, v89
	v_mfma_f32_16x16x32_bf16 v[84:87], v[44:47], v[92:95], v[84:87]
	v_add_u32_e32 v190, v150, v161
	s_add_i32 s93, s47, 3
	s_add_i32 s8, s87, 4
	v_mfma_f32_16x16x32_bf16 v[44:47], v[44:47], v[96:99], v[48:51]
	s_and_b64 s[52:53], s[30:31], exec
	s_cselect_b32 s8, s93, s8
	s_lshl_b32 s8, s8, 6
	v_mfma_f32_16x16x32_bf16 v[100:103], v[212:215], v[216:219], v[100:103]
	ds_read_b128 v[212:215], v190
	v_mfma_f32_16x16x32_bf16 v[84:87], v[40:43], v[200:203], v[84:87]
	v_mfma_f32_16x16x32_bf16 v[88:91], v[40:43], v[208:211], v[44:47]
	v_mul_f32_e64 v42, v38, v82
	v_mul_f32_e64 v43, v39, v83
	v_mul_f32_e32 v40, v36, v80
	v_mul_f32_e32 v41, v37, v81
	v_mul_f32_e32 v38, v38, v78
	v_mul_f32_e32 v39, v39, v79
	v_mul_f32_e32 v36, v36, v76
	v_mul_f32_e32 v37, v37, v77
	v_mfma_f32_16x16x32_bf16 v[40:43], v[32:35], v[92:95], v[40:43]
	global_load_dwordx4 v[60:63], v[250:251], off offset:64
	s_waitcnt lgkmcnt(0)
	v_mfma_f32_16x16x32_bf16 v[100:103], v[104:107], v[212:215], v[100:103]
	v_mfma_f32_16x16x32_bf16 v[32:35], v[32:35], v[96:99], v[36:39]
	v_mfma_f32_16x16x32_bf16 v[80:83], v[28:31], v[200:203], v[40:43]
	s_nop 5
	v_cvt_pk_bf16_f32 v44, v100, v101
	v_cvt_pk_bf16_f32 v45, v102, v103
	v_lshl_add_u64 v[40:41], v[144:145], 0, s[8:9]
	v_lshlrev_b64 v[36:37], 6, v[40:41]
	v_lshl_add_u64 v[36:37], v[146:147], 0, v[36:37]
	v_mfma_f32_16x16x32_bf16 v[76:79], v[28:31], v[208:211], v[32:35]
	global_store_dwordx2 v[36:37], v[44:45], off
	v_cvt_pk_bf16_f32 v28, v84, v85
	v_cvt_pk_bf16_f32 v29, v86, v87
	s_waitcnt lgkmcnt(0)
	s_barrier
	ds_write_b64 v185, v[28:29]
	v_cvt_pk_bf16_f32 v28, v88, v89
	v_cvt_pk_bf16_f32 v29, v90, v91
	ds_write_b64 v185, v[28:29] offset:8448
	v_cvt_pk_bf16_f32 v28, v80, v81
	v_cvt_pk_bf16_f32 v29, v82, v83
	ds_write_b64 v186, v[28:29]
	v_cvt_pk_bf16_f32 v28, v76, v77
	v_cvt_pk_bf16_f32 v29, v78, v79
	ds_write_b64 v186, v[28:29] offset:8448
	s_waitcnt vmcnt(14) lgkmcnt(0)
	s_barrier
	s_add_i32 s8, s87, 1
	s_add_i32 s54, s47, 6
	s_and_b64 s[52:53], s[30:31], exec
	s_cselect_b32 s8, s54, s8
	s_lshl_b32 s52, s8, 6
	s_add_i32 s52, s52, s71
	s_ashr_i32 s53, s52, 31
	s_lshl_b64 s[52:53], s[52:53], 11
	s_add_u32 s52, s83, s52
	s_addc_u32 s53, s86, s53
	v_lshl_add_u64 v[234:235], v[122:123], 1, s[52:53]
	v_lshl_add_u64 v[236:237], v[124:125], 1, s[52:53]
	v_lshl_add_u64 v[238:239], v[126:127], 1, s[52:53]
	v_lshl_add_u64 v[240:241], v[128:129], 1, s[52:53]
	s_add_i32 s52, s8, s68
	s_ashr_i32 s53, s52, 31
	s_lshl_b64 s[54:55], s[52:53], 13
	v_lshl_add_u64 v[242:243], v[136:137], 0, s[54:55]
	s_and_saveexec_b64 s[54:55], s[38:39]
	s_cbranch_execz .LBB0_374
	s_lshl_b64 s[94:95], s[52:53], 16
	v_lshl_add_u64 v[28:29], v[142:143], 0, s[94:95]
	s_add_i32 m0, s66, 0x8000
	s_nop 0
	global_load_lds_dwordx4 v[28:29], off
.LBB0_374:
	s_or_b64 exec, exec, s[54:55]
	s_lshl_b64 s[54:55], s[52:53], 8
	v_lshl_add_u64 v[28:29], s[54:55], 0, v[114:115]
	v_lshlrev_b64 v[28:29], 7, v[28:29]
	v_lshl_add_u64 v[244:245], v[138:139], 0, v[28:29]
	s_lshl_b64 s[52:53], s[52:53], 10
	v_lshl_add_u64 v[250:251], v[140:141], 0, s[52:53]
	v_add_u32_e32 v199, v162, v117
	v_add_u32_e32 v200, v162, v119
	ds_read_b128 v[104:107], v199
	ds_read_b128 v[96:99], v200
	v_add_u32_e32 v201, v163, v117
	v_add_u32_e32 v202, v163, v119
	v_add_u32_e32 v203, v162, v113
	ds_read_b128 v[100:103], v201
	ds_read_b128 v[92:95], v202
	s_mov_b32 m0, s64
	s_nop 0
	global_load_lds_dwordx4 v[234:235], off
	s_mov_b32 m0, s73
	s_nop 0
	global_load_lds_dwordx4 v[236:237], off
	s_waitcnt lgkmcnt(0)
	v_cndmask_b32_e64 v211, v99, v107, s[42:43]
	v_cndmask_b32_e64 v210, v98, v106, s[42:43]
	v_cndmask_b32_e64 v209, v97, v105, s[42:43]
	v_cndmask_b32_e64 v208, v96, v104, s[42:43]
	ds_read_b128 v[212:215], v203 offset:36864
	v_add_u32_e32 v207, v163, v113
	ds_read_b128 v[216:219], v207 offset:36864
	s_mov_b32 m0, s74
	s_nop 0
	global_load_lds_dwordx4 v[238:239], off
	s_waitcnt lgkmcnt(0)
	v_mfma_f32_16x16x32_bf16 v[208:211], v[208:211], v[212:215], 0
	v_cndmask_b32_e64 v215, v95, v103, s[42:43]
	v_cndmask_b32_e64 v214, v94, v102, s[42:43]
	v_cndmask_b32_e64 v213, v93, v101, s[42:43]
	v_cndmask_b32_e64 v212, v92, v100, s[42:43]
	v_mul_f32_e32 v86, v26, v86
	v_mul_f32_e32 v87, v27, v87
	v_mul_f32_e32 v84, v24, v84
	v_mul_f32_e32 v85, v25, v85
	v_mfma_f32_16x16x32_bf16 v[208:211], v[212:215], v[216:219], v[208:211]
	ds_read_b128 v[212:215], v184
	ds_read_b128 v[216:219], v194 offset:45056
	v_mul_f32_e32 v26, v26, v90
	v_mul_f32_e32 v27, v27, v91
	v_mul_f32_e32 v24, v24, v88
	v_mul_f32_e32 v25, v25, v89
	s_mov_b32 m0, s75
	s_nop 0
	global_load_lds_dwordx4 v[240:241], off
	s_waitcnt lgkmcnt(0)
	v_mfma_f32_16x16x32_bf16 v[208:211], v[212:215], v[216:219], v[208:211]
	ds_read_b128 v[212:215], v184 offset:64
	ds_read_b128 v[216:219], v193 offset:45056
	s_add_i32 s8, s47, 4
	s_add_i32 s54, s87, 3
	s_mov_b32 m0, s78
	s_nop 0
	global_load_lds_dwordx4 v[242:243], off
	s_waitcnt lgkmcnt(0)
	v_mfma_f32_16x16x32_bf16 v[208:211], v[212:215], v[216:219], v[208:211]
	ds_read_b128 v[212:215], v184 offset:128
	ds_read_b128 v[216:219], v192 offset:45056
	s_and_b64 s[52:53], s[30:31], exec
	s_cselect_b32 s8, s8, s54
	global_load_dwordx4 v[44:47], v[244:245], off offset:0
	s_waitcnt lgkmcnt(0)
	v_mfma_f32_16x16x32_bf16 v[208:211], v[212:215], v[216:219], v[208:211]
	ds_read_b128 v[212:215], v184 offset:192
	ds_read_b128 v[216:219], v191 offset:45056
	s_lshl_b32 s8, s8, 6
	global_load_dwordx4 v[40:43], v[244:245], off offset:64
	s_waitcnt lgkmcnt(0)
	v_mfma_f32_16x16x32_bf16 v[208:211], v[212:215], v[216:219], v[208:211]
	ds_read_b128 v[212:215], v184 offset:256
	ds_read_b128 v[216:219], v188 offset:45056
	global_load_dwordx4 v[32:35], v[244:245], off offset:0x800
	s_waitcnt lgkmcnt(0)
	v_mfma_f32_16x16x32_bf16 v[208:211], v[212:215], v[216:219], v[208:211]
	ds_read_b128 v[212:215], v184 offset:320
	ds_read_b128 v[216:219], v187 offset:45056
	global_load_dwordx4 v[28:31], v[244:245], off offset:0x840
	s_waitcnt lgkmcnt(0)
	v_mfma_f32_16x16x32_bf16 v[208:211], v[212:215], v[216:219], v[208:211]
	ds_read_b128 v[212:215], v184 offset:384
	ds_read_b128 v[216:219], v189 offset:45056
	global_load_dwordx4 v[48:51], v[250:251], off offset:0
	s_waitcnt lgkmcnt(0)
	v_mfma_f32_16x16x32_bf16 v[208:211], v[212:215], v[216:219], v[208:211]
	ds_read_b128 v[212:215], v184 offset:448
	ds_read_b128 v[216:219], v190 offset:45056
	v_mfma_f32_16x16x32_bf16 v[84:87], v[20:23], v[104:107], v[84:87]
	v_mfma_f32_16x16x32_bf16 v[20:23], v[20:23], v[96:99], v[24:27]
	global_load_dwordx4 v[36:39], v[250:251], off offset:64
	s_waitcnt lgkmcnt(0)
	v_mfma_f32_16x16x32_bf16 v[208:211], v[212:215], v[216:219], v[208:211]
	v_mfma_f32_16x16x32_bf16 v[84:87], v[16:19], v[100:103], v[84:87]
	v_mfma_f32_16x16x32_bf16 v[88:91], v[16:19], v[92:95], v[20:23]
	v_mul_f32_e64 v18, v14, v82
	v_mul_f32_e64 v19, v15, v83
	v_mul_f32_e32 v16, v12, v80
	v_mul_f32_e32 v17, v13, v81
	v_mul_f32_e32 v14, v14, v78
	v_mul_f32_e32 v15, v15, v79
	v_mul_f32_e32 v12, v12, v76
	v_mul_f32_e32 v13, v13, v77
	v_mfma_f32_16x16x32_bf16 v[16:19], v[8:11], v[104:107], v[16:19]
	v_cvt_pk_bf16_f32 v208, v208, v209
	v_cvt_pk_bf16_f32 v209, v210, v211
	v_lshl_add_u64 v[210:211], v[144:145], 0, s[8:9]
	v_mfma_f32_16x16x32_bf16 v[8:11], v[8:11], v[96:99], v[12:15]
	v_lshlrev_b64 v[210:211], 6, v[210:211]
	v_lshl_add_u64 v[210:211], v[146:147], 0, v[210:211]
	global_store_dwordx2 v[210:211], v[208:209], off
	v_mfma_f32_16x16x32_bf16 v[80:83], v[4:7], v[100:103], v[16:19]
	s_waitcnt lgkmcnt(0)
	s_barrier
	v_mfma_f32_16x16x32_bf16 v[76:79], v[4:7], v[92:95], v[8:11]
	v_cvt_pk_bf16_f32 v4, v84, v85
	v_cvt_pk_bf16_f32 v5, v86, v87
	ds_write_b64 v185, v[4:5]
	v_cvt_pk_bf16_f32 v4, v88, v89
	v_cvt_pk_bf16_f32 v5, v90, v91
	ds_write_b64 v185, v[4:5] offset:8448
	v_cvt_pk_bf16_f32 v4, v80, v81
	v_cvt_pk_bf16_f32 v5, v82, v83
	ds_write_b64 v186, v[4:5]
	v_cvt_pk_bf16_f32 v4, v76, v77
	v_cvt_pk_bf16_f32 v5, v78, v79
	ds_write_b64 v186, v[4:5] offset:8448
	s_waitcnt vmcnt(14) lgkmcnt(0)
	s_barrier
	s_add_i32 s8, s47, 7
	s_and_b64 s[52:53], s[30:31], exec
	s_cselect_b32 s8, s8, s87
	s_lshl_b32 s47, s8, 6
	s_add_i32 s52, s47, s71
	s_ashr_i32 s53, s52, 31
	s_lshl_b64 s[52:53], s[52:53], 11
	s_add_u32 s52, s83, s52
	s_addc_u32 s53, s86, s53
	v_lshl_add_u64 v[234:235], v[122:123], 1, s[52:53]
	v_lshl_add_u64 v[236:237], v[124:125], 1, s[52:53]
	v_lshl_add_u64 v[238:239], v[126:127], 1, s[52:53]
	v_lshl_add_u64 v[240:241], v[128:129], 1, s[52:53]
	s_add_i32 s52, s8, s68
	s_ashr_i32 s53, s52, 31
	s_lshl_b64 s[54:55], s[52:53], 13
	v_lshl_add_u64 v[242:243], v[136:137], 0, s[54:55]
	s_and_saveexec_b64 s[54:55], s[38:39]
	s_cbranch_execz .LBB0_369
	s_lshl_b64 s[94:95], s[52:53], 16
	s_add_i32 s8, s65, 0
	v_lshl_add_u64 v[4:5], v[142:143], 0, s[94:95]
	s_add_i32 m0, s8, 0x13000
	s_nop 0
	global_load_lds_dwordx4 v[4:5], off
	s_branch .LBB0_369

; DI void gla_scan_phase(LAS unsigned char* lds, LAS unsigned char* sml, const bf16_t* QF, const bf16_t* QB, const bf16_t* KEF, const bf16_t* KEB, const bf16_t* VT, const float* DEC, const bf16_t* PF, const bf16_t* PB, bf16_t* OF, bf16_t* OB) {
;     ...
;     SCAN_STEP(NCH - 4, 0, R0, 2, R2, 1, 14); SCAN_STEP(NCH - 3, 1, R1, 0, R0, 1, 14); SCAN_STEP(NCH - 2, 2, R2, 1, R1, 0, 2); SCAN_STEP(NCH - 1, 0, R0, 2, R2, 0, 0);
.LBB0_378:
	s_or_b64 exec, exec, s[52:53]
	s_lshl_b64 s[52:53], s[46:47], 8
	v_lshl_add_u64 v[52:53], s[52:53], 0, v[114:115]
	v_lshlrev_b64 v[52:53], 7, v[52:53]
	v_lshl_add_u64 v[52:53], s[44:45], 0, v[52:53]
	s_lshl_b64 s[46:47], s[46:47], 10
	v_lshl_add_u64 v[60:61], v[52:53], 0, v[2:3]
	global_load_dwordx4 v[68:71], v[60:61], off offset:0
	s_add_u32 s46, s76, s46
	global_load_dwordx4 v[64:67], v[60:61], off offset:64
	s_addc_u32 s47, s77, s47
	global_load_dwordx4 v[52:55], v[60:61], off offset:0x800
	s_add_u32 s46, s46, s12
	global_load_dwordx4 v[56:59], v[60:61], off offset:0x840
	s_addc_u32 s47, s47, s13
	v_mov_b32_e32 v131, v3
	v_lshl_add_u64 v[92:93], s[46:47], 0, v[130:131]
	global_load_dwordx4 v[72:75], v[92:93], off offset:0
	global_load_dwordx4 v[60:63], v[92:93], off offset:64
	ds_read_b128 v[104:107], v197 offset:32768
	ds_read_b128 v[96:99], v197 offset:34816
	ds_read_b128 v[100:103], v198 offset:32768
	ds_read_b128 v[92:95], v198 offset:34816
	ds_read_b128 v[140:143], v196 offset:36864
	ds_read_b128 v[144:147], v195 offset:36864
	s_waitcnt lgkmcnt(0)
	v_cndmask_b32_e64 v139, v99, v107, s[42:43]
	v_cndmask_b32_e64 v138, v98, v106, s[42:43]
	v_cndmask_b32_e64 v137, v97, v105, s[42:43]
	v_cndmask_b32_e64 v136, v96, v104, s[42:43]
	v_mul_f32_e32 v86, v50, v86
	v_mul_f32_e32 v87, v51, v87
	v_mul_f32_e32 v84, v48, v84
	v_mul_f32_e32 v85, v49, v85
	v_mfma_f32_16x16x32_bf16 v[136:139], v[136:139], v[140:143], 0
	v_cndmask_b32_e64 v143, v95, v103, s[42:43]
	v_cndmask_b32_e64 v142, v94, v102, s[42:43]
	v_cndmask_b32_e64 v141, v93, v101, s[42:43]
	v_cndmask_b32_e64 v140, v92, v100, s[42:43]
	v_mul_f32_e32 v50, v50, v90
	v_mul_f32_e32 v51, v51, v91
	v_mul_f32_e32 v48, v48, v88
	v_mul_f32_e32 v49, v49, v89
	v_mfma_f32_16x16x32_bf16 v[136:139], v[140:143], v[144:147], v[136:139]
	ds_read_b128 v[140:143], v184
	ds_read_b128 v[144:147], v194
	s_and_b64 s[46:47], s[30:31], exec
	s_movk_i32 s46, 0x3f00
	s_waitcnt lgkmcnt(0)
	v_mfma_f32_16x16x32_bf16 v[136:139], v[140:143], v[144:147], v[136:139]
	ds_read_b128 v[140:143], v184 offset:64
	ds_read_b128 v[144:147], v193
	s_cselect_b32 s46, s46, 0xc0
	v_mov_b32_e32 v133, s22
	s_waitcnt lgkmcnt(0)
	v_mfma_f32_16x16x32_bf16 v[136:139], v[140:143], v[144:147], v[136:139]
	ds_read_b128 v[140:143], v184 offset:128
	ds_read_b128 v[144:147], v192
	s_waitcnt lgkmcnt(0)
	v_mfma_f32_16x16x32_bf16 v[136:139], v[140:143], v[144:147], v[136:139]
	ds_read_b128 v[140:143], v184 offset:192
	ds_read_b128 v[144:147], v191
	s_waitcnt lgkmcnt(0)
	v_mfma_f32_16x16x32_bf16 v[136:139], v[140:143], v[144:147], v[136:139]
	ds_read_b128 v[140:143], v184 offset:256
	ds_read_b128 v[144:147], v188
	s_waitcnt lgkmcnt(0)
	v_mfma_f32_16x16x32_bf16 v[136:139], v[140:143], v[144:147], v[136:139]
	ds_read_b128 v[140:143], v184 offset:320
	ds_read_b128 v[144:147], v187
	s_waitcnt lgkmcnt(0)
	v_mfma_f32_16x16x32_bf16 v[136:139], v[140:143], v[144:147], v[136:139]
	ds_read_b128 v[140:143], v184 offset:384
	ds_read_b128 v[144:147], v189
	s_waitcnt lgkmcnt(0)
	v_mfma_f32_16x16x32_bf16 v[136:139], v[140:143], v[144:147], v[136:139]
	ds_read_b128 v[140:143], v184 offset:448
	ds_read_b128 v[144:147], v190
	v_mfma_f32_16x16x32_bf16 v[84:87], v[44:47], v[104:107], v[84:87]
	v_mfma_f32_16x16x32_bf16 v[44:47], v[44:47], v[96:99], v[48:51]
	s_waitcnt lgkmcnt(0)
	v_mfma_f32_16x16x32_bf16 v[136:139], v[140:143], v[144:147], v[136:139]
	v_mfma_f32_16x16x32_bf16 v[84:87], v[40:43], v[100:103], v[84:87]
	v_mfma_f32_16x16x32_bf16 v[88:91], v[40:43], v[92:95], v[44:47]
	v_mul_f32_e64 v42, v38, v82
	v_mul_f32_e64 v43, v39, v83
	v_mul_f32_e32 v40, v36, v80
	v_mul_f32_e32 v41, v37, v81
	v_mul_f32_e32 v38, v38, v78
	v_mul_f32_e32 v39, v39, v79
	v_mul_f32_e32 v36, v36, v76
	v_mul_f32_e32 v37, v37, v77
	v_mfma_f32_16x16x32_bf16 v[40:43], v[32:35], v[104:107], v[40:43]
	v_cvt_pk_bf16_f32 v140, v136, v137
	v_or3_b32 v137, 0, 0, s23
	v_or3_b32 v136, s46, v112, v133
	v_mfma_f32_16x16x32_bf16 v[32:35], v[32:35], v[96:99], v[36:39]
	v_cvt_pk_bf16_f32 v141, v138, v139
	v_lshlrev_b64 v[138:139], 6, v[136:137]
	v_lshl_add_u64 v[138:139], s[18:19], 0, v[138:139]
	v_lshl_add_u64 v[138:139], s[2:3], 1, v[138:139]
	v_mov_b32_e32 v133, v3
	v_mfma_f32_16x16x32_bf16 v[80:83], v[28:31], v[100:103], v[40:43]
	v_lshl_add_u64 v[138:139], v[138:139], 0, v[132:133]
	global_store_dwordx2 v[138:139], v[140:141], off
	s_waitcnt lgkmcnt(0)
	v_mfma_f32_16x16x32_bf16 v[76:79], v[28:31], v[92:95], v[32:35]
	v_cvt_pk_bf16_f32 v28, v84, v85
	v_cvt_pk_bf16_f32 v29, v86, v87
	s_barrier
	ds_write_b64 v185, v[28:29]
	v_cvt_pk_bf16_f32 v28, v88, v89
	v_cvt_pk_bf16_f32 v29, v90, v91
	ds_write_b64 v185, v[28:29] offset:8448
	v_cvt_pk_bf16_f32 v28, v80, v81
	v_cvt_pk_bf16_f32 v29, v82, v83
	ds_write_b64 v186, v[28:29]
	v_cvt_pk_bf16_f32 v28, v76, v77
	v_cvt_pk_bf16_f32 v29, v78, v79
	ds_write_b64 v186, v[28:29] offset:8448
	s_waitcnt vmcnt(14) lgkmcnt(0)
	s_barrier
	s_cselect_b32 s53, 0xff, 0
	s_lshl_b32 s52, s53, 6
	s_or_b32 s46, s71, s52
	s_ashr_i32 s47, s46, 31
	s_lshl_b64 s[46:47], s[46:47], 11
	s_add_u32 s46, s70, s46
	s_addc_u32 s47, s69, s47
	s_add_u32 s46, s46, s72
	s_addc_u32 s47, s47, 0
	s_mov_b32 m0, s64
	v_lshl_add_u64 v[28:29], v[122:123], 1, s[46:47]
	global_load_lds_dwordx4 v[28:29], off
	v_lshl_add_u64 v[28:29], v[124:125], 1, s[46:47]
	s_mov_b32 m0, s73
	s_nop 0
	global_load_lds_dwordx4 v[28:29], off
	v_lshl_add_u64 v[28:29], v[126:127], 1, s[46:47]
	s_mov_b32 m0, s74
	s_nop 0
	global_load_lds_dwordx4 v[28:29], off
	v_lshl_add_u64 v[28:29], v[128:129], 1, s[46:47]
	s_or_b32 s46, s68, s53
	s_ashr_i32 s47, s46, 31
	s_lshl_b64 s[54:55], s[46:47], 13
	s_add_u32 s36, s36, s54
	s_mov_b32 m0, s75
	s_addc_u32 s37, s37, s55
	global_load_lds_dwordx4 v[28:29], off
	v_lshl_add_u64 v[28:29], v[108:109], 1, s[36:37]
	s_mov_b32 m0, s78
	s_nop 0
	global_load_lds_dwordx4 v[28:29], off
	s_and_saveexec_b64 s[36:37], s[38:39]
	s_mov_b32 s83, 0x26e00000
	s_cbranch_execz .LBB0_358
	s_lshl_b64 s[54:55], s[46:47], 16
	s_add_u32 s54, s0, s54
	s_addc_u32 s55, s1, s55
	v_lshl_add_u64 v[28:29], v[134:135], 1, s[54:55]
	v_lshl_add_u64 v[28:29], v[110:111], 1, v[28:29]
	s_add_i32 m0, s66, 0x8000
	s_nop 0
	global_load_lds_dwordx4 v[28:29], off
	s_branch .LBB0_358

; DI unsigned cvt_pk_bf16(float lo, float hi) { const f32x2 v = {lo, hi}; const bf16x2_t r = __builtin_convertvector(v, bf16x2_t); return __builtin_bit_cast(unsigned, r); }
; DI float bf_lo(unsigned w) { return __uint_as_float(w << 16); }
; DI float bf_hi(unsigned w) { return __uint_as_float(w & 0xffff0000u); }
; DI float silu_f(float g) { return g * __builtin_amdgcn_rcpf(1.0f + __expf(-g)); }
; DI void gla_norm_phase(const bf16_t* OF, const bf16_t* OB, bf16_t* R, const float* hgain) {
;     ...
;   for (int row = gw; row < MTOK; row += nw) {
; #pragma unroll
;     for (int h = 0; h < 4; ++h) {
;       const size_t off = (size_t)row * GV + h * HV + lane * 8;
;       const size_t ooff = ((size_t)(((row >> 14) * 4 + h) * 16 + (lane >> 2)) * SEQ + (row & (SEQ - 1))) * 32 + (lane & 3) * 8;
;       const u32x4 a = *(const u32x4*)(OF + ooff), c = *(const u32x4*)(OB + ooff);
;       bf16_t* rp = R + off;
;       const u32x4 rv = *(const u32x4*)rp;
;       float o[8];
;       o[0] = bf_lo(a.x) + bf_lo(c.x); o[1] = bf_hi(a.x) + bf_hi(c.x); o[2] = bf_lo(a.y) + bf_lo(c.y); o[3] = bf_hi(a.y) + bf_hi(c.y);
;       o[4] = bf_lo(a.z) + bf_lo(c.z); o[5] = bf_hi(a.z) + bf_hi(c.z); o[6] = bf_lo(a.w) + bf_lo(c.w); o[7] = bf_hi(a.w) + bf_hi(c.w);
;       float ss = 0.f;
; #pragma unroll
;       for (int e = 0; e < 8; ++e) ss += o[e] * o[e];
;       ss = wave_sum(ss);
;       const float rs = __frsqrt_rn(ss * (1.0f / HV) + EPS);
;       u32x4 w;
;       w.x = cvt_pk_bf16(o[0] * rs * hg0[0] * pg8::silu_f(bf_lo(rv.x)), o[1] * rs * hg0[1] * pg8::silu_f(bf_hi(rv.x)));
;       w.y = cvt_pk_bf16(o[2] * rs * hg0[2] * pg8::silu_f(bf_lo(rv.y)), o[3] * rs * hg0[3] * pg8::silu_f(bf_hi(rv.y)));
;       w.z = cvt_pk_bf16(o[4] * rs * hg1[0] * pg8::silu_f(bf_lo(rv.z)), o[5] * rs * hg1[1] * pg8::silu_f(bf_hi(rv.z)));
;       w.w = cvt_pk_bf16(o[6] * rs * hg1[2] * pg8::silu_f(bf_lo(rv.w)), o[7] * rs * hg1[3] * pg8::silu_f(bf_hi(rv.w)));
;       *(u32x4*)rp = w;
;     }
.LBB0_430:
	v_ashrrev_i32_e32 v13, 8, v20
	v_and_b32_e32 v21, 0xffffffc0, v13
	s_mov_b32 s8, 0x7ffe0
	v_or_b32_e32 v24, v21, v2
	v_and_or_b32 v12, v28, s8, v26
	v_ashrrev_i32_e32 v25, 31, v24
	v_lshlrev_b64 v[16:17], 20, v[24:25]
	v_lshlrev_b32_e32 v25, 1, v12
	v_or_b32_e32 v16, v16, v25
	v_lshl_add_u64 v[12:13], s[2:3], 0, v[16:17]
	global_load_dwordx4 v[12:15], v[12:13], off
	v_lshl_add_u64 v[16:17], s[12:13], 0, v[16:17]
	global_load_dwordx4 v[16:19], v[16:17], off
	s_nop 0
	global_load_dwordx4 v[30:33], v[22:23], off
	v_or_b32_e32 v60, 16, v24
	v_ashrrev_i32_e32 v61, 31, v60
	v_lshlrev_b64 v[62:63], 20, v[60:61]
	v_or_b32_e32 v62, v62, v25
	v_lshl_add_u64 v[60:61], s[2:3], 0, v[62:63]
	global_load_dwordx4 v[48:51], v[60:61], off
	v_lshl_add_u64 v[62:63], s[12:13], 0, v[62:63]
	global_load_dwordx4 v[52:55], v[62:63], off
	s_nop 0
	global_load_dwordx4 v[56:59], v[22:23], off offset:1024
	v_or_b32_e32 v60, 32, v24
	v_ashrrev_i32_e32 v61, 31, v60
	v_lshlrev_b64 v[62:63], 20, v[60:61]
	v_or_b32_e32 v62, v62, v25
	v_lshl_add_u64 v[60:61], s[2:3], 0, v[62:63]
	global_load_dwordx4 v[64:67], v[60:61], off
	v_lshl_add_u64 v[62:63], s[12:13], 0, v[62:63]
	global_load_dwordx4 v[68:71], v[62:63], off
	s_nop 0
	global_load_dwordx4 v[72:75], v[22:23], off offset:2048
	v_or_b32_e32 v60, v21, v27
	v_ashrrev_i32_e32 v61, 31, v60
	v_lshlrev_b64 v[62:63], 20, v[60:61]
	v_or_b32_e32 v62, v62, v25
	v_lshl_add_u64 v[60:61], s[2:3], 0, v[62:63]
	global_load_dwordx4 v[80:83], v[60:61], off
	v_lshl_add_u64 v[62:63], s[12:13], 0, v[62:63]
	global_load_dwordx4 v[84:87], v[62:63], off
	s_nop 0
	global_load_dwordx4 v[88:91], v[22:23], off offset:3072
	v_add_u32_e32 v20, s26, v20
	v_cmp_lt_i32_e32 vcc, s36, v20
	v_add_u32_e32 v28, s27, v28
	s_or_b64 s[18:19], vcc, s[18:19]
	s_waitcnt vmcnt(11)
	v_lshlrev_b32_e32 v34, 16, v15
	v_and_b32_e32 v35, 0xffff0000, v15
	v_lshlrev_b32_e32 v38, 16, v14
	v_and_b32_e32 v39, 0xffff0000, v14
	s_waitcnt vmcnt(10)
	v_lshlrev_b32_e32 v14, 16, v18
	v_and_b32_e32 v15, 0xffff0000, v18
	v_pk_add_f32 v[14:15], v[38:39], v[14:15]
	s_waitcnt vmcnt(9)
	v_lshlrev_b32_e32 v38, 16, v32
	v_mul_f32_e32 v29, 0xbfb8aa3b, v38
	v_exp_f32_e32 v29, v29
	v_and_b32_e32 v39, 0xffff0000, v32
	v_lshlrev_b32_e32 v44, 16, v31
	v_and_b32_e32 v45, 0xffff0000, v31
	v_add_f32_e32 v29, 1.0, v29
	v_rcp_f32_e32 v40, v29
	v_mul_f32_e32 v29, 0xbfb8aa3b, v39
	v_exp_f32_e32 v29, v29
	v_lshlrev_b32_e32 v42, 16, v17
	v_and_b32_e32 v43, 0xffff0000, v17
	v_lshlrev_b32_e32 v36, 16, v19
	v_add_f32_e32 v29, 1.0, v29
	v_rcp_f32_e32 v41, v29
	v_and_b32_e32 v37, 0xffff0000, v19
	v_pk_mul_f32 v[18:19], v[14:15], v[14:15]
	v_pk_add_f32 v[34:35], v[34:35], v[36:37]
	v_pk_mul_f32 v[38:39], v[40:41], v[38:39]
	v_lshlrev_b32_e32 v40, 16, v13
	v_and_b32_e32 v41, 0xffff0000, v13
	v_mul_f32_e32 v13, 0xbfb8aa3b, v44
	v_exp_f32_e32 v13, v13
	v_pk_add_f32 v[40:41], v[40:41], v[42:43]
	v_pk_mul_f32 v[36:37], v[34:35], v[34:35]
	v_pk_mul_f32 v[42:43], v[40:41], v[40:41]
	v_add_f32_e32 v13, 1.0, v13
	v_rcp_f32_e32 v46, v13
	v_mul_f32_e32 v13, 0xbfb8aa3b, v45
	v_exp_f32_e32 v13, v13
	s_nop 0
	v_add_f32_e32 v13, 1.0, v13
	v_rcp_f32_e32 v47, v13
	v_and_b32_e32 v13, 0xffff0000, v16
	v_pk_mul_f32 v[44:45], v[46:47], v[44:45]
	v_lshlrev_b32_e32 v46, 16, v12
	v_and_b32_e32 v47, 0xffff0000, v12
	v_lshlrev_b32_e32 v12, 16, v16
	v_pk_add_f32 v[12:13], v[46:47], v[12:13]
	v_lshlrev_b32_e32 v46, 16, v30
	v_pk_mul_f32 v[16:17], v[12:13], v[12:13]
	v_mul_f32_e32 v29, 0xbfb8aa3b, v46
	v_add_f32_e32 v16, v16, v17
	v_add_f32_e32 v16, v42, v16
	v_add_f32_e32 v16, v43, v16
	v_add_f32_e32 v16, v18, v16
	v_add_f32_e32 v16, v19, v16
	v_add_f32_e32 v16, v36, v16
	v_exp_f32_e32 v29, v29
	v_add_f32_e32 v16, v37, v16
	v_and_b32_e32 v47, 0xffff0000, v30
	v_add_f32_e32 v29, 1.0, v29
	v_add_f32_dpp v16, v16, v16 quad_perm:[1,0,3,2] row_mask:0xf bank_mask:0xf bound_ctrl:1
	v_rcp_f32_e32 v30, v29
	v_mul_f32_e32 v29, 0xbfb8aa3b, v47
	v_add_f32_dpp v16, v16, v16 quad_perm:[2,3,0,1] row_mask:0xf bank_mask:0xf bound_ctrl:1
	v_exp_f32_e32 v29, v29
	s_nop 0
	v_add_f32_dpp v16, v16, v16 row_half_mirror row_mask:0xf bank_mask:0xf bound_ctrl:1
	v_add_f32_e32 v29, 1.0, v29
	s_nop 0
	v_add_f32_dpp v16, v16, v16 row_mirror row_mask:0xf bank_mask:0xf bound_ctrl:1
	v_rcp_f32_e32 v31, v29
	v_readlane_b32 s8, v16, 16
	v_readlane_b32 s25, v16, 48
	v_readlane_b32 s22, v16, 0
	v_readlane_b32 s23, v16, 32
	v_mov_b32_e32 v16, s8
	v_mov_b32_e32 v17, s25
	v_pk_add_f32 v[16:17], s[22:23], v[16:17]
	v_pk_mul_f32 v[30:31], v[30:31], v[46:47]
	v_add_f32_e32 v16, v16, v17
	v_fmamk_f32 v16, v16, 0x3b000000, v204
	v_rsq_f32_e32 v16, v16
	s_nop 0
	v_pk_mul_f32 v[12:13], v[12:13], v[16:17] op_sel_hi:[1,0]
	v_pk_mul_f32 v[18:19], v[40:41], v[16:17] op_sel_hi:[1,0]
	v_pk_mul_f32 v[12:13], v[4:5], v[12:13]
	v_pk_mul_f32 v[18:19], v[6:7], v[18:19]
	v_pk_mul_f32 v[14:15], v[14:15], v[16:17] op_sel_hi:[1,0]
	v_pk_mul_f32 v[12:13], v[30:31], v[12:13]
	v_pk_mul_f32 v[18:19], v[44:45], v[18:19]
	v_pk_mul_f32 v[14:15], v[8:9], v[14:15]
	v_cvt_pk_bf16_f32 v12, v12, v13
	v_cvt_pk_bf16_f32 v13, v18, v19
	v_pk_mul_f32 v[14:15], v[38:39], v[14:15]
	v_lshlrev_b32_e32 v18, 16, v33
	v_cvt_pk_bf16_f32 v14, v14, v15
	v_mul_f32_e32 v15, 0xbfb8aa3b, v18
	v_exp_f32_e32 v15, v15
	v_and_b32_e32 v19, 0xffff0000, v33
	v_pk_mul_f32 v[16:17], v[34:35], v[16:17] op_sel_hi:[1,0]
	v_add_f32_e32 v15, 1.0, v15
	v_rcp_f32_e32 v30, v15
	v_mul_f32_e32 v15, 0xbfb8aa3b, v19
	v_exp_f32_e32 v15, v15
	v_pk_mul_f32 v[16:17], v[10:11], v[16:17]
	v_add_f32_e32 v15, 1.0, v15
	v_rcp_f32_e32 v31, v15
	s_nop 0
	v_pk_mul_f32 v[18:19], v[30:31], v[18:19]
	s_nop 0
	v_pk_mul_f32 v[16:17], v[18:19], v[16:17]
	s_nop 0
	v_cvt_pk_bf16_f32 v15, v16, v17
	global_store_dwordx4 v[22:23], v[12:15], off
	s_nop 1
	s_waitcnt vmcnt(7)
; DI unsigned cvt_pk_bf16(float lo, float hi) { const f32x2 v = {lo, hi}; const bf16x2_t r = __builtin_convertvector(v, bf16x2_t); return __builtin_bit_cast(unsigned, r); }
; DI float bf_lo(unsigned w) { return __uint_as_float(w << 16); }
; DI float bf_hi(unsigned w) { return __uint_as_float(w & 0xffff0000u); }
; DI float silu_f(float g) { return g * __builtin_amdgcn_rcpf(1.0f + __expf(-g)); }
; DI void gla_norm_phase(const bf16_t* OF, const bf16_t* OB, bf16_t* R, const float* hgain) {
;     ...
;     for (int h = 0; h < 4; ++h) {
;       const size_t off = (size_t)row * GV + h * HV + lane * 8;
;       const size_t ooff = ((size_t)(((row >> 14) * 4 + h) * 16 + (lane >> 2)) * SEQ + (row & (SEQ - 1))) * 32 + (lane & 3) * 8;
;       const u32x4 a = *(const u32x4*)(OF + ooff), c = *(const u32x4*)(OB + ooff);
;       bf16_t* rp = R + off;
;       const u32x4 rv = *(const u32x4*)rp;
;       float o[8];
;       o[0] = bf_lo(a.x) + bf_lo(c.x); o[1] = bf_hi(a.x) + bf_hi(c.x); o[2] = bf_lo(a.y) + bf_lo(c.y); o[3] = bf_hi(a.y) + bf_hi(c.y);
;       o[4] = bf_lo(a.z) + bf_lo(c.z); o[5] = bf_hi(a.z) + bf_hi(c.z); o[6] = bf_lo(a.w) + bf_lo(c.w); o[7] = bf_hi(a.w) + bf_hi(c.w);
;       float ss = 0.f;
; #pragma unroll
;       for (int e = 0; e < 8; ++e) ss += o[e] * o[e];
;       ss = wave_sum(ss);
;       const float rs = __frsqrt_rn(ss * (1.0f / HV) + EPS);
;       u32x4 w;
;       w.x = cvt_pk_bf16(o[0] * rs * hg0[0] * pg8::silu_f(bf_lo(rv.x)), o[1] * rs * hg0[1] * pg8::silu_f(bf_hi(rv.x)));
;       w.y = cvt_pk_bf16(o[2] * rs * hg0[2] * pg8::silu_f(bf_lo(rv.y)), o[3] * rs * hg0[3] * pg8::silu_f(bf_hi(rv.y)));
;       w.z = cvt_pk_bf16(o[4] * rs * hg1[0] * pg8::silu_f(bf_lo(rv.z)), o[5] * rs * hg1[1] * pg8::silu_f(bf_hi(rv.z)));
;       w.w = cvt_pk_bf16(o[6] * rs * hg1[2] * pg8::silu_f(bf_lo(rv.w)), o[7] * rs * hg1[3] * pg8::silu_f(bf_hi(rv.w)));
;       *(u32x4*)rp = w;
;     }
	v_mov_b32_e32 v12, v48
	v_mov_b32_e32 v13, v49
	v_mov_b32_e32 v14, v50
	v_mov_b32_e32 v15, v51
	v_mov_b32_e32 v16, v52
	v_mov_b32_e32 v17, v53
	v_mov_b32_e32 v18, v54
	v_mov_b32_e32 v19, v55
	v_mov_b32_e32 v30, v56
	v_mov_b32_e32 v31, v57
	v_mov_b32_e32 v32, v58
	v_mov_b32_e32 v33, v59
	v_lshlrev_b32_e32 v34, 16, v15
	v_and_b32_e32 v35, 0xffff0000, v15
	v_lshlrev_b32_e32 v38, 16, v14
	v_and_b32_e32 v39, 0xffff0000, v14
	v_lshlrev_b32_e32 v14, 16, v18
	v_and_b32_e32 v15, 0xffff0000, v18
	v_pk_add_f32 v[14:15], v[38:39], v[14:15]
	v_lshlrev_b32_e32 v38, 16, v32
	v_mul_f32_e32 v29, 0xbfb8aa3b, v38
	v_exp_f32_e32 v29, v29
	v_and_b32_e32 v39, 0xffff0000, v32
	v_lshlrev_b32_e32 v44, 16, v31
	v_and_b32_e32 v45, 0xffff0000, v31
	v_add_f32_e32 v29, 1.0, v29
	v_rcp_f32_e32 v40, v29
	v_mul_f32_e32 v29, 0xbfb8aa3b, v39
	v_exp_f32_e32 v29, v29
	v_lshlrev_b32_e32 v42, 16, v17
	v_and_b32_e32 v43, 0xffff0000, v17
	v_lshlrev_b32_e32 v36, 16, v19
	v_add_f32_e32 v29, 1.0, v29
	v_rcp_f32_e32 v41, v29
	v_and_b32_e32 v37, 0xffff0000, v19
	v_pk_mul_f32 v[18:19], v[14:15], v[14:15]
	v_pk_add_f32 v[34:35], v[34:35], v[36:37]
	v_pk_mul_f32 v[38:39], v[40:41], v[38:39]
	v_lshlrev_b32_e32 v40, 16, v13
	v_and_b32_e32 v41, 0xffff0000, v13
	v_mul_f32_e32 v13, 0xbfb8aa3b, v44
	v_exp_f32_e32 v13, v13
	v_pk_add_f32 v[40:41], v[40:41], v[42:43]
	v_pk_mul_f32 v[36:37], v[34:35], v[34:35]
	v_pk_mul_f32 v[42:43], v[40:41], v[40:41]
	v_add_f32_e32 v13, 1.0, v13
	v_rcp_f32_e32 v46, v13
	v_mul_f32_e32 v13, 0xbfb8aa3b, v45
	v_exp_f32_e32 v13, v13
	s_nop 0
	v_add_f32_e32 v13, 1.0, v13
	v_rcp_f32_e32 v47, v13
	v_and_b32_e32 v13, 0xffff0000, v16
	v_pk_mul_f32 v[44:45], v[46:47], v[44:45]
	v_lshlrev_b32_e32 v46, 16, v12
	v_and_b32_e32 v47, 0xffff0000, v12
	v_lshlrev_b32_e32 v12, 16, v16
	v_pk_add_f32 v[12:13], v[46:47], v[12:13]
	v_lshlrev_b32_e32 v46, 16, v30
	v_pk_mul_f32 v[16:17], v[12:13], v[12:13]
	v_mul_f32_e32 v29, 0xbfb8aa3b, v46
	v_add_f32_e32 v16, v16, v17
	v_add_f32_e32 v16, v42, v16
	v_add_f32_e32 v16, v43, v16
	v_add_f32_e32 v16, v18, v16
	v_add_f32_e32 v16, v19, v16
	v_add_f32_e32 v16, v36, v16
	v_exp_f32_e32 v29, v29
	v_add_f32_e32 v16, v37, v16
	v_and_b32_e32 v47, 0xffff0000, v30
	v_add_f32_e32 v29, 1.0, v29
	v_add_f32_dpp v16, v16, v16 quad_perm:[1,0,3,2] row_mask:0xf bank_mask:0xf bound_ctrl:1
	v_rcp_f32_e32 v30, v29
	v_mul_f32_e32 v29, 0xbfb8aa3b, v47
	v_add_f32_dpp v16, v16, v16 quad_perm:[2,3,0,1] row_mask:0xf bank_mask:0xf bound_ctrl:1
	v_exp_f32_e32 v29, v29
	s_nop 0
	v_add_f32_dpp v16, v16, v16 row_half_mirror row_mask:0xf bank_mask:0xf bound_ctrl:1
	v_add_f32_e32 v29, 1.0, v29
	s_nop 0
	v_add_f32_dpp v16, v16, v16 row_mirror row_mask:0xf bank_mask:0xf bound_ctrl:1
	v_rcp_f32_e32 v31, v29
	v_readlane_b32 s8, v16, 16
	v_readlane_b32 s25, v16, 48
	v_readlane_b32 s22, v16, 0
	v_readlane_b32 s23, v16, 32
	v_mov_b32_e32 v16, s8
	v_mov_b32_e32 v17, s25
	v_pk_add_f32 v[16:17], s[22:23], v[16:17]
	v_pk_mul_f32 v[30:31], v[30:31], v[46:47]
	v_add_f32_e32 v16, v16, v17
	v_fmamk_f32 v16, v16, 0x3b000000, v204
	v_rsq_f32_e32 v16, v16
	s_nop 0
	v_pk_mul_f32 v[12:13], v[12:13], v[16:17] op_sel_hi:[1,0]
	v_pk_mul_f32 v[18:19], v[40:41], v[16:17] op_sel_hi:[1,0]
	v_pk_mul_f32 v[12:13], v[4:5], v[12:13]
	v_pk_mul_f32 v[18:19], v[6:7], v[18:19]
	v_pk_mul_f32 v[14:15], v[14:15], v[16:17] op_sel_hi:[1,0]
	v_pk_mul_f32 v[12:13], v[30:31], v[12:13]
	v_pk_mul_f32 v[18:19], v[44:45], v[18:19]
	v_pk_mul_f32 v[14:15], v[8:9], v[14:15]
	v_cvt_pk_bf16_f32 v12, v12, v13
	v_cvt_pk_bf16_f32 v13, v18, v19
	v_pk_mul_f32 v[14:15], v[38:39], v[14:15]
	v_lshlrev_b32_e32 v18, 16, v33
	v_cvt_pk_bf16_f32 v14, v14, v15
	v_mul_f32_e32 v15, 0xbfb8aa3b, v18
	v_exp_f32_e32 v15, v15
	v_and_b32_e32 v19, 0xffff0000, v33
	v_pk_mul_f32 v[16:17], v[34:35], v[16:17] op_sel_hi:[1,0]
	v_add_f32_e32 v15, 1.0, v15
	v_rcp_f32_e32 v30, v15
	v_mul_f32_e32 v15, 0xbfb8aa3b, v19
	v_exp_f32_e32 v15, v15
	v_pk_mul_f32 v[16:17], v[10:11], v[16:17]
	v_add_f32_e32 v15, 1.0, v15
	v_rcp_f32_e32 v31, v15
	s_nop 0
	v_pk_mul_f32 v[18:19], v[30:31], v[18:19]
	s_nop 0
	v_pk_mul_f32 v[16:17], v[18:19], v[16:17]
	s_nop 0
	v_cvt_pk_bf16_f32 v15, v16, v17
	global_store_dwordx4 v[22:23], v[12:15], off offset:1024
	s_nop 1
	s_waitcnt vmcnt(5)
	v_mov_b32_e32 v12, v64
	v_mov_b32_e32 v13, v65
	v_mov_b32_e32 v14, v66
	v_mov_b32_e32 v15, v67
	v_mov_b32_e32 v16, v68
	v_mov_b32_e32 v17, v69
	v_mov_b32_e32 v18, v70
	v_mov_b32_e32 v19, v71
	v_mov_b32_e32 v30, v72
	v_mov_b32_e32 v31, v73
	v_mov_b32_e32 v32, v74
	v_mov_b32_e32 v33, v75
	v_lshlrev_b32_e32 v34, 16, v15
	v_and_b32_e32 v35, 0xffff0000, v15
	v_lshlrev_b32_e32 v38, 16, v14
	v_and_b32_e32 v39, 0xffff0000, v14
	v_lshlrev_b32_e32 v14, 16, v18
	v_and_b32_e32 v15, 0xffff0000, v18
	v_pk_add_f32 v[14:15], v[38:39], v[14:15]
	v_lshlrev_b32_e32 v38, 16, v32
	v_mul_f32_e32 v24, 0xbfb8aa3b, v38
	v_exp_f32_e32 v24, v24
	v_and_b32_e32 v39, 0xffff0000, v32
	v_lshlrev_b32_e32 v44, 16, v31
	v_and_b32_e32 v45, 0xffff0000, v31
	v_add_f32_e32 v24, 1.0, v24
	v_rcp_f32_e32 v40, v24
	v_mul_f32_e32 v24, 0xbfb8aa3b, v39
	v_exp_f32_e32 v24, v24
	v_lshlrev_b32_e32 v42, 16, v17
	v_and_b32_e32 v43, 0xffff0000, v17
	v_lshlrev_b32_e32 v36, 16, v19
	v_add_f32_e32 v24, 1.0, v24
	v_rcp_f32_e32 v41, v24
	v_and_b32_e32 v37, 0xffff0000, v19
	v_pk_mul_f32 v[18:19], v[14:15], v[14:15]
	v_pk_add_f32 v[34:35], v[34:35], v[36:37]
	v_pk_mul_f32 v[38:39], v[40:41], v[38:39]
	v_lshlrev_b32_e32 v40, 16, v13
	v_and_b32_e32 v41, 0xffff0000, v13
	v_mul_f32_e32 v13, 0xbfb8aa3b, v44
	v_exp_f32_e32 v13, v13
	v_pk_add_f32 v[40:41], v[40:41], v[42:43]
	v_pk_mul_f32 v[36:37], v[34:35], v[34:35]
	v_pk_mul_f32 v[42:43], v[40:41], v[40:41]
; DI unsigned cvt_pk_bf16(float lo, float hi) { const f32x2 v = {lo, hi}; const bf16x2_t r = __builtin_convertvector(v, bf16x2_t); return __builtin_bit_cast(unsigned, r); }
; DI float bf_lo(unsigned w) { return __uint_as_float(w << 16); }
; DI float bf_hi(unsigned w) { return __uint_as_float(w & 0xffff0000u); }
; DI float silu_f(float g) { return g * __builtin_amdgcn_rcpf(1.0f + __expf(-g)); }
; DI void gla_norm_phase(const bf16_t* OF, const bf16_t* OB, bf16_t* R, const float* hgain) {
;     ...
;     for (int h = 0; h < 4; ++h) {
;       const size_t off = (size_t)row * GV + h * HV + lane * 8;
;       const size_t ooff = ((size_t)(((row >> 14) * 4 + h) * 16 + (lane >> 2)) * SEQ + (row & (SEQ - 1))) * 32 + (lane & 3) * 8;
;       const u32x4 a = *(const u32x4*)(OF + ooff), c = *(const u32x4*)(OB + ooff);
;       bf16_t* rp = R + off;
;       const u32x4 rv = *(const u32x4*)rp;
;       float o[8];
;       o[0] = bf_lo(a.x) + bf_lo(c.x); o[1] = bf_hi(a.x) + bf_hi(c.x); o[2] = bf_lo(a.y) + bf_lo(c.y); o[3] = bf_hi(a.y) + bf_hi(c.y);
;       o[4] = bf_lo(a.z) + bf_lo(c.z); o[5] = bf_hi(a.z) + bf_hi(c.z); o[6] = bf_lo(a.w) + bf_lo(c.w); o[7] = bf_hi(a.w) + bf_hi(c.w);
;       float ss = 0.f;
; #pragma unroll
;       for (int e = 0; e < 8; ++e) ss += o[e] * o[e];
;       ss = wave_sum(ss);
;       const float rs = __frsqrt_rn(ss * (1.0f / HV) + EPS);
;       u32x4 w;
;       w.x = cvt_pk_bf16(o[0] * rs * hg0[0] * pg8::silu_f(bf_lo(rv.x)), o[1] * rs * hg0[1] * pg8::silu_f(bf_hi(rv.x)));
;       w.y = cvt_pk_bf16(o[2] * rs * hg0[2] * pg8::silu_f(bf_lo(rv.y)), o[3] * rs * hg0[3] * pg8::silu_f(bf_hi(rv.y)));
;       w.z = cvt_pk_bf16(o[4] * rs * hg1[0] * pg8::silu_f(bf_lo(rv.z)), o[5] * rs * hg1[1] * pg8::silu_f(bf_hi(rv.z)));
;       w.w = cvt_pk_bf16(o[6] * rs * hg1[2] * pg8::silu_f(bf_lo(rv.w)), o[7] * rs * hg1[3] * pg8::silu_f(bf_hi(rv.w)));
;       *(u32x4*)rp = w;
;     }
	v_add_f32_e32 v13, 1.0, v13
	v_rcp_f32_e32 v46, v13
	v_mul_f32_e32 v13, 0xbfb8aa3b, v45
	v_exp_f32_e32 v13, v13
	s_nop 0
	v_add_f32_e32 v13, 1.0, v13
	v_rcp_f32_e32 v47, v13
	v_and_b32_e32 v13, 0xffff0000, v16
	v_pk_mul_f32 v[44:45], v[46:47], v[44:45]
	v_lshlrev_b32_e32 v46, 16, v12
	v_and_b32_e32 v47, 0xffff0000, v12
	v_lshlrev_b32_e32 v12, 16, v16
	v_pk_add_f32 v[12:13], v[46:47], v[12:13]
	v_lshlrev_b32_e32 v46, 16, v30
	v_pk_mul_f32 v[16:17], v[12:13], v[12:13]
	v_mul_f32_e32 v24, 0xbfb8aa3b, v46
	v_add_f32_e32 v16, v16, v17
	v_add_f32_e32 v16, v42, v16
	v_add_f32_e32 v16, v43, v16
	v_add_f32_e32 v16, v18, v16
	v_add_f32_e32 v16, v19, v16
	v_add_f32_e32 v16, v36, v16
	v_exp_f32_e32 v24, v24
	v_add_f32_e32 v16, v37, v16
	v_and_b32_e32 v47, 0xffff0000, v30
	v_add_f32_e32 v24, 1.0, v24
	v_add_f32_dpp v16, v16, v16 quad_perm:[1,0,3,2] row_mask:0xf bank_mask:0xf bound_ctrl:1
	v_rcp_f32_e32 v30, v24
	v_mul_f32_e32 v24, 0xbfb8aa3b, v47
	v_add_f32_dpp v16, v16, v16 quad_perm:[2,3,0,1] row_mask:0xf bank_mask:0xf bound_ctrl:1
	v_exp_f32_e32 v24, v24
	s_nop 0
	v_add_f32_dpp v16, v16, v16 row_half_mirror row_mask:0xf bank_mask:0xf bound_ctrl:1
	v_add_f32_e32 v24, 1.0, v24
	s_nop 0
	v_add_f32_dpp v16, v16, v16 row_mirror row_mask:0xf bank_mask:0xf bound_ctrl:1
	v_rcp_f32_e32 v31, v24
	v_readlane_b32 s8, v16, 16
	v_readlane_b32 s25, v16, 48
	v_readlane_b32 s22, v16, 0
	v_readlane_b32 s23, v16, 32
	v_mov_b32_e32 v16, s8
	v_mov_b32_e32 v17, s25
	v_pk_add_f32 v[16:17], s[22:23], v[16:17]
	v_pk_mul_f32 v[30:31], v[30:31], v[46:47]
	v_add_f32_e32 v16, v16, v17
	v_fmamk_f32 v16, v16, 0x3b000000, v204
	v_rsq_f32_e32 v16, v16
	s_nop 0
	v_pk_mul_f32 v[12:13], v[12:13], v[16:17] op_sel_hi:[1,0]
	v_pk_mul_f32 v[18:19], v[40:41], v[16:17] op_sel_hi:[1,0]
	v_pk_mul_f32 v[12:13], v[4:5], v[12:13]
	v_pk_mul_f32 v[18:19], v[6:7], v[18:19]
	v_pk_mul_f32 v[14:15], v[14:15], v[16:17] op_sel_hi:[1,0]
	v_pk_mul_f32 v[12:13], v[30:31], v[12:13]
	v_pk_mul_f32 v[18:19], v[44:45], v[18:19]
	v_pk_mul_f32 v[14:15], v[8:9], v[14:15]
	v_cvt_pk_bf16_f32 v12, v12, v13
	v_cvt_pk_bf16_f32 v13, v18, v19
	v_pk_mul_f32 v[14:15], v[38:39], v[14:15]
	v_lshlrev_b32_e32 v18, 16, v33
	v_cvt_pk_bf16_f32 v14, v14, v15
	v_mul_f32_e32 v15, 0xbfb8aa3b, v18
	v_exp_f32_e32 v15, v15
	v_and_b32_e32 v19, 0xffff0000, v33
	v_pk_mul_f32 v[16:17], v[34:35], v[16:17] op_sel_hi:[1,0]
	v_add_f32_e32 v15, 1.0, v15
	v_rcp_f32_e32 v30, v15
	v_mul_f32_e32 v15, 0xbfb8aa3b, v19
	v_exp_f32_e32 v15, v15
	v_pk_mul_f32 v[16:17], v[10:11], v[16:17]
	v_add_f32_e32 v15, 1.0, v15
	v_rcp_f32_e32 v31, v15
	s_nop 0
	v_pk_mul_f32 v[18:19], v[30:31], v[18:19]
	s_nop 0
	v_pk_mul_f32 v[16:17], v[18:19], v[16:17]
	s_nop 0
	v_cvt_pk_bf16_f32 v15, v16, v17
	global_store_dwordx4 v[22:23], v[12:15], off offset:2048
	s_nop 1
	s_waitcnt vmcnt(3)
; DI unsigned cvt_pk_bf16(float lo, float hi) { const f32x2 v = {lo, hi}; const bf16x2_t r = __builtin_convertvector(v, bf16x2_t); return __builtin_bit_cast(unsigned, r); }
; DI float bf_lo(unsigned w) { return __uint_as_float(w << 16); }
; DI float bf_hi(unsigned w) { return __uint_as_float(w & 0xffff0000u); }
; DI float silu_f(float g) { return g * __builtin_amdgcn_rcpf(1.0f + __expf(-g)); }
; DI void gla_norm_phase(const bf16_t* OF, const bf16_t* OB, bf16_t* R, const float* hgain) {
;     ...
;     for (int h = 0; h < 4; ++h) {
;       const size_t off = (size_t)row * GV + h * HV + lane * 8;
;       const size_t ooff = ((size_t)(((row >> 14) * 4 + h) * 16 + (lane >> 2)) * SEQ + (row & (SEQ - 1))) * 32 + (lane & 3) * 8;
;       const u32x4 a = *(const u32x4*)(OF + ooff), c = *(const u32x4*)(OB + ooff);
;       bf16_t* rp = R + off;
;       const u32x4 rv = *(const u32x4*)rp;
;       float o[8];
;       o[0] = bf_lo(a.x) + bf_lo(c.x); o[1] = bf_hi(a.x) + bf_hi(c.x); o[2] = bf_lo(a.y) + bf_lo(c.y); o[3] = bf_hi(a.y) + bf_hi(c.y);
;       o[4] = bf_lo(a.z) + bf_lo(c.z); o[5] = bf_hi(a.z) + bf_hi(c.z); o[6] = bf_lo(a.w) + bf_lo(c.w); o[7] = bf_hi(a.w) + bf_hi(c.w);
;       float ss = 0.f;
; #pragma unroll
;       for (int e = 0; e < 8; ++e) ss += o[e] * o[e];
;       ss = wave_sum(ss);
;       const float rs = __frsqrt_rn(ss * (1.0f / HV) + EPS);
;       u32x4 w;
;       w.x = cvt_pk_bf16(o[0] * rs * hg0[0] * pg8::silu_f(bf_lo(rv.x)), o[1] * rs * hg0[1] * pg8::silu_f(bf_hi(rv.x)));
;       w.y = cvt_pk_bf16(o[2] * rs * hg0[2] * pg8::silu_f(bf_lo(rv.y)), o[3] * rs * hg0[3] * pg8::silu_f(bf_hi(rv.y)));
;       w.z = cvt_pk_bf16(o[4] * rs * hg1[0] * pg8::silu_f(bf_lo(rv.z)), o[5] * rs * hg1[1] * pg8::silu_f(bf_hi(rv.z)));
;       w.w = cvt_pk_bf16(o[6] * rs * hg1[2] * pg8::silu_f(bf_lo(rv.w)), o[7] * rs * hg1[3] * pg8::silu_f(bf_hi(rv.w)));
;       *(u32x4*)rp = w;
;     }
;   }
	v_mov_b32_e32 v12, v80
	v_mov_b32_e32 v13, v81
	v_mov_b32_e32 v14, v82
	v_mov_b32_e32 v15, v83
	v_mov_b32_e32 v16, v84
	v_mov_b32_e32 v17, v85
	v_mov_b32_e32 v18, v86
	v_mov_b32_e32 v19, v87
	v_mov_b32_e32 v30, v88
	v_mov_b32_e32 v31, v89
	v_mov_b32_e32 v32, v90
	v_mov_b32_e32 v33, v91
	v_lshlrev_b32_e32 v24, 16, v15
	v_and_b32_e32 v25, 0xffff0000, v15
	v_lshlrev_b32_e32 v36, 16, v14
	v_and_b32_e32 v37, 0xffff0000, v14
	v_lshlrev_b32_e32 v14, 16, v18
	v_and_b32_e32 v15, 0xffff0000, v18
	v_pk_add_f32 v[14:15], v[36:37], v[14:15]
	v_lshlrev_b32_e32 v36, 16, v32
	v_mul_f32_e32 v21, 0xbfb8aa3b, v36
	v_exp_f32_e32 v21, v21
	v_and_b32_e32 v37, 0xffff0000, v32
	v_lshlrev_b32_e32 v42, 16, v31
	v_and_b32_e32 v43, 0xffff0000, v31
	v_add_f32_e32 v21, 1.0, v21
	v_rcp_f32_e32 v38, v21
	v_mul_f32_e32 v21, 0xbfb8aa3b, v37
	v_exp_f32_e32 v21, v21
	v_lshlrev_b32_e32 v40, 16, v17
	v_and_b32_e32 v41, 0xffff0000, v17
	v_lshlrev_b32_e32 v34, 16, v19
	v_add_f32_e32 v21, 1.0, v21
	v_rcp_f32_e32 v39, v21
	v_and_b32_e32 v35, 0xffff0000, v19
	v_pk_mul_f32 v[18:19], v[14:15], v[14:15]
	v_pk_add_f32 v[24:25], v[24:25], v[34:35]
	v_pk_mul_f32 v[36:37], v[38:39], v[36:37]
	v_lshlrev_b32_e32 v38, 16, v13
	v_and_b32_e32 v39, 0xffff0000, v13
	v_mul_f32_e32 v13, 0xbfb8aa3b, v42
	v_exp_f32_e32 v13, v13
	v_pk_add_f32 v[38:39], v[38:39], v[40:41]
	v_pk_mul_f32 v[34:35], v[24:25], v[24:25]
	v_pk_mul_f32 v[40:41], v[38:39], v[38:39]
	v_add_f32_e32 v13, 1.0, v13
	v_rcp_f32_e32 v44, v13
	v_mul_f32_e32 v13, 0xbfb8aa3b, v43
	v_exp_f32_e32 v13, v13
	s_nop 0
	v_add_f32_e32 v13, 1.0, v13
	v_rcp_f32_e32 v45, v13
	v_and_b32_e32 v13, 0xffff0000, v16
	v_pk_mul_f32 v[42:43], v[44:45], v[42:43]
	v_lshlrev_b32_e32 v44, 16, v12
	v_and_b32_e32 v45, 0xffff0000, v12
	v_lshlrev_b32_e32 v12, 16, v16
	v_pk_add_f32 v[12:13], v[44:45], v[12:13]
	v_lshlrev_b32_e32 v44, 16, v30
	v_pk_mul_f32 v[16:17], v[12:13], v[12:13]
	v_mul_f32_e32 v21, 0xbfb8aa3b, v44
	v_add_f32_e32 v16, v16, v17
	v_add_f32_e32 v16, v40, v16
	v_add_f32_e32 v16, v41, v16
	v_add_f32_e32 v16, v18, v16
	v_add_f32_e32 v16, v19, v16
	v_add_f32_e32 v16, v34, v16
	v_exp_f32_e32 v21, v21
	v_add_f32_e32 v16, v35, v16
	v_and_b32_e32 v45, 0xffff0000, v30
	v_add_f32_e32 v21, 1.0, v21
	v_add_f32_dpp v16, v16, v16 quad_perm:[1,0,3,2] row_mask:0xf bank_mask:0xf bound_ctrl:1
	v_rcp_f32_e32 v30, v21
	v_mul_f32_e32 v21, 0xbfb8aa3b, v45
	v_add_f32_dpp v16, v16, v16 quad_perm:[2,3,0,1] row_mask:0xf bank_mask:0xf bound_ctrl:1
	v_exp_f32_e32 v21, v21
	s_nop 0
	v_add_f32_dpp v16, v16, v16 row_half_mirror row_mask:0xf bank_mask:0xf bound_ctrl:1
	v_add_f32_e32 v21, 1.0, v21
	s_nop 0
	v_add_f32_dpp v16, v16, v16 row_mirror row_mask:0xf bank_mask:0xf bound_ctrl:1
	v_rcp_f32_e32 v31, v21
	v_readlane_b32 s8, v16, 16
	v_readlane_b32 s25, v16, 48
	v_readlane_b32 s22, v16, 0
	v_readlane_b32 s23, v16, 32
	v_mov_b32_e32 v16, s8
	v_mov_b32_e32 v17, s25
	v_pk_add_f32 v[16:17], s[22:23], v[16:17]
	v_pk_mul_f32 v[30:31], v[30:31], v[44:45]
	v_add_f32_e32 v16, v16, v17
	v_fmamk_f32 v16, v16, 0x3b000000, v204
	v_rsq_f32_e32 v16, v16
	s_nop 0
	v_pk_mul_f32 v[12:13], v[12:13], v[16:17] op_sel_hi:[1,0]
	v_pk_mul_f32 v[18:19], v[38:39], v[16:17] op_sel_hi:[1,0]
	v_pk_mul_f32 v[12:13], v[4:5], v[12:13]
	v_pk_mul_f32 v[18:19], v[6:7], v[18:19]
	v_pk_mul_f32 v[14:15], v[14:15], v[16:17] op_sel_hi:[1,0]
	v_pk_mul_f32 v[12:13], v[30:31], v[12:13]
	v_pk_mul_f32 v[18:19], v[42:43], v[18:19]
	v_pk_mul_f32 v[14:15], v[8:9], v[14:15]
	v_cvt_pk_bf16_f32 v12, v12, v13
	v_cvt_pk_bf16_f32 v13, v18, v19
	v_pk_mul_f32 v[14:15], v[36:37], v[14:15]
	v_lshlrev_b32_e32 v18, 16, v33
	v_cvt_pk_bf16_f32 v14, v14, v15
	v_mul_f32_e32 v15, 0xbfb8aa3b, v18
	v_exp_f32_e32 v15, v15
	v_and_b32_e32 v19, 0xffff0000, v33
	v_pk_mul_f32 v[16:17], v[24:25], v[16:17] op_sel_hi:[1,0]
	v_add_f32_e32 v15, 1.0, v15
	v_rcp_f32_e32 v30, v15
	v_mul_f32_e32 v15, 0xbfb8aa3b, v19
	v_exp_f32_e32 v15, v15
	v_pk_mul_f32 v[16:17], v[10:11], v[16:17]
	v_add_f32_e32 v15, 1.0, v15
	v_rcp_f32_e32 v31, v15
	s_nop 0
	v_pk_mul_f32 v[18:19], v[30:31], v[18:19]
	s_nop 0
	v_pk_mul_f32 v[16:17], v[18:19], v[16:17]
	s_nop 0
	v_cvt_pk_bf16_f32 v15, v16, v17
	global_store_dwordx4 v[22:23], v[12:15], off offset:3072
	v_lshl_add_u64 v[22:23], v[22:23], 0, s[30:31]
	s_andn2_b64 exec, exec, s[18:19]
	s_cbranch_execnz .LBB0_430

; #define PG8_STAGE(bufoff, gbase, voff) do { _Pragma("unroll") for (int _i = 0; _i < 2; ++_i) \
;     __builtin_amdgcn_global_load_lds((const unsigned*)((const char*)(gbase) + (voff)[_i]), (LAS unsigned*)(lds + (bufoff) + ldsw + _i * 8192), 16, 0, 0); } while (0)
; #define PG8_LDA(dst, b, h) do { _Pragma("unroll") for (int m = 0; m < 4; ++m) _Pragma("unroll") for (int k = 0; k < 2; ++k) dst[m][k] = *(const LAS bf16x8*)(lds + PG8_SA(b, h) + aoff + m * 2048 + k * 1024); } while (0)
; #define PG8_LDB(dst, b, h) do { _Pragma("unroll") for (int n = 0; n < 2; ++n) _Pragma("unroll") for (int k = 0; k < 2; ++k) dst[n][k] = *(const LAS bf16x8*)(lds + PG8_SB(b, h) + boff + n * 2048 + k * 1024); } while (0)
; #define PG8_MMA(ai, bj, At, Bt) do { __builtin_amdgcn_s_setprio(1); _Pragma("unroll") for (int m = 0; m < 4; ++m) _Pragma("unroll") for (int n = 0; n < 2; ++n) _Pragma("unroll") for (int k = 0; k < 2; ++k) \
;     acc[ai][bj][m][n] = __builtin_amdgcn_mfma_f32_16x16x32_bf16(Bt[n][k], At[m][k], acc[ai][bj][m][n], 0, 0, 0); __builtin_amdgcn_s_setprio(0); } while (0)
; #define PG8_WAIT_L(n) asm volatile("s_waitcnt lgkmcnt(" #n ")" ::: "memory")
; #define PG8_BAR __builtin_amdgcn_s_barrier()
; #define PG8_SCHED __builtin_amdgcn_sched_barrier(0)
; template <class Epi>
; DI void gemm_phase(LAS unsigned char* lds, const Gemm g, const Epi& E) {
;     ...
;     const bool has_next = S.next(ui + 1, nxt);
;     const char* nA = has_next ? PG8_APTR(nxt) : cA; const char* nB = has_next ? (const char*)g.Bt + (size_t)nxt.pn * tstepB : cB;
;     for (int t = 0; t < nt; t += 2) {
;       const bool last = (t == nt - 2);
;       const char* a1 = cA + (size_t)(t + 1) * kstep;
;       const char* a2 = last ? nA : cA + (size_t)(t + 2) * kstep; const char* b2 = last ? nB : cB + (size_t)(t + 2) * kstep;
;       const char* a3 = a2 + kstep; const char* b3 = b2 + kstep;
;       PG8_LDB(B0, 0, 0); PG8_SCHED; PG8_LDA(At, 0, 0); PG8_STAGE(PG8_SA(1, 1), a1 + hstepA, voffA);
;       PG8_WAIT_L(8); PG8_BAR; PG8_WAIT_L(0); PG8_MMA(0, 0, At, B0); PG8_BAR; PG8_SCHED;
;       PG8_LDB(B1, 0, 1); PG8_STAGE(PG8_SB(0, 0), b2, voffB);
;       PG8_BAR; PG8_WAIT_L(0); PG8_MMA(0, 1, At, B1); PG8_BAR;
;       PG8_LDA(At, 0, 1); PG8_STAGE(PG8_SA(0, 0), a2, voffA);
;       PG8_BAR; PG8_WAIT_L(0); PG8_MMA(1, 0, At, B0); PG8_BAR; PG8_SCHED;
.LBB0_513:
	s_add_u32 s42, s58, 0x80
	s_addc_u32 s43, s59, 0
	s_add_u32 s58, s56, 0x100
	s_addc_u32 s59, s57, 0
	s_mov_b32 s44, 0
	v_add_u32_e32 v248, 0x10000, v193
	ds_read_b128 v[132:135], v248
	ds_read_b128 v[136:139], v248 offset:1024
	ds_read_b128 v[140:143], v248 offset:2048
	ds_read_b128 v[144:147], v248 offset:3072
	s_add_i32 m0, s64, 0xc000
	ds_read_b128 v[148:151], v195
	ds_read_b128 v[152:155], v195 offset:1024
	ds_read_b128 v[156:159], v195 offset:2048
	ds_read_b128 v[160:163], v195 offset:3072
	ds_read_b128 v[196:199], v195 offset:4096
	ds_read_b128 v[200:203], v195 offset:5120
	ds_read_b128 v[208:211], v195 offset:6144
	ds_read_b128 v[212:215], v195 offset:7168
	global_load_lds_dwordx4 v186, s[42:43]
	s_add_i32 m0, s64, 0xe000
	s_nop 0
	global_load_lds_dwordx4 v188, s[42:43]
	s_waitcnt lgkmcnt(8)
	s_barrier
	s_waitcnt lgkmcnt(0)
	s_setprio 1
	s_waitcnt lgkmcnt(0)
	v_mfma_f32_16x16x32_bf16 v[128:131], v[132:135], v[148:151], 0
	s_add_i32 s78, s44, 2
	v_mfma_f32_16x16x32_bf16 v[124:127], v[140:143], v[148:151], 0
	s_add_u32 s56, s42, 0x80
	s_addc_u32 s45, s43, 0
	v_mfma_f32_16x16x32_bf16 v[116:119], v[132:135], v[156:159], 0
	s_add_i32 s79, 0, 0x10000
	v_mfma_f32_16x16x32_bf16 v[108:111], v[140:143], v[156:159], 0
	s_cmp_eq_u32 s72, s44
	s_cselect_b32 s44, s52, s56
	s_cselect_b32 s45, s53, s45
	s_cselect_b32 s57, s55, s59
	s_cselect_b32 s56, s54, s58
	v_mfma_f32_16x16x32_bf16 v[100:103], v[132:135], v[196:199], 0
	v_mfma_f32_16x16x32_bf16 v[92:95], v[140:143], v[196:199], 0
	v_mfma_f32_16x16x32_bf16 v[84:87], v[132:135], v[208:211], 0
	v_mfma_f32_16x16x32_bf16 v[76:79], v[140:143], v[208:211], 0
	v_mfma_f32_16x16x32_bf16 v[128:131], v[136:139], v[152:155], v[128:131]
	v_mfma_f32_16x16x32_bf16 v[124:127], v[144:147], v[152:155], v[124:127]
	v_mfma_f32_16x16x32_bf16 v[116:119], v[136:139], v[160:163], v[116:119]
	v_mfma_f32_16x16x32_bf16 v[108:111], v[144:147], v[160:163], v[108:111]
	v_mfma_f32_16x16x32_bf16 v[100:103], v[136:139], v[200:203], v[100:103]
	v_mfma_f32_16x16x32_bf16 v[92:95], v[144:147], v[200:203], v[92:95]
	s_setprio 2
	s_barrier
	v_mfma_f32_16x16x32_bf16 v[84:87], v[136:139], v[212:215], v[84:87]
	v_mfma_f32_16x16x32_bf16 v[76:79], v[144:147], v[212:215], v[76:79]
	s_setprio 0
	s_add_i32 s80, 0, 0x14000
	s_add_i32 s79, s79, s63
	ds_read_b128 v[216:219], v248 offset:16384
	ds_read_b128 v[220:223], v248 offset:17408
	ds_read_b128 v[224:227], v248 offset:18432
	ds_read_b128 v[228:231], v248 offset:19456
	s_add_u32 s98, s56, 0x80
	s_addc_u32 s99, s57, 0
	s_mov_b32 m0, s79
	global_load_lds_dwordx4 v2, s[56:57]
	s_add_i32 m0, s79, 0x2000
	s_nop 0
	global_load_lds_dwordx4 v184, s[56:57]
	s_barrier
	s_waitcnt lgkmcnt(0)
	s_setprio 1
	s_waitcnt lgkmcnt(0)
	v_mfma_f32_16x16x32_bf16 v[120:123], v[216:219], v[148:151], 0
	v_mfma_f32_16x16x32_bf16 v[112:115], v[224:227], v[148:151], 0
	v_mfma_f32_16x16x32_bf16 v[104:107], v[216:219], v[156:159], 0
	v_mfma_f32_16x16x32_bf16 v[96:99], v[224:227], v[156:159], 0
	v_mfma_f32_16x16x32_bf16 v[88:91], v[216:219], v[196:199], 0
	v_mfma_f32_16x16x32_bf16 v[80:83], v[224:227], v[196:199], 0
	v_mfma_f32_16x16x32_bf16 v[72:75], v[216:219], v[208:211], 0
	v_mfma_f32_16x16x32_bf16 v[68:71], v[224:227], v[208:211], 0
	v_mfma_f32_16x16x32_bf16 v[120:123], v[220:223], v[152:155], v[120:123]
	v_mfma_f32_16x16x32_bf16 v[112:115], v[228:231], v[152:155], v[112:115]
	v_mfma_f32_16x16x32_bf16 v[104:107], v[220:223], v[160:163], v[104:107]
	v_mfma_f32_16x16x32_bf16 v[96:99], v[228:231], v[160:163], v[96:99]
	v_mfma_f32_16x16x32_bf16 v[88:91], v[220:223], v[200:203], v[88:91]
	v_mfma_f32_16x16x32_bf16 v[80:83], v[228:231], v[200:203], v[80:83]
	s_setprio 2
	s_barrier
	v_mfma_f32_16x16x32_bf16 v[72:75], v[220:223], v[212:215], v[72:75]
	v_mfma_f32_16x16x32_bf16 v[68:71], v[228:231], v[212:215], v[68:71]
	s_setprio 0
	s_mov_b32 m0, s64
	s_add_u32 s100, s44, 0x80
	s_addc_u32 s101, s45, 0
	ds_read_b128 v[148:151], v195 offset:16384
	ds_read_b128 v[152:155], v195 offset:17408
	ds_read_b128 v[156:159], v195 offset:18432
	ds_read_b128 v[160:163], v195 offset:19456
	ds_read_b128 v[196:199], v195 offset:20480
	ds_read_b128 v[200:203], v195 offset:21504
	ds_read_b128 v[208:211], v195 offset:22528
	ds_read_b128 v[212:215], v195 offset:23552
	global_load_lds_dwordx4 v180, s[44:45]
	s_mov_b32 m0, s65
	s_nop 0
	global_load_lds_dwordx4 v182, s[44:45]
	s_waitcnt vmcnt(10)
	s_barrier
	s_waitcnt lgkmcnt(0)
	s_setprio 1
	s_waitcnt lgkmcnt(0)
	v_mfma_f32_16x16x32_bf16 v[64:67], v[132:135], v[148:151], 0
	v_mfma_f32_16x16x32_bf16 v[60:63], v[140:143], v[148:151], 0
	v_mfma_f32_16x16x32_bf16 v[56:59], v[132:135], v[156:159], 0
	v_mfma_f32_16x16x32_bf16 v[48:51], v[140:143], v[156:159], 0
	v_mfma_f32_16x16x32_bf16 v[40:43], v[132:135], v[196:199], 0
	v_mfma_f32_16x16x32_bf16 v[32:35], v[140:143], v[196:199], 0
	v_mfma_f32_16x16x32_bf16 v[24:27], v[132:135], v[208:211], 0
	v_mfma_f32_16x16x32_bf16 v[16:19], v[140:143], v[208:211], 0
	v_mfma_f32_16x16x32_bf16 v[64:67], v[136:139], v[152:155], v[64:67]
	v_mfma_f32_16x16x32_bf16 v[60:63], v[144:147], v[152:155], v[60:63]
	v_mfma_f32_16x16x32_bf16 v[56:59], v[136:139], v[160:163], v[56:59]
	v_mfma_f32_16x16x32_bf16 v[48:51], v[144:147], v[160:163], v[48:51]
	v_mfma_f32_16x16x32_bf16 v[40:43], v[136:139], v[200:203], v[40:43]
	v_mfma_f32_16x16x32_bf16 v[32:35], v[144:147], v[200:203], v[32:35]
	s_setprio 2
	s_barrier
; #define PG8_STAGE(bufoff, gbase, voff) do { _Pragma("unroll") for (int _i = 0; _i < 2; ++_i) \
;     __builtin_amdgcn_global_load_lds((const unsigned*)((const char*)(gbase) + (voff)[_i]), (LAS unsigned*)(lds + (bufoff) + ldsw + _i * 8192), 16, 0, 0); } while (0)
; #define PG8_LDA(dst, b, h) do { _Pragma("unroll") for (int m = 0; m < 4; ++m) _Pragma("unroll") for (int k = 0; k < 2; ++k) dst[m][k] = *(const LAS bf16x8*)(lds + PG8_SA(b, h) + aoff + m * 2048 + k * 1024); } while (0)
; #define PG8_LDB(dst, b, h) do { _Pragma("unroll") for (int n = 0; n < 2; ++n) _Pragma("unroll") for (int k = 0; k < 2; ++k) dst[n][k] = *(const LAS bf16x8*)(lds + PG8_SB(b, h) + boff + n * 2048 + k * 1024); } while (0)
; #define PG8_MMA(ai, bj, At, Bt) do { __builtin_amdgcn_s_setprio(1); _Pragma("unroll") for (int m = 0; m < 4; ++m) _Pragma("unroll") for (int n = 0; n < 2; ++n) _Pragma("unroll") for (int k = 0; k < 2; ++k) \
;     acc[ai][bj][m][n] = __builtin_amdgcn_mfma_f32_16x16x32_bf16(Bt[n][k], At[m][k], acc[ai][bj][m][n], 0, 0, 0); __builtin_amdgcn_s_setprio(0); } while (0)
; #define PG8_WAIT_V(n) asm volatile("s_waitcnt vmcnt(" #n ")" ::: "memory")
; #define PG8_WAIT_L(n) asm volatile("s_waitcnt lgkmcnt(" #n ")" ::: "memory")
; #define PG8_BAR __builtin_amdgcn_s_barrier()
; #define PG8_SCHED __builtin_amdgcn_sched_barrier(0)
; template <class Epi>
; DI void gemm_phase(LAS unsigned char* lds, const Gemm g, const Epi& E) {
;     ...
;       PG8_STAGE(PG8_SB(0, 1), b2 + hstepB, voffB);
;       PG8_WAIT_V(6); PG8_BAR; PG8_MMA(1, 1, At, B1); PG8_BAR;
;       PG8_LDB(B0, 1, 0); PG8_SCHED; PG8_LDA(At, 1, 0); PG8_STAGE(PG8_SA(0, 1), a2 + hstepA, voffA);
;       PG8_WAIT_L(8); PG8_BAR; PG8_WAIT_L(0); PG8_MMA(0, 0, At, B0); PG8_BAR; PG8_SCHED;
;       PG8_LDB(B1, 1, 1); PG8_STAGE(PG8_SB(1, 0), b3, voffB);
;       PG8_BAR; PG8_WAIT_L(0); PG8_MMA(0, 1, At, B1); PG8_BAR;
;       PG8_LDA(At, 1, 1); PG8_STAGE(PG8_SA(1, 0), a3, voffA);
	v_mfma_f32_16x16x32_bf16 v[24:27], v[136:139], v[212:215], v[24:27]
	v_mfma_f32_16x16x32_bf16 v[16:19], v[144:147], v[212:215], v[16:19]
	s_setprio 0
	ds_read_b128 v[132:135], v248 offset:32768
	ds_read_b128 v[136:139], v248 offset:33792
	ds_read_b128 v[140:143], v248 offset:34816
	ds_read_b128 v[144:147], v248 offset:35840
	s_add_u32 s56, s56, s18
	s_addc_u32 s57, s57, s19
	s_add_i32 s79, s80, s63
	v_lshl_add_u64 v[238:239], s[56:57], 0, v[2:3]
	s_mov_b32 m0, s79
	v_lshl_add_u64 v[240:241], s[56:57], 0, v[184:185]
	global_load_lds_dwordx4 v[238:239], off
	s_add_i32 m0, s79, 0x2000
	s_nop 0
	global_load_lds_dwordx4 v[240:241], off
	s_waitcnt vmcnt(6)
	s_barrier
	s_setprio 1
	v_mfma_f32_16x16x32_bf16 v[52:55], v[216:219], v[148:151], 0
	v_mfma_f32_16x16x32_bf16 v[44:47], v[224:227], v[148:151], 0
	v_mfma_f32_16x16x32_bf16 v[36:39], v[216:219], v[156:159], 0
	v_mfma_f32_16x16x32_bf16 v[28:31], v[224:227], v[156:159], 0
	v_mfma_f32_16x16x32_bf16 v[20:23], v[216:219], v[196:199], 0
	v_mfma_f32_16x16x32_bf16 v[12:15], v[224:227], v[196:199], 0
	v_mfma_f32_16x16x32_bf16 v[8:11], v[216:219], v[208:211], 0
	v_mfma_f32_16x16x32_bf16 v[4:7], v[224:227], v[208:211], 0
	v_mfma_f32_16x16x32_bf16 v[52:55], v[220:223], v[152:155], v[52:55]
	v_mfma_f32_16x16x32_bf16 v[44:47], v[228:231], v[152:155], v[44:47]
	v_mfma_f32_16x16x32_bf16 v[36:39], v[220:223], v[160:163], v[36:39]
	v_mfma_f32_16x16x32_bf16 v[28:31], v[228:231], v[160:163], v[28:31]
	v_mfma_f32_16x16x32_bf16 v[20:23], v[220:223], v[200:203], v[20:23]
	v_mfma_f32_16x16x32_bf16 v[12:15], v[228:231], v[200:203], v[12:15]
	s_setprio 2
	s_barrier
	v_mfma_f32_16x16x32_bf16 v[8:11], v[220:223], v[212:215], v[8:11]
	v_mfma_f32_16x16x32_bf16 v[4:7], v[228:231], v[212:215], v[4:7]
	s_setprio 0
	s_add_i32 s56, 0, 0x18000
	s_add_u32 s44, s44, s8
	s_addc_u32 s45, s45, 0
	s_mov_b32 m0, s66
	ds_read_b128 v[148:151], v195 offset:32768
	ds_read_b128 v[152:155], v195 offset:33792
	ds_read_b128 v[156:159], v195 offset:34816
	ds_read_b128 v[160:163], v195 offset:35840
	ds_read_b128 v[196:199], v195 offset:36864
	ds_read_b128 v[200:203], v195 offset:37888
	ds_read_b128 v[208:211], v195 offset:38912
	ds_read_b128 v[212:215], v195 offset:39936
	global_load_lds_dwordx4 v180, s[44:45]
	s_mov_b32 m0, s67
	s_nop 0
	global_load_lds_dwordx4 v182, s[44:45]
	s_waitcnt lgkmcnt(8)
	s_barrier
	s_waitcnt lgkmcnt(0)
	s_setprio 1
	s_waitcnt lgkmcnt(0)
	v_mfma_f32_16x16x32_bf16 v[128:131], v[132:135], v[148:151], v[128:131]
	v_mfma_f32_16x16x32_bf16 v[124:127], v[140:143], v[148:151], v[124:127]
	v_mfma_f32_16x16x32_bf16 v[116:119], v[132:135], v[156:159], v[116:119]
	v_mfma_f32_16x16x32_bf16 v[108:111], v[140:143], v[156:159], v[108:111]
	v_mfma_f32_16x16x32_bf16 v[100:103], v[132:135], v[196:199], v[100:103]
	v_mfma_f32_16x16x32_bf16 v[92:95], v[140:143], v[196:199], v[92:95]
	v_mfma_f32_16x16x32_bf16 v[84:87], v[132:135], v[208:211], v[84:87]
	v_mfma_f32_16x16x32_bf16 v[76:79], v[140:143], v[208:211], v[76:79]
	v_mfma_f32_16x16x32_bf16 v[128:131], v[136:139], v[152:155], v[128:131]
	v_mfma_f32_16x16x32_bf16 v[124:127], v[144:147], v[152:155], v[124:127]
	v_mfma_f32_16x16x32_bf16 v[116:119], v[136:139], v[160:163], v[116:119]
	v_mfma_f32_16x16x32_bf16 v[108:111], v[144:147], v[160:163], v[108:111]
	v_mfma_f32_16x16x32_bf16 v[100:103], v[136:139], v[200:203], v[100:103]
	v_mfma_f32_16x16x32_bf16 v[92:95], v[144:147], v[200:203], v[92:95]
	s_setprio 2
	s_barrier
	v_mfma_f32_16x16x32_bf16 v[84:87], v[136:139], v[212:215], v[84:87]
	v_mfma_f32_16x16x32_bf16 v[76:79], v[144:147], v[212:215], v[76:79]
	s_setprio 0
	s_add_i32 s44, 0, 0x1c000
	s_add_i32 s45, s56, s63
	s_mov_b32 m0, s45
	ds_read_b128 v[216:219], v248 offset:49152
	ds_read_b128 v[220:223], v248 offset:50176
	ds_read_b128 v[224:227], v248 offset:51200
	ds_read_b128 v[228:231], v248 offset:52224
	global_load_lds_dwordx4 v2, s[98:99]
	s_add_i32 m0, s45, 0x2000
	s_nop 0
	global_load_lds_dwordx4 v184, s[98:99]
	s_barrier
	s_waitcnt lgkmcnt(0)
	s_setprio 1
	s_waitcnt lgkmcnt(0)
	v_mfma_f32_16x16x32_bf16 v[120:123], v[216:219], v[148:151], v[120:123]
	v_mfma_f32_16x16x32_bf16 v[112:115], v[224:227], v[148:151], v[112:115]
	v_mfma_f32_16x16x32_bf16 v[104:107], v[216:219], v[156:159], v[104:107]
	v_mfma_f32_16x16x32_bf16 v[96:99], v[224:227], v[156:159], v[96:99]
	v_mfma_f32_16x16x32_bf16 v[88:91], v[216:219], v[196:199], v[88:91]
	v_mfma_f32_16x16x32_bf16 v[80:83], v[224:227], v[196:199], v[80:83]
	v_mfma_f32_16x16x32_bf16 v[72:75], v[216:219], v[208:211], v[72:75]
	v_mfma_f32_16x16x32_bf16 v[68:71], v[224:227], v[208:211], v[68:71]
	v_mfma_f32_16x16x32_bf16 v[120:123], v[220:223], v[152:155], v[120:123]
	v_mfma_f32_16x16x32_bf16 v[112:115], v[228:231], v[152:155], v[112:115]
	v_mfma_f32_16x16x32_bf16 v[104:107], v[220:223], v[160:163], v[104:107]
	v_mfma_f32_16x16x32_bf16 v[96:99], v[228:231], v[160:163], v[96:99]
	v_mfma_f32_16x16x32_bf16 v[88:91], v[220:223], v[200:203], v[88:91]
	v_mfma_f32_16x16x32_bf16 v[80:83], v[228:231], v[200:203], v[80:83]
	s_setprio 2
	s_barrier
	v_mfma_f32_16x16x32_bf16 v[72:75], v[220:223], v[212:215], v[72:75]
	v_mfma_f32_16x16x32_bf16 v[68:71], v[228:231], v[212:215], v[68:71]
	s_setprio 0
	s_mov_b32 m0, s69
	ds_read_b128 v[148:151], v195 offset:49152
	ds_read_b128 v[152:155], v195 offset:50176
	ds_read_b128 v[156:159], v195 offset:51200
	ds_read_b128 v[160:163], v195 offset:52224
	ds_read_b128 v[196:199], v195 offset:53248
	ds_read_b128 v[200:203], v195 offset:54272
	ds_read_b128 v[208:211], v195 offset:55296
	ds_read_b128 v[212:215], v195 offset:56320
	global_load_lds_dwordx4 v180, s[100:101]
	s_mov_b32 m0, s71
	s_nop 0
	global_load_lds_dwordx4 v182, s[100:101]
	s_waitcnt vmcnt(10)
	s_barrier
; #define PG8_STAGE(bufoff, gbase, voff) do { _Pragma("unroll") for (int _i = 0; _i < 2; ++_i) \
;     __builtin_amdgcn_global_load_lds((const unsigned*)((const char*)(gbase) + (voff)[_i]), (LAS unsigned*)(lds + (bufoff) + ldsw + _i * 8192), 16, 0, 0); } while (0)
; #define PG8_LDA(dst, b, h) do { _Pragma("unroll") for (int m = 0; m < 4; ++m) _Pragma("unroll") for (int k = 0; k < 2; ++k) dst[m][k] = *(const LAS bf16x8*)(lds + PG8_SA(b, h) + aoff + m * 2048 + k * 1024); } while (0)
; #define PG8_LDB(dst, b, h) do { _Pragma("unroll") for (int n = 0; n < 2; ++n) _Pragma("unroll") for (int k = 0; k < 2; ++k) dst[n][k] = *(const LAS bf16x8*)(lds + PG8_SB(b, h) + boff + n * 2048 + k * 1024); } while (0)
; #define PG8_MMA(ai, bj, At, Bt) do { __builtin_amdgcn_s_setprio(1); _Pragma("unroll") for (int m = 0; m < 4; ++m) _Pragma("unroll") for (int n = 0; n < 2; ++n) _Pragma("unroll") for (int k = 0; k < 2; ++k) \
;     acc[ai][bj][m][n] = __builtin_amdgcn_mfma_f32_16x16x32_bf16(Bt[n][k], At[m][k], acc[ai][bj][m][n], 0, 0, 0); __builtin_amdgcn_s_setprio(0); } while (0)
; #define PG8_WAIT_V(n) asm volatile("s_waitcnt vmcnt(" #n ")" ::: "memory")
; #define PG8_WAIT_L(n) asm volatile("s_waitcnt lgkmcnt(" #n ")" ::: "memory")
; #define PG8_BAR __builtin_amdgcn_s_barrier()
; template <class Epi>
; DI void gemm_phase(LAS unsigned char* lds, const Gemm g, const Epi& E) {
;     ...
;     const bool has_next = S.next(ui + 1, nxt);
;     const char* nA = has_next ? PG8_APTR(nxt) : cA; const char* nB = has_next ? (const char*)g.Bt + (size_t)nxt.pn * tstepB : cB;
;     for (int t = 0; t < nt; t += 2) {
;       const bool last = (t == nt - 2);
;       const char* a1 = cA + (size_t)(t + 1) * kstep;
;       const char* a2 = last ? nA : cA + (size_t)(t + 2) * kstep; const char* b2 = last ? nB : cB + (size_t)(t + 2) * kstep;
;       const char* a3 = a2 + kstep; const char* b3 = b2 + kstep;
;       PG8_LDB(B0, 0, 0); PG8_SCHED; PG8_LDA(At, 0, 0); PG8_STAGE(PG8_SA(1, 1), a1 + hstepA, voffA);
;       PG8_WAIT_L(8); PG8_BAR; PG8_WAIT_L(0); PG8_MMA(0, 0, At, B0); PG8_BAR; PG8_SCHED;
;       PG8_LDB(B1, 0, 1); PG8_STAGE(PG8_SB(0, 0), b2, voffB);
;       PG8_BAR; PG8_WAIT_L(0); PG8_MMA(0, 1, At, B1); PG8_BAR;
;     ...
;       PG8_BAR; PG8_WAIT_L(0); PG8_MMA(1, 0, At, B0); PG8_BAR; PG8_SCHED;
;       PG8_STAGE(PG8_SB(1, 1), b3 + hstepB, voffB);
;       PG8_WAIT_V(6); PG8_BAR; PG8_MMA(1, 1, At, B1); PG8_BAR;
	s_waitcnt lgkmcnt(0)
	s_setprio 1
	s_waitcnt lgkmcnt(0)
	v_mfma_f32_16x16x32_bf16 v[64:67], v[132:135], v[148:151], v[64:67]
	v_mfma_f32_16x16x32_bf16 v[60:63], v[140:143], v[148:151], v[60:63]
	v_mfma_f32_16x16x32_bf16 v[56:59], v[132:135], v[156:159], v[56:59]
	v_mfma_f32_16x16x32_bf16 v[48:51], v[140:143], v[156:159], v[48:51]
	v_mfma_f32_16x16x32_bf16 v[40:43], v[132:135], v[196:199], v[40:43]
	v_mfma_f32_16x16x32_bf16 v[32:35], v[140:143], v[196:199], v[32:35]
	v_mfma_f32_16x16x32_bf16 v[24:27], v[132:135], v[208:211], v[24:27]
	v_mfma_f32_16x16x32_bf16 v[16:19], v[140:143], v[208:211], v[16:19]
	v_mfma_f32_16x16x32_bf16 v[64:67], v[136:139], v[152:155], v[64:67]
	v_mfma_f32_16x16x32_bf16 v[60:63], v[144:147], v[152:155], v[60:63]
	v_mfma_f32_16x16x32_bf16 v[56:59], v[136:139], v[160:163], v[56:59]
	v_mfma_f32_16x16x32_bf16 v[48:51], v[144:147], v[160:163], v[48:51]
	v_mfma_f32_16x16x32_bf16 v[40:43], v[136:139], v[200:203], v[40:43]
	v_mfma_f32_16x16x32_bf16 v[32:35], v[144:147], v[200:203], v[32:35]
	s_setprio 2
	s_barrier
	v_mfma_f32_16x16x32_bf16 v[24:27], v[136:139], v[212:215], v[24:27]
	v_mfma_f32_16x16x32_bf16 v[16:19], v[144:147], v[212:215], v[16:19]
	s_setprio 0
	ds_read_b128 v[132:135], v248
	ds_read_b128 v[136:139], v248 offset:1024
	ds_read_b128 v[140:143], v248 offset:2048
	ds_read_b128 v[144:147], v248 offset:3072
	s_add_i32 s44, s44, s63
	v_lshl_add_u64 v[246:247], v[238:239], 0, s[84:85]
	s_mov_b32 m0, s44
	s_nop 0
	global_load_lds_dwordx4 v[246:247], off
	v_lshl_add_u64 v[246:247], v[240:241], 0, s[84:85]
	s_add_i32 m0, s44, 0x2000
	s_nop 0
	global_load_lds_dwordx4 v[246:247], off
	s_waitcnt vmcnt(6)
	s_barrier
	s_setprio 1
	v_mfma_f32_16x16x32_bf16 v[52:55], v[216:219], v[148:151], v[52:55]
	v_mfma_f32_16x16x32_bf16 v[44:47], v[224:227], v[148:151], v[44:47]
	v_mfma_f32_16x16x32_bf16 v[36:39], v[216:219], v[156:159], v[36:39]
	v_mfma_f32_16x16x32_bf16 v[28:31], v[224:227], v[156:159], v[28:31]
	v_mfma_f32_16x16x32_bf16 v[20:23], v[216:219], v[196:199], v[20:23]
	v_mfma_f32_16x16x32_bf16 v[12:15], v[224:227], v[196:199], v[12:15]
	v_mfma_f32_16x16x32_bf16 v[8:11], v[216:219], v[208:211], v[8:11]
	v_mfma_f32_16x16x32_bf16 v[4:7], v[224:227], v[208:211], v[4:7]
	v_mfma_f32_16x16x32_bf16 v[52:55], v[220:223], v[152:155], v[52:55]
	v_mfma_f32_16x16x32_bf16 v[44:47], v[228:231], v[152:155], v[44:47]
	v_mfma_f32_16x16x32_bf16 v[36:39], v[220:223], v[160:163], v[36:39]
	v_mfma_f32_16x16x32_bf16 v[28:31], v[228:231], v[160:163], v[28:31]
	v_mfma_f32_16x16x32_bf16 v[20:23], v[220:223], v[200:203], v[20:23]
	v_mfma_f32_16x16x32_bf16 v[12:15], v[228:231], v[200:203], v[12:15]
	s_setprio 2
	s_barrier
	v_mfma_f32_16x16x32_bf16 v[8:11], v[220:223], v[212:215], v[8:11]
	v_mfma_f32_16x16x32_bf16 v[4:7], v[228:231], v[212:215], v[4:7]
	s_setprio 0
	s_add_u32 s42, s42, 0x100
	s_addc_u32 s43, s43, 0
	s_add_u32 s58, s58, 0x100
	s_addc_u32 s59, s59, 0
	s_cmp_ge_u32 s78, s68
	s_mov_b32 s44, s78
	s_cbranch_scc1 .Lpeel_exit_514
.LBB0_514:
	s_add_i32 m0, s64, 0xc000
	ds_read_b128 v[148:151], v195
	ds_read_b128 v[152:155], v195 offset:1024
	ds_read_b128 v[156:159], v195 offset:2048
	ds_read_b128 v[160:163], v195 offset:3072
	ds_read_b128 v[196:199], v195 offset:4096
	ds_read_b128 v[200:203], v195 offset:5120
	ds_read_b128 v[208:211], v195 offset:6144
	ds_read_b128 v[212:215], v195 offset:7168
	global_load_lds_dwordx4 v186, s[42:43]
	s_add_i32 m0, s64, 0xe000
	s_nop 0
	global_load_lds_dwordx4 v188, s[42:43]
	s_waitcnt lgkmcnt(8)
	s_barrier
	s_waitcnt lgkmcnt(0)
	s_setprio 1
	s_waitcnt lgkmcnt(0)
	v_mfma_f32_16x16x32_bf16 v[128:131], v[132:135], v[148:151], v[128:131]
	s_add_i32 s78, s44, 2
	v_mfma_f32_16x16x32_bf16 v[124:127], v[140:143], v[148:151], v[124:127]
	s_add_u32 s56, s42, 0x80
	s_addc_u32 s45, s43, 0
	v_mfma_f32_16x16x32_bf16 v[116:119], v[132:135], v[156:159], v[116:119]
	s_add_i32 s79, 0, 0x10000
	v_mfma_f32_16x16x32_bf16 v[108:111], v[140:143], v[156:159], v[108:111]
	s_cmp_eq_u32 s72, s44
	s_cselect_b32 s44, s52, s56
	s_cselect_b32 s45, s53, s45
	s_cselect_b32 s57, s55, s59
	s_cselect_b32 s56, s54, s58
	v_mfma_f32_16x16x32_bf16 v[100:103], v[132:135], v[196:199], v[100:103]
	v_mfma_f32_16x16x32_bf16 v[92:95], v[140:143], v[196:199], v[92:95]
	v_mfma_f32_16x16x32_bf16 v[84:87], v[132:135], v[208:211], v[84:87]
	v_mfma_f32_16x16x32_bf16 v[76:79], v[140:143], v[208:211], v[76:79]
	v_mfma_f32_16x16x32_bf16 v[128:131], v[136:139], v[152:155], v[128:131]
	v_mfma_f32_16x16x32_bf16 v[124:127], v[144:147], v[152:155], v[124:127]
	v_mfma_f32_16x16x32_bf16 v[116:119], v[136:139], v[160:163], v[116:119]
	v_mfma_f32_16x16x32_bf16 v[108:111], v[144:147], v[160:163], v[108:111]
	v_mfma_f32_16x16x32_bf16 v[100:103], v[136:139], v[200:203], v[100:103]
	v_mfma_f32_16x16x32_bf16 v[92:95], v[144:147], v[200:203], v[92:95]
	s_setprio 2
	s_barrier
	v_mfma_f32_16x16x32_bf16 v[84:87], v[136:139], v[212:215], v[84:87]
	v_mfma_f32_16x16x32_bf16 v[76:79], v[144:147], v[212:215], v[76:79]
	s_setprio 0
	s_add_i32 s80, 0, 0x14000
	s_add_i32 s79, s79, s63
	ds_read_b128 v[216:219], v248 offset:16384
	ds_read_b128 v[220:223], v248 offset:17408
	ds_read_b128 v[224:227], v248 offset:18432
	ds_read_b128 v[228:231], v248 offset:19456
	s_add_u32 s98, s56, 0x80
	s_addc_u32 s99, s57, 0
	s_mov_b32 m0, s79
	global_load_lds_dwordx4 v2, s[56:57]
	s_add_i32 m0, s79, 0x2000
	s_nop 0
	global_load_lds_dwordx4 v184, s[56:57]
	s_barrier
; #define PG8_STAGE(bufoff, gbase, voff) do { _Pragma("unroll") for (int _i = 0; _i < 2; ++_i) \
;     __builtin_amdgcn_global_load_lds((const unsigned*)((const char*)(gbase) + (voff)[_i]), (LAS unsigned*)(lds + (bufoff) + ldsw + _i * 8192), 16, 0, 0); } while (0)
; #define PG8_LDA(dst, b, h) do { _Pragma("unroll") for (int m = 0; m < 4; ++m) _Pragma("unroll") for (int k = 0; k < 2; ++k) dst[m][k] = *(const LAS bf16x8*)(lds + PG8_SA(b, h) + aoff + m * 2048 + k * 1024); } while (0)
; #define PG8_LDB(dst, b, h) do { _Pragma("unroll") for (int n = 0; n < 2; ++n) _Pragma("unroll") for (int k = 0; k < 2; ++k) dst[n][k] = *(const LAS bf16x8*)(lds + PG8_SB(b, h) + boff + n * 2048 + k * 1024); } while (0)
; #define PG8_MMA(ai, bj, At, Bt) do { __builtin_amdgcn_s_setprio(1); _Pragma("unroll") for (int m = 0; m < 4; ++m) _Pragma("unroll") for (int n = 0; n < 2; ++n) _Pragma("unroll") for (int k = 0; k < 2; ++k) \
;     acc[ai][bj][m][n] = __builtin_amdgcn_mfma_f32_16x16x32_bf16(Bt[n][k], At[m][k], acc[ai][bj][m][n], 0, 0, 0); __builtin_amdgcn_s_setprio(0); } while (0)
; #define PG8_WAIT_V(n) asm volatile("s_waitcnt vmcnt(" #n ")" ::: "memory")
; #define PG8_WAIT_L(n) asm volatile("s_waitcnt lgkmcnt(" #n ")" ::: "memory")
; #define PG8_BAR __builtin_amdgcn_s_barrier()
; #define PG8_SCHED __builtin_amdgcn_sched_barrier(0)
; template <class Epi>
; DI void gemm_phase(LAS unsigned char* lds, const Gemm g, const Epi& E) {
;     ...
;       PG8_BAR; PG8_WAIT_L(0); PG8_MMA(0, 1, At, B1); PG8_BAR;
;       PG8_LDA(At, 0, 1); PG8_STAGE(PG8_SA(0, 0), a2, voffA);
;       PG8_BAR; PG8_WAIT_L(0); PG8_MMA(1, 0, At, B0); PG8_BAR; PG8_SCHED;
;       PG8_STAGE(PG8_SB(0, 1), b2 + hstepB, voffB);
;       PG8_WAIT_V(6); PG8_BAR; PG8_MMA(1, 1, At, B1); PG8_BAR;
;       PG8_LDB(B0, 1, 0); PG8_SCHED; PG8_LDA(At, 1, 0); PG8_STAGE(PG8_SA(0, 1), a2 + hstepA, voffA);
;       PG8_WAIT_L(8); PG8_BAR; PG8_WAIT_L(0); PG8_MMA(0, 0, At, B0); PG8_BAR; PG8_SCHED;
;       PG8_LDB(B1, 1, 1); PG8_STAGE(PG8_SB(1, 0), b3, voffB);
;       PG8_BAR; PG8_WAIT_L(0); PG8_MMA(0, 1, At, B1); PG8_BAR;
	s_waitcnt lgkmcnt(0)
	s_setprio 1
	s_waitcnt lgkmcnt(0)
	v_mfma_f32_16x16x32_bf16 v[120:123], v[216:219], v[148:151], v[120:123]
	v_mfma_f32_16x16x32_bf16 v[112:115], v[224:227], v[148:151], v[112:115]
	v_mfma_f32_16x16x32_bf16 v[104:107], v[216:219], v[156:159], v[104:107]
	v_mfma_f32_16x16x32_bf16 v[96:99], v[224:227], v[156:159], v[96:99]
	v_mfma_f32_16x16x32_bf16 v[88:91], v[216:219], v[196:199], v[88:91]
	v_mfma_f32_16x16x32_bf16 v[80:83], v[224:227], v[196:199], v[80:83]
	v_mfma_f32_16x16x32_bf16 v[72:75], v[216:219], v[208:211], v[72:75]
	v_mfma_f32_16x16x32_bf16 v[68:71], v[224:227], v[208:211], v[68:71]
	v_mfma_f32_16x16x32_bf16 v[120:123], v[220:223], v[152:155], v[120:123]
	v_mfma_f32_16x16x32_bf16 v[112:115], v[228:231], v[152:155], v[112:115]
	v_mfma_f32_16x16x32_bf16 v[104:107], v[220:223], v[160:163], v[104:107]
	v_mfma_f32_16x16x32_bf16 v[96:99], v[228:231], v[160:163], v[96:99]
	v_mfma_f32_16x16x32_bf16 v[88:91], v[220:223], v[200:203], v[88:91]
	v_mfma_f32_16x16x32_bf16 v[80:83], v[228:231], v[200:203], v[80:83]
	s_setprio 2
	s_barrier
	v_mfma_f32_16x16x32_bf16 v[72:75], v[220:223], v[212:215], v[72:75]
	v_mfma_f32_16x16x32_bf16 v[68:71], v[228:231], v[212:215], v[68:71]
	s_setprio 0
	s_mov_b32 m0, s64
	s_add_u32 s100, s44, 0x80
	s_addc_u32 s101, s45, 0
	ds_read_b128 v[148:151], v195 offset:16384
	ds_read_b128 v[152:155], v195 offset:17408
	ds_read_b128 v[156:159], v195 offset:18432
	ds_read_b128 v[160:163], v195 offset:19456
	ds_read_b128 v[196:199], v195 offset:20480
	ds_read_b128 v[200:203], v195 offset:21504
	ds_read_b128 v[208:211], v195 offset:22528
	ds_read_b128 v[212:215], v195 offset:23552
	global_load_lds_dwordx4 v180, s[44:45]
	s_mov_b32 m0, s65
	s_nop 0
	global_load_lds_dwordx4 v182, s[44:45]
	s_waitcnt vmcnt(10)
	s_barrier
	s_waitcnt lgkmcnt(0)
	s_setprio 1
	s_waitcnt lgkmcnt(0)
	v_mfma_f32_16x16x32_bf16 v[64:67], v[132:135], v[148:151], v[64:67]
	v_mfma_f32_16x16x32_bf16 v[60:63], v[140:143], v[148:151], v[60:63]
	v_mfma_f32_16x16x32_bf16 v[56:59], v[132:135], v[156:159], v[56:59]
	v_mfma_f32_16x16x32_bf16 v[48:51], v[140:143], v[156:159], v[48:51]
	v_mfma_f32_16x16x32_bf16 v[40:43], v[132:135], v[196:199], v[40:43]
	v_mfma_f32_16x16x32_bf16 v[32:35], v[140:143], v[196:199], v[32:35]
	v_mfma_f32_16x16x32_bf16 v[24:27], v[132:135], v[208:211], v[24:27]
	v_mfma_f32_16x16x32_bf16 v[16:19], v[140:143], v[208:211], v[16:19]
	v_mfma_f32_16x16x32_bf16 v[64:67], v[136:139], v[152:155], v[64:67]
	v_mfma_f32_16x16x32_bf16 v[60:63], v[144:147], v[152:155], v[60:63]
	v_mfma_f32_16x16x32_bf16 v[56:59], v[136:139], v[160:163], v[56:59]
	v_mfma_f32_16x16x32_bf16 v[48:51], v[144:147], v[160:163], v[48:51]
	v_mfma_f32_16x16x32_bf16 v[40:43], v[136:139], v[200:203], v[40:43]
	v_mfma_f32_16x16x32_bf16 v[32:35], v[144:147], v[200:203], v[32:35]
	s_setprio 2
	s_barrier
	v_mfma_f32_16x16x32_bf16 v[24:27], v[136:139], v[212:215], v[24:27]
	v_mfma_f32_16x16x32_bf16 v[16:19], v[144:147], v[212:215], v[16:19]
	s_setprio 0
	ds_read_b128 v[132:135], v248 offset:32768
	ds_read_b128 v[136:139], v248 offset:33792
	ds_read_b128 v[140:143], v248 offset:34816
	ds_read_b128 v[144:147], v248 offset:35840
	s_add_u32 s56, s56, s18
	s_addc_u32 s57, s57, s19
	s_add_i32 s79, s80, s63
	v_lshl_add_u64 v[238:239], s[56:57], 0, v[2:3]
	s_mov_b32 m0, s79
	v_lshl_add_u64 v[240:241], s[56:57], 0, v[184:185]
	global_load_lds_dwordx4 v[238:239], off
	s_add_i32 m0, s79, 0x2000
	s_nop 0
	global_load_lds_dwordx4 v[240:241], off
	s_waitcnt vmcnt(6)
	s_barrier
	s_setprio 1
	v_mfma_f32_16x16x32_bf16 v[52:55], v[216:219], v[148:151], v[52:55]
	v_mfma_f32_16x16x32_bf16 v[44:47], v[224:227], v[148:151], v[44:47]
	v_mfma_f32_16x16x32_bf16 v[36:39], v[216:219], v[156:159], v[36:39]
	v_mfma_f32_16x16x32_bf16 v[28:31], v[224:227], v[156:159], v[28:31]
	v_mfma_f32_16x16x32_bf16 v[20:23], v[216:219], v[196:199], v[20:23]
	v_mfma_f32_16x16x32_bf16 v[12:15], v[224:227], v[196:199], v[12:15]
	v_mfma_f32_16x16x32_bf16 v[8:11], v[216:219], v[208:211], v[8:11]
	v_mfma_f32_16x16x32_bf16 v[4:7], v[224:227], v[208:211], v[4:7]
	v_mfma_f32_16x16x32_bf16 v[52:55], v[220:223], v[152:155], v[52:55]
	v_mfma_f32_16x16x32_bf16 v[44:47], v[228:231], v[152:155], v[44:47]
	v_mfma_f32_16x16x32_bf16 v[36:39], v[220:223], v[160:163], v[36:39]
	v_mfma_f32_16x16x32_bf16 v[28:31], v[228:231], v[160:163], v[28:31]
	v_mfma_f32_16x16x32_bf16 v[20:23], v[220:223], v[200:203], v[20:23]
	v_mfma_f32_16x16x32_bf16 v[12:15], v[228:231], v[200:203], v[12:15]
	s_setprio 2
	s_barrier
	v_mfma_f32_16x16x32_bf16 v[8:11], v[220:223], v[212:215], v[8:11]
	v_mfma_f32_16x16x32_bf16 v[4:7], v[228:231], v[212:215], v[4:7]
	s_setprio 0
	s_add_i32 s56, 0, 0x18000
	s_add_u32 s44, s44, s8
	s_addc_u32 s45, s45, 0
	s_mov_b32 m0, s66
	ds_read_b128 v[148:151], v195 offset:32768
	ds_read_b128 v[152:155], v195 offset:33792
	ds_read_b128 v[156:159], v195 offset:34816
	ds_read_b128 v[160:163], v195 offset:35840
	ds_read_b128 v[196:199], v195 offset:36864
	ds_read_b128 v[200:203], v195 offset:37888
	ds_read_b128 v[208:211], v195 offset:38912
	ds_read_b128 v[212:215], v195 offset:39936
	global_load_lds_dwordx4 v180, s[44:45]
	s_mov_b32 m0, s67
	s_nop 0
	global_load_lds_dwordx4 v182, s[44:45]
	s_waitcnt lgkmcnt(8)
	s_barrier
; #define PG8_STAGE(bufoff, gbase, voff) do { _Pragma("unroll") for (int _i = 0; _i < 2; ++_i) \
;     __builtin_amdgcn_global_load_lds((const unsigned*)((const char*)(gbase) + (voff)[_i]), (LAS unsigned*)(lds + (bufoff) + ldsw + _i * 8192), 16, 0, 0); } while (0)
; #define PG8_LDA(dst, b, h) do { _Pragma("unroll") for (int m = 0; m < 4; ++m) _Pragma("unroll") for (int k = 0; k < 2; ++k) dst[m][k] = *(const LAS bf16x8*)(lds + PG8_SA(b, h) + aoff + m * 2048 + k * 1024); } while (0)
; #define PG8_MMA(ai, bj, At, Bt) do { __builtin_amdgcn_s_setprio(1); _Pragma("unroll") for (int m = 0; m < 4; ++m) _Pragma("unroll") for (int n = 0; n < 2; ++n) _Pragma("unroll") for (int k = 0; k < 2; ++k) \
;     acc[ai][bj][m][n] = __builtin_amdgcn_mfma_f32_16x16x32_bf16(Bt[n][k], At[m][k], acc[ai][bj][m][n], 0, 0, 0); __builtin_amdgcn_s_setprio(0); } while (0)
; #define PG8_WAIT_V(n) asm volatile("s_waitcnt vmcnt(" #n ")" ::: "memory")
; #define PG8_WAIT_L(n) asm volatile("s_waitcnt lgkmcnt(" #n ")" ::: "memory")
; #define PG8_BAR __builtin_amdgcn_s_barrier()
; #define PG8_SCHED __builtin_amdgcn_sched_barrier(0)
; template <class Epi>
; DI void gemm_phase(LAS unsigned char* lds, const Gemm g, const Epi& E) {
;     ...
;       PG8_BAR; PG8_WAIT_L(0); PG8_MMA(0, 1, At, B1); PG8_BAR;
;       PG8_LDA(At, 1, 1); PG8_STAGE(PG8_SA(1, 0), a3, voffA);
;       PG8_BAR; PG8_WAIT_L(0); PG8_MMA(1, 0, At, B0); PG8_BAR; PG8_SCHED;
;       PG8_STAGE(PG8_SB(1, 1), b3 + hstepB, voffB);
;       PG8_WAIT_V(6); PG8_BAR; PG8_MMA(1, 1, At, B1); PG8_BAR;
	s_waitcnt lgkmcnt(0)
	s_setprio 1
	s_waitcnt lgkmcnt(0)
	v_mfma_f32_16x16x32_bf16 v[128:131], v[132:135], v[148:151], v[128:131]
	v_mfma_f32_16x16x32_bf16 v[124:127], v[140:143], v[148:151], v[124:127]
	v_mfma_f32_16x16x32_bf16 v[116:119], v[132:135], v[156:159], v[116:119]
	v_mfma_f32_16x16x32_bf16 v[108:111], v[140:143], v[156:159], v[108:111]
	v_mfma_f32_16x16x32_bf16 v[100:103], v[132:135], v[196:199], v[100:103]
	v_mfma_f32_16x16x32_bf16 v[92:95], v[140:143], v[196:199], v[92:95]
	v_mfma_f32_16x16x32_bf16 v[84:87], v[132:135], v[208:211], v[84:87]
	v_mfma_f32_16x16x32_bf16 v[76:79], v[140:143], v[208:211], v[76:79]
	v_mfma_f32_16x16x32_bf16 v[128:131], v[136:139], v[152:155], v[128:131]
	v_mfma_f32_16x16x32_bf16 v[124:127], v[144:147], v[152:155], v[124:127]
	v_mfma_f32_16x16x32_bf16 v[116:119], v[136:139], v[160:163], v[116:119]
	v_mfma_f32_16x16x32_bf16 v[108:111], v[144:147], v[160:163], v[108:111]
	v_mfma_f32_16x16x32_bf16 v[100:103], v[136:139], v[200:203], v[100:103]
	v_mfma_f32_16x16x32_bf16 v[92:95], v[144:147], v[200:203], v[92:95]
	s_setprio 2
	s_barrier
	v_mfma_f32_16x16x32_bf16 v[84:87], v[136:139], v[212:215], v[84:87]
	v_mfma_f32_16x16x32_bf16 v[76:79], v[144:147], v[212:215], v[76:79]
	s_setprio 0
	s_add_i32 s44, 0, 0x1c000
	s_add_i32 s45, s56, s63
	s_mov_b32 m0, s45
	ds_read_b128 v[216:219], v248 offset:49152
	ds_read_b128 v[220:223], v248 offset:50176
	ds_read_b128 v[224:227], v248 offset:51200
	ds_read_b128 v[228:231], v248 offset:52224
	global_load_lds_dwordx4 v2, s[98:99]
	s_add_i32 m0, s45, 0x2000
	s_nop 0
	global_load_lds_dwordx4 v184, s[98:99]
	s_barrier
	s_waitcnt lgkmcnt(0)
	s_setprio 1
	s_waitcnt lgkmcnt(0)
	v_mfma_f32_16x16x32_bf16 v[120:123], v[216:219], v[148:151], v[120:123]
	v_mfma_f32_16x16x32_bf16 v[112:115], v[224:227], v[148:151], v[112:115]
	v_mfma_f32_16x16x32_bf16 v[104:107], v[216:219], v[156:159], v[104:107]
	v_mfma_f32_16x16x32_bf16 v[96:99], v[224:227], v[156:159], v[96:99]
	v_mfma_f32_16x16x32_bf16 v[88:91], v[216:219], v[196:199], v[88:91]
	v_mfma_f32_16x16x32_bf16 v[80:83], v[224:227], v[196:199], v[80:83]
	v_mfma_f32_16x16x32_bf16 v[72:75], v[216:219], v[208:211], v[72:75]
	v_mfma_f32_16x16x32_bf16 v[68:71], v[224:227], v[208:211], v[68:71]
	v_mfma_f32_16x16x32_bf16 v[120:123], v[220:223], v[152:155], v[120:123]
	v_mfma_f32_16x16x32_bf16 v[112:115], v[228:231], v[152:155], v[112:115]
	v_mfma_f32_16x16x32_bf16 v[104:107], v[220:223], v[160:163], v[104:107]
	v_mfma_f32_16x16x32_bf16 v[96:99], v[228:231], v[160:163], v[96:99]
	v_mfma_f32_16x16x32_bf16 v[88:91], v[220:223], v[200:203], v[88:91]
	v_mfma_f32_16x16x32_bf16 v[80:83], v[228:231], v[200:203], v[80:83]
	s_setprio 2
	s_barrier
	v_mfma_f32_16x16x32_bf16 v[72:75], v[220:223], v[212:215], v[72:75]
	v_mfma_f32_16x16x32_bf16 v[68:71], v[228:231], v[212:215], v[68:71]
	s_setprio 0
	s_mov_b32 m0, s69
	ds_read_b128 v[148:151], v195 offset:49152
	ds_read_b128 v[152:155], v195 offset:50176
	ds_read_b128 v[156:159], v195 offset:51200
	ds_read_b128 v[160:163], v195 offset:52224
	ds_read_b128 v[196:199], v195 offset:53248
	ds_read_b128 v[200:203], v195 offset:54272
	ds_read_b128 v[208:211], v195 offset:55296
	ds_read_b128 v[212:215], v195 offset:56320
	global_load_lds_dwordx4 v180, s[100:101]
	s_mov_b32 m0, s71
	s_nop 0
	global_load_lds_dwordx4 v182, s[100:101]
	s_waitcnt vmcnt(10)
	s_barrier
	s_waitcnt lgkmcnt(0)
	s_setprio 1
	s_waitcnt lgkmcnt(0)
	v_mfma_f32_16x16x32_bf16 v[64:67], v[132:135], v[148:151], v[64:67]
	v_mfma_f32_16x16x32_bf16 v[60:63], v[140:143], v[148:151], v[60:63]
	v_mfma_f32_16x16x32_bf16 v[56:59], v[132:135], v[156:159], v[56:59]
	v_mfma_f32_16x16x32_bf16 v[48:51], v[140:143], v[156:159], v[48:51]
	v_mfma_f32_16x16x32_bf16 v[40:43], v[132:135], v[196:199], v[40:43]
	v_mfma_f32_16x16x32_bf16 v[32:35], v[140:143], v[196:199], v[32:35]
	v_mfma_f32_16x16x32_bf16 v[24:27], v[132:135], v[208:211], v[24:27]
	v_mfma_f32_16x16x32_bf16 v[16:19], v[140:143], v[208:211], v[16:19]
	v_mfma_f32_16x16x32_bf16 v[64:67], v[136:139], v[152:155], v[64:67]
	v_mfma_f32_16x16x32_bf16 v[60:63], v[144:147], v[152:155], v[60:63]
	v_mfma_f32_16x16x32_bf16 v[56:59], v[136:139], v[160:163], v[56:59]
	v_mfma_f32_16x16x32_bf16 v[48:51], v[144:147], v[160:163], v[48:51]
	v_mfma_f32_16x16x32_bf16 v[40:43], v[136:139], v[200:203], v[40:43]
	v_mfma_f32_16x16x32_bf16 v[32:35], v[144:147], v[200:203], v[32:35]
	s_setprio 2
	s_barrier
	v_mfma_f32_16x16x32_bf16 v[24:27], v[136:139], v[212:215], v[24:27]
	v_mfma_f32_16x16x32_bf16 v[16:19], v[144:147], v[212:215], v[16:19]
	s_setprio 0
	ds_read_b128 v[132:135], v248
	ds_read_b128 v[136:139], v248 offset:1024
	ds_read_b128 v[140:143], v248 offset:2048
	ds_read_b128 v[144:147], v248 offset:3072
	s_add_i32 s44, s44, s63
	v_lshl_add_u64 v[246:247], v[238:239], 0, s[84:85]
	s_mov_b32 m0, s44
	s_nop 0
	global_load_lds_dwordx4 v[246:247], off
	v_lshl_add_u64 v[246:247], v[240:241], 0, s[84:85]
	s_add_i32 m0, s44, 0x2000
	s_nop 0
	global_load_lds_dwordx4 v[246:247], off
	s_waitcnt vmcnt(6)
	s_barrier
	s_setprio 1
	v_mfma_f32_16x16x32_bf16 v[52:55], v[216:219], v[148:151], v[52:55]
	v_mfma_f32_16x16x32_bf16 v[44:47], v[224:227], v[148:151], v[44:47]
	v_mfma_f32_16x16x32_bf16 v[36:39], v[216:219], v[156:159], v[36:39]
	v_mfma_f32_16x16x32_bf16 v[28:31], v[224:227], v[156:159], v[28:31]
	v_mfma_f32_16x16x32_bf16 v[20:23], v[216:219], v[196:199], v[20:23]
	v_mfma_f32_16x16x32_bf16 v[12:15], v[224:227], v[196:199], v[12:15]
	v_mfma_f32_16x16x32_bf16 v[8:11], v[216:219], v[208:211], v[8:11]
	v_mfma_f32_16x16x32_bf16 v[4:7], v[224:227], v[208:211], v[4:7]
	v_mfma_f32_16x16x32_bf16 v[52:55], v[220:223], v[152:155], v[52:55]
	v_mfma_f32_16x16x32_bf16 v[44:47], v[228:231], v[152:155], v[44:47]
	v_mfma_f32_16x16x32_bf16 v[36:39], v[220:223], v[160:163], v[36:39]
	v_mfma_f32_16x16x32_bf16 v[28:31], v[228:231], v[160:163], v[28:31]
	v_mfma_f32_16x16x32_bf16 v[20:23], v[220:223], v[200:203], v[20:23]
	v_mfma_f32_16x16x32_bf16 v[12:15], v[228:231], v[200:203], v[12:15]
	s_setprio 2
	s_barrier
	v_mfma_f32_16x16x32_bf16 v[8:11], v[220:223], v[212:215], v[8:11]
	v_mfma_f32_16x16x32_bf16 v[4:7], v[228:231], v[212:215], v[4:7]
	s_setprio 0
	s_add_u32 s42, s42, 0x100
	s_addc_u32 s43, s43, 0
	s_add_u32 s58, s58, 0x100
	s_addc_u32 s59, s59, 0
	s_cmp_ge_u32 s78, s68
	s_mov_b32 s44, s78
	s_cbranch_scc0 .LBB0_514

; DI void cvt_load(const CvtJob& j, int t, int tid, CvtRegs& R) {
;   const int nkt = j.K / 64; const int kt = t % nkt, ct = t / nkt; const int k0 = kt * 64, n0 = ct * 64;
;   const float* sp = j.mode == 2 ? j.src + (size_t)(n0 >> 9) * 512 * 512 + (n0 & 511) : j.src + n0;
; #pragma unroll
;   for (int i = 0; i < 2; ++i) {
;     const int r = (tid >> 4) + i * 32, c4 = (tid & 15) * 4;
;     R.v[i] = (f32x4){0.f, 0.f, 0.f, 0.f};
;     if (n0 + c4 < j.nvalid) R.v[i] = __builtin_nontemporal_load((const f32x4*)(sp + (size_t)(k0 + r) * j.ldsrc + c4));
;     float sc = (n0 + c4 < j.nscale) ? j.sc : 1.0f;
;     if (j.ks) sc *= j.ks[(j.mode == 2 ? (n0 >> 9) * 512 : 0) + k0 + r];
;     R.s[i] = sc;
;   }
; DI void cvt_job(LAS float* tile, const CvtJob& j, int& cursor) {
;     ...
;   CvtRegs cur, nxt; int buf = 0;
;   if (t < ntiles) cvt_load(j, t, tid, cur);
;   for (; t < ntiles; t += G) {
.LBB0_608:
	s_or_b64 exec, exec, s[30:31]
	s_ashr_i32 s27, s26, 31
	v_ashrrev_i32_e32 v21, 31, v20
	v_lshl_add_u64 v[12:13], s[26:27], 0, v[20:21]
	v_lshl_add_u64 v[12:13], v[12:13], 2, s[18:19]
	global_load_dword v28, v[12:13], off offset:128
	v_ashrrev_i32_e32 v34, 3, v2
	v_lshlrev_b32_e32 v2, 3, v2
	s_movk_i32 s26, 0x104
	v_and_b32_e32 v2, 56, v2
	v_mov_b32_e32 v23, v3
	v_mul_lo_u32 v29, v20, s26
	v_mul_u32_u24_e32 v35, 0x104, v2
	v_lshl_add_u64 v[24:25], s[22:23], 0, v[22:23]
	s_lshl_b32 s31, s25, 6
	v_add_u32_e32 v23, s28, v20
	s_mov_b32 s30, 0
	v_lshlrev_b32_e32 v2, 1, v2
	s_waitcnt vmcnt(0)
	s_branch .LBB0_611

; #define LAS __attribute__((address_space(3)))
; DI unsigned cvt_pk_bf16(float lo, float hi) { const f32x2 v = {lo, hi}; const bf16x2_t r = __builtin_convertvector(v, bf16x2_t); return __builtin_bit_cast(unsigned, r); }
; DI void cvt_write(LAS float* tile  , int tid, const CvtRegs& R) {
; #pragma unroll
;   for (int i = 0; i < 2; ++i) {
;     const int r = (tid >> 4) + i * 32, c4 = (tid & 15) * 4;
;     const f32x4 v = R.v[i] * R.s[i];
;     tile[r * 65 + c4 + 0] = v[0]; tile[r * 65 + c4 + 1] = v[1]; tile[r * 65 + c4 + 2] = v[2]; tile[r * 65 + c4 + 3] = v[3];
;   }
; }
; DI void cvt_store(const LAS float* tile, const CvtJob& j, int t, int tid) {
;   const int nkt = j.K / 64; const int kt = t % nkt, ct = t / nkt; const int k0 = kt * 64, n0 = ct * 64;
;   const int n = tid >> 3, ks = (tid & 7) * 8;
;   u32x4 w;
;   w.x = cvt_pk_bf16(tile[(ks + 0) * 65 + n], tile[(ks + 1) * 65 + n]); w.y = cvt_pk_bf16(tile[(ks + 2) * 65 + n], tile[(ks + 3) * 65 + n]);
;   w.z = cvt_pk_bf16(tile[(ks + 4) * 65 + n], tile[(ks + 5) * 65 + n]); w.w = cvt_pk_bf16(tile[(ks + 6) * 65 + n], tile[(ks + 7) * 65 + n]);
;   const int ng = n0 + n; const int row = j.mode == 1 ? (256 * (ng >> 7) + (ng & 127) + j.rowadd) : ng;
;   *(u32x4*)(j.dst + (size_t)row * j.K + k0 + ks) = w;
; DI void cvt_job(LAS float* tile, const CvtJob& j, int& cursor) {
;     ...
;   for (; t < ntiles; t += G) {
;     const bool more = t + G < ntiles;
;     if (more) cvt_load(j, t + G, tid, nxt);
;     LAS float* tb = tile + buf * 4224;
;     cvt_write(tb, tid, cur);
;     asm volatile("s_waitcnt lgkmcnt(0)" ::: "memory"); __builtin_amdgcn_s_barrier(); asm volatile("" ::: "memory");
;     cvt_store(tb, j, t, tid);
;     if (more) cur = nxt;
;     buf ^= 1;
.LBB0_610:
	s_mul_i32 s26, s30, 0x4200
	s_add_i32 s26, s26, 0
	v_pk_mul_f32 v[10:11], v[10:11], v[26:27] op_sel_hi:[1,0]
	v_pk_mul_f32 v[8:9], v[8:9], v[26:27] op_sel_hi:[1,0]
	v_add3_u32 v26, s26, v22, v29
	ds_write2_b32 v26, v8, v9 offset1:1
	ds_write2_b32 v26, v10, v11 offset0:2 offset1:3
	v_pk_mul_f32 v[4:5], v[4:5], v[28:29] op_sel_hi:[1,0]
	v_add_u32_e32 v8, 0x2080, v26
	v_pk_mul_f32 v[6:7], v[6:7], v[28:29] op_sel_hi:[1,0]
	ds_write2_b32 v8, v4, v5 offset1:1
	v_add_u32_e32 v4, 0x2088, v26
	ds_write2_b32 v4, v6, v7 offset1:1
	v_lshlrev_b32_e32 v4, 2, v34
	s_waitcnt lgkmcnt(0)
	s_barrier
	v_add3_u32 v8, s26, v35, v4
	ds_read2_b32 v[4:5], v8 offset1:65
	ds_read2_b32 v[6:7], v8 offset0:130 offset1:195
	v_add_u32_e32 v10, 0x400, v8
	s_ashr_i32 s27, s25, 31
	ds_read2_b32 v[8:9], v10 offset0:4 offset1:69
	ds_read2_b32 v[10:11], v10 offset0:134 offset1:199
	s_lshr_b32 s27, s27, 27
	s_add_i32 s25, s25, s27
	s_ashr_i32 s25, s25, 5
	s_waitcnt lgkmcnt(3)
	v_cvt_pk_bf16_f32 v4, v4, v5
	s_waitcnt lgkmcnt(2)
	v_cvt_pk_bf16_f32 v5, v6, v7
	s_waitcnt lgkmcnt(1)
	v_cvt_pk_bf16_f32 v6, v8, v9
	v_lshl_add_u32 v8, s25, 6, v34
	v_lshlrev_b32_e32 v9, 1, v8
	v_and_b32_e32 v8, 0x7f, v8
	s_movk_i32 s26, 0xff00
	v_and_or_b32 v8, v9, s26, v8
	s_lshl_b32 s25, s25, 11
	v_ashrrev_i32_e32 v9, 31, v8
	s_sub_i32 s26, s31, s25
	v_lshlrev_b64 v[8:9], 12, v[8:9]
	v_lshl_add_u64 v[8:9], s[12:13], 0, v[8:9]
	s_ashr_i32 s27, s26, 31
	v_lshl_add_u64 v[8:9], s[26:27], 1, v[8:9]
	s_waitcnt lgkmcnt(0)
	v_cvt_pk_bf16_f32 v7, v10, v11
	v_lshl_add_u64 v[8:9], v[8:9], 0, v[2:3]
	global_store_dwordx4 v[8:9], v[4:7], off
	s_waitcnt vmcnt(1)
	v_mov_b64_e32 v[8:9], v[16:17]
	s_xor_b32 s30, s30, 1
	v_mov_b64_e32 v[4:5], v[12:13]
	s_andn2_b64 vcc, exec, s[22:23]
	s_mov_b32 s31, s37
	s_mov_b32 s25, s36
	v_mov_b64_e32 v[10:11], v[18:19]
	v_mov_b64_e32 v[6:7], v[14:15]
	v_mov_b32_e32 v26, v33
	v_mov_b32_e32 v28, v30
	s_cbranch_vccz .LBB0_618

; #define LAS __attribute__((address_space(3)))
; DI unsigned cvt_pk_bf16(float lo, float hi) { const f32x2 v = {lo, hi}; const bf16x2_t r = __builtin_convertvector(v, bf16x2_t); return __builtin_bit_cast(unsigned, r); }
; DI void cvt_write(LAS float* tile  , int tid, const CvtRegs& R) {
; #pragma unroll
;   for (int i = 0; i < 2; ++i) {
;     const int r = (tid >> 4) + i * 32, c4 = (tid & 15) * 4;
;     const f32x4 v = R.v[i] * R.s[i];
;     tile[r * 65 + c4 + 0] = v[0]; tile[r * 65 + c4 + 1] = v[1]; tile[r * 65 + c4 + 2] = v[2]; tile[r * 65 + c4 + 3] = v[3];
;   }
; }
; DI void cvt_store(const LAS float* tile, const CvtJob& j, int t, int tid) {
;   const int nkt = j.K / 64; const int kt = t % nkt, ct = t / nkt; const int k0 = kt * 64, n0 = ct * 64;
;   const int n = tid >> 3, ks = (tid & 7) * 8;
;   u32x4 w;
;   w.x = cvt_pk_bf16(tile[(ks + 0) * 65 + n], tile[(ks + 1) * 65 + n]); w.y = cvt_pk_bf16(tile[(ks + 2) * 65 + n], tile[(ks + 3) * 65 + n]);
;   w.z = cvt_pk_bf16(tile[(ks + 4) * 65 + n], tile[(ks + 5) * 65 + n]); w.w = cvt_pk_bf16(tile[(ks + 6) * 65 + n], tile[(ks + 7) * 65 + n]);
;   const int ng = n0 + n; const int row = j.mode == 1 ? (256 * (ng >> 7) + (ng & 127) + j.rowadd) : ng;
;   *(u32x4*)(j.dst + (size_t)row * j.K + k0 + ks) = w;
; DI void cvt_job(LAS float* tile, const CvtJob& j, int& cursor) {
;     ...
;   for (; t < ntiles; t += G) {
;     const bool more = t + G < ntiles;
;     if (more) cvt_load(j, t + G, tid, nxt);
;     LAS float* tb = tile + buf * 4224;
;     cvt_write(tb, tid, cur);
;     asm volatile("s_waitcnt lgkmcnt(0)" ::: "memory"); __builtin_amdgcn_s_barrier(); asm volatile("" ::: "memory");
;     cvt_store(tb, j, t, tid);
;     if (more) cur = nxt;
;     buf ^= 1;
.LBB0_625:
	s_mul_i32 s26, s30, 0x4200
	s_add_i32 s26, s26, 0
	v_pk_mul_f32 v[10:11], v[10:11], v[26:27] op_sel_hi:[1,0]
	v_pk_mul_f32 v[8:9], v[8:9], v[26:27] op_sel_hi:[1,0]
	v_add3_u32 v26, s26, v22, v29
	ds_write2_b32 v26, v8, v9 offset1:1
	ds_write2_b32 v26, v10, v11 offset0:2 offset1:3
	v_pk_mul_f32 v[4:5], v[4:5], v[28:29] op_sel_hi:[1,0]
	v_add_u32_e32 v8, 0x2080, v26
	v_pk_mul_f32 v[6:7], v[6:7], v[28:29] op_sel_hi:[1,0]
	ds_write2_b32 v8, v4, v5 offset1:1
	v_add_u32_e32 v4, 0x2088, v26
	ds_write2_b32 v4, v6, v7 offset1:1
	v_lshlrev_b32_e32 v4, 2, v34
	s_waitcnt lgkmcnt(0)
	s_barrier
	v_add3_u32 v8, s26, v35, v4
	ds_read2_b32 v[4:5], v8 offset1:65
	ds_read2_b32 v[6:7], v8 offset0:130 offset1:195
	v_add_u32_e32 v10, 0x400, v8
	s_ashr_i32 s27, s25, 31
	ds_read2_b32 v[8:9], v10 offset0:4 offset1:69
	ds_read2_b32 v[10:11], v10 offset0:134 offset1:199
	s_lshr_b32 s27, s27, 27
	s_add_i32 s25, s25, s27
	s_ashr_i32 s25, s25, 5
	s_waitcnt lgkmcnt(3)
	v_cvt_pk_bf16_f32 v4, v4, v5
	s_waitcnt lgkmcnt(2)
	v_cvt_pk_bf16_f32 v5, v6, v7
	s_waitcnt lgkmcnt(1)
	v_cvt_pk_bf16_f32 v6, v8, v9
	v_lshl_add_u32 v8, s25, 6, v34
	v_lshlrev_b32_e32 v9, 1, v8
	v_and_b32_e32 v9, 0xffffff00, v9
	v_and_b32_e32 v8, 0x7f, v8
	s_movk_i32 s26, 0x80
	v_or3_b32 v8, v8, v9, s26
	s_lshl_b32 s25, s25, 11
	v_ashrrev_i32_e32 v9, 31, v8
	s_sub_i32 s26, s31, s25
	v_lshlrev_b64 v[8:9], 12, v[8:9]
	v_lshl_add_u64 v[8:9], s[12:13], 0, v[8:9]
	s_ashr_i32 s27, s26, 31
	v_lshl_add_u64 v[8:9], s[26:27], 1, v[8:9]
	s_waitcnt lgkmcnt(0)
	v_cvt_pk_bf16_f32 v7, v10, v11
	v_lshl_add_u64 v[8:9], v[8:9], 0, v[2:3]
	global_store_dwordx4 v[8:9], v[4:7], off
	s_waitcnt vmcnt(1)
	v_mov_b64_e32 v[8:9], v[16:17]
	s_xor_b32 s30, s30, 1
	v_mov_b64_e32 v[4:5], v[12:13]
	s_andn2_b64 vcc, exec, s[22:23]
	s_mov_b32 s31, s37
	s_mov_b32 s25, s36
	v_mov_b64_e32 v[10:11], v[18:19]
	v_mov_b64_e32 v[6:7], v[14:15]
	v_mov_b32_e32 v26, v33
	v_mov_b32_e32 v28, v30
	s_cbranch_vccz .LBB0_633

; __global__ void __launch_bounds__(512, 2) mega(Params p_unused) {
;   extern __shared__ __attribute__((aligned(16))) unsigned char lds_raw[];
	.amdhsa_kernel _Z4mega6Params
		.amdhsa_group_segment_fixed_size 0
		.amdhsa_private_segment_fixed_size 0
		.amdhsa_kernarg_size 376
		.amdhsa_user_sgpr_count 2
		.amdhsa_user_sgpr_dispatch_ptr 0
		.amdhsa_user_sgpr_queue_ptr 0
		.amdhsa_user_sgpr_kernarg_segment_ptr 1
		.amdhsa_user_sgpr_dispatch_id 0
		.amdhsa_user_sgpr_kernarg_preload_length 0
		.amdhsa_user_sgpr_kernarg_preload_offset 0
		.amdhsa_user_sgpr_private_segment_size 0
		.amdhsa_uses_dynamic_stack 0
		.amdhsa_enable_private_segment 0
		.amdhsa_system_sgpr_workgroup_id_x 1
		.amdhsa_system_sgpr_workgroup_id_y 0
		.amdhsa_system_sgpr_workgroup_id_z 0
		.amdhsa_system_sgpr_workgroup_info 0
		.amdhsa_system_vgpr_workitem_id 0
		.amdhsa_next_free_vgpr 254
		.amdhsa_next_free_sgpr 102
		.amdhsa_accum_offset 256
		.amdhsa_reserve_vcc 1
		.amdhsa_float_round_mode_32 0
		.amdhsa_float_round_mode_16_64 0
		.amdhsa_float_denorm_mode_32 3
		.amdhsa_float_denorm_mode_16_64 3
		.amdhsa_dx10_clamp 1
		.amdhsa_ieee_mode 1
		.amdhsa_fp16_overflow 0
		.amdhsa_tg_split 0
		.amdhsa_exception_fp_ieee_invalid_op 0
		.amdhsa_exception_fp_denorm_src 0
		.amdhsa_exception_fp_ieee_div_zero 0
		.amdhsa_exception_fp_ieee_overflow 0
		.amdhsa_exception_fp_ieee_underflow 0
		.amdhsa_exception_fp_ieee_inexact 0
		.amdhsa_exception_int_div_zero 0
	.end_amdhsa_kernel

; DI ParamsK fresh_params() { ParamsK k = (ParamsK)__builtin_amdgcn_kernarg_segment_ptr(); asm volatile("" : "+s"(k)); return k; }
; __global__ void __launch_bounds__(512, 2) mega(Params p_unused) {
amdhsa.kernels:
  - .agpr_count:     0
    .args:
      - .offset:         0
        .size:           120
        .value_kind:     by_value
      - .offset:         120
        .size:           4
        .value_kind:     hidden_block_count_x
      - .offset:         124
        .size:           4
        .value_kind:     hidden_block_count_y
      - .offset:         128
        .size:           4
        .value_kind:     hidden_block_count_z
      - .offset:         132
        .size:           2
        .value_kind:     hidden_group_size_x
      - .offset:         134
        .size:           2
        .value_kind:     hidden_group_size_y
      - .offset:         136
        .size:           2
        .value_kind:     hidden_group_size_z
      - .offset:         138
        .size:           2
        .value_kind:     hidden_remainder_x
      - .offset:         140
        .size:           2
        .value_kind:     hidden_remainder_y
      - .offset:         142
        .size:           2
        .value_kind:     hidden_remainder_z
      - .offset:         160
        .size:           8
        .value_kind:     hidden_global_offset_x
      - .offset:         168
        .size:           8
        .value_kind:     hidden_global_offset_y
      - .offset:         176
        .size:           8
        .value_kind:     hidden_global_offset_z
      - .offset:         184
        .size:           2
        .value_kind:     hidden_grid_dims
      - .offset:         208
        .size:           8
        .value_kind:     hidden_multigrid_sync_arg
      - .offset:         240
        .size:           4
        .value_kind:     hidden_dynamic_lds_size
    .group_segment_fixed_size: 0
    .kernarg_segment_align: 8
    .kernarg_segment_size: 376
    .language:       OpenCL C
    .language_version:
      - 2
      - 0
    .max_flat_workgroup_size: 512
    .name:           _Z4mega6Params
    .private_segment_fixed_size: 0
    .sgpr_count:     108
    .sgpr_spill_count: 119
    .symbol:         _Z4mega6Params.kd
    .uniform_work_group_size: 1
    .uses_dynamic_stack: false
    .vgpr_count:     254
    .vgpr_spill_count: 0
    .wavefront_size: 64
